# attention: constant-fold the inactive query set of the 10 dilation-16 steps (alpha=1, p=0, mnew=mrun) and dead-code-eliminate its QK MFMAs, masks, reduce and exps
# speedup vs baseline: 1.0028x; 1.0028x over previous
.LBB0_246:
	s_lshl_b32 s1, s71, 2
	s_and_b32 s22, s1, 0xffffff00
	s_lshr_b32 s0, s71, 3
	s_bfe_u32 s56, s71, 0x30003
	s_or_b32 s24, s22, s72
	s_cmp_lt_i32 s24, 0x8000
	s_movk_i32 s22, 0xfff
	s_cselect_b32 s75, s22, 0x1fff
	s_bfe_u32 s0, s0, 0x10002
	s_andn2_b32 s74, s1, s75
	s_mul_i32 s0, s0, 0x1800000
	s_add_u32 s0, s96, s0
	s_addc_u32 s1, s97, 0
	s_lshl_b32 s22, s71, 4
	s_and_b32 s22, s22, 0x180
	s_add_u32 s22, s0, s22
	v_or_b32_e32 v162, s24, v167
	s_addc_u32 s23, s1, 0
	v_ashrrev_i32_e32 v163, 31, v162
	v_lshl_add_u64 v[12:13], s[22:23], 0, v[158:159]
	v_lshlrev_b64 v[0:1], 9, v[162:163]
	v_lshl_add_u64 v[8:9], v[12:13], 0, v[0:1]
	global_load_dwordx4 v[0:3], v[8:9], off
	v_or_b32_e32 v160, 8, v162
	v_ashrrev_i32_e32 v161, 31, v160
	s_add_u32 s68, s22, 0x3000000
	s_addc_u32 s69, s23, 0
	s_lshl_b32 s98, s74, 9
	s_add_u32 s100, s68, s98
	s_addc_u32 s101, s69, 0
	s_add_u32 s98, s100, 0x3000000
	s_addc_u32 s99, s101, 0
	s_sub_i32 s76, s24, s74
	s_sub_i32 s0, s76, 64
	s_waitcnt vmcnt(7)
	v_add_u32_e32 v20, s0, v172
	v_min_i32_e32 v21, s75, v20
	s_waitcnt vmcnt(6)
	v_add_u32_e32 v24, s0, v173
	v_min_i32_e32 v25, s75, v24
	s_waitcnt vmcnt(5)
	v_add_u32_e32 v28, s0, v182
	v_min_i32_e32 v29, s75, v28
	s_waitcnt vmcnt(2)
	v_add_u32_e32 v40, s0, v166
	v_min_i32_e32 v32, s75, v40
	v_add_u32_e32 v41, 16, v40
	s_movk_i32 s1, 0xffef
	v_min_i32_e32 v41, s75, v41
	v_or_b32_e32 v128, 32, v166
	v_add_u32_e32 v56, s0, v128
	v_add_u32_e32 v149, s76, v155
	v_add_u32_e32 v150, s76, v172
	v_add_u32_e32 v151, s76, v173
	v_add_u32_e32 v252, s76, v182
	v_or_b32_e32 v251, s76, v167
	v_subrev_u32_e32 v250, s76, v251
	v_or_b32_e32 v144, 8, v251
	v_subrev_u32_e32 v249, s76, v144
	v_add_u32_e32 v196, 0x60, v155
	v_add_u32_e32 v168, 0x60, v172
	v_add_u32_e32 v193, 0x60, v173
	v_add_u32_e32 v194, 0x60, v182
	v_add_u32_e32 v186, s76, v206
	s_waitcnt vmcnt(0)
	v_lshlrev_b32_e32 v4, 16, v0
	v_and_b32_e32 v5, 0xffff0000, v0
	v_lshlrev_b32_e32 v0, 16, v1
	v_and_b32_e32 v1, 0xffff0000, v1
	v_pk_mul_f32 v[4:5], v[4:5], s[58:59] op_sel_hi:[1,0]
	v_pk_mul_f32 v[0:1], v[0:1], s[58:59] op_sel_hi:[1,0]
	v_cvt_pk_bf16_f32 v4, v4, v5
	v_cvt_pk_bf16_f32 v5, v0, v1
	v_lshlrev_b32_e32 v0, 16, v2
	v_and_b32_e32 v1, 0xffff0000, v2
	v_pk_mul_f32 v[0:1], v[0:1], s[58:59] op_sel_hi:[1,0]
	s_nop 0
	v_cvt_pk_bf16_f32 v6, v0, v1
	v_lshlrev_b32_e32 v0, 16, v3
	v_and_b32_e32 v1, 0xffff0000, v3
	v_pk_mul_f32 v[0:1], v[0:1], s[58:59] op_sel_hi:[1,0]
	s_nop 0
	v_cvt_pk_bf16_f32 v7, v0, v1
	global_load_dwordx4 v[0:3], v[8:9], off offset:64
	s_waitcnt vmcnt(0)
	v_lshlrev_b32_e32 v8, 16, v0
	v_and_b32_e32 v9, 0xffff0000, v0
	v_lshlrev_b32_e32 v0, 16, v1
	v_and_b32_e32 v1, 0xffff0000, v1
	v_pk_mul_f32 v[8:9], v[8:9], s[58:59] op_sel_hi:[1,0]
	v_pk_mul_f32 v[0:1], v[0:1], s[58:59] op_sel_hi:[1,0]
	v_cvt_pk_bf16_f32 v8, v8, v9
	v_cvt_pk_bf16_f32 v9, v0, v1
	v_lshlrev_b32_e32 v0, 16, v2
	v_and_b32_e32 v1, 0xffff0000, v2
	v_pk_mul_f32 v[0:1], v[0:1], s[58:59] op_sel_hi:[1,0]
	s_nop 0
	v_cvt_pk_bf16_f32 v10, v0, v1
	v_lshlrev_b32_e32 v0, 16, v3
	v_and_b32_e32 v1, 0xffff0000, v3
	v_pk_mul_f32 v[0:1], v[0:1], s[58:59] op_sel_hi:[1,0]
	s_nop 0
	v_cvt_pk_bf16_f32 v11, v0, v1
	v_lshlrev_b64 v[0:1], 9, v[160:161]
	v_lshl_add_u64 v[16:17], v[12:13], 0, v[0:1]
	global_load_dwordx4 v[0:3], v[16:17], off
	s_waitcnt vmcnt(0)
	v_lshlrev_b32_e32 v12, 16, v0
	v_and_b32_e32 v13, 0xffff0000, v0
	v_lshlrev_b32_e32 v0, 16, v1
	v_and_b32_e32 v1, 0xffff0000, v1
	v_pk_mul_f32 v[12:13], v[12:13], s[58:59] op_sel_hi:[1,0]
	v_pk_mul_f32 v[0:1], v[0:1], s[58:59] op_sel_hi:[1,0]
	v_cvt_pk_bf16_f32 v12, v12, v13
	v_cvt_pk_bf16_f32 v13, v0, v1
	v_lshlrev_b32_e32 v0, 16, v2
	v_and_b32_e32 v1, 0xffff0000, v2
	v_pk_mul_f32 v[0:1], v[0:1], s[58:59] op_sel_hi:[1,0]
	s_nop 0
	v_cvt_pk_bf16_f32 v14, v0, v1
	v_lshlrev_b32_e32 v0, 16, v3
	v_and_b32_e32 v1, 0xffff0000, v3
	v_pk_mul_f32 v[0:1], v[0:1], s[58:59] op_sel_hi:[1,0]
	s_nop 0
	v_cvt_pk_bf16_f32 v15, v0, v1
	global_load_dwordx4 v[0:3], v[16:17], off offset:64
	s_waitcnt vmcnt(0)
	v_lshlrev_b32_e32 v16, 16, v0
	v_and_b32_e32 v17, 0xffff0000, v0
	v_pk_mul_f32 v[16:17], v[16:17], s[58:59] op_sel_hi:[1,0]
	s_nop 0
	v_cvt_pk_bf16_f32 v0, v16, v17
	v_lshlrev_b32_e32 v16, 16, v1
	v_and_b32_e32 v17, 0xffff0000, v1
	v_pk_mul_f32 v[16:17], v[16:17], s[58:59] op_sel_hi:[1,0]
	s_nop 0
	v_cvt_pk_bf16_f32 v1, v16, v17
	v_lshlrev_b32_e32 v16, 16, v2
	v_and_b32_e32 v17, 0xffff0000, v2
	v_pk_mul_f32 v[16:17], v[16:17], s[58:59] op_sel_hi:[1,0]
	s_nop 0
	v_cvt_pk_bf16_f32 v2, v16, v17
	v_lshlrev_b32_e32 v16, 16, v3
	v_and_b32_e32 v17, 0xffff0000, v3
	v_pk_mul_f32 v[16:17], v[16:17], s[58:59] op_sel_hi:[1,0]
	s_nop 0
	v_cvt_pk_bf16_f32 v3, v16, v17
	s_mov_b64 s[22:23], 0x6000000
	v_add_u32_e32 v16, s0, v155
	s_sub_i32 s22, 0x80, s76
	s_nop 0
	v_med3_i32 v16, v16, 0, s75
	v_cmp_lt_i32_e32 vcc, -1, v20
	s_nop 1
	v_cndmask_b32_e32 v20, 0, v21, vcc
	v_cmp_lt_i32_e32 vcc, -1, v24
	s_nop 1
	v_cndmask_b32_e32 v24, 0, v25, vcc
	v_cmp_lt_i32_e32 vcc, -1, v28
	s_nop 1
	v_cndmask_b32_e32 v28, 0, v29, vcc
	v_lshl_add_u32 v16, v16, 9, v152
	global_load_dwordx4 v[16:19], v16, s[98:99]
	v_lshl_add_u32 v20, v20, 9, v152
	v_cmp_lt_i32_e32 vcc, -1, v40
	global_load_dwordx4 v[20:23], v20, s[98:99]
	v_lshl_add_u32 v24, v24, 9, v152
	v_cndmask_b32_e32 v32, 0, v32, vcc
	v_cmp_lt_i32_e32 vcc, s1, v40
	global_load_dwordx4 v[24:27], v24, s[98:99]
	v_lshl_add_u32 v28, v28, 9, v152
	v_cndmask_b32_e32 v40, 0, v41, vcc
	global_load_dwordx4 v[28:31], v28, s[98:99]
	v_lshl_add_u32 v36, v32, 9, v158
	v_lshl_add_u32 v40, v40, 9, v158
	s_sub_i32 s1, s76, 32
	global_load_dwordx4 v[32:35], v36, s[100:101]
	s_nop 0
	global_load_dwordx4 v[36:39], v36, s[100:101] offset:64
	s_nop 0
	global_load_dwordx4 v[48:51], v40, s[100:101]
	global_load_dwordx4 v[52:55], v40, s[100:101] offset:64
	v_add_u32_e32 v40, s1, v155
	v_med3_i32 v40, v40, 0, s75
	v_lshl_add_u32 v40, v40, 9, v152
	global_load_dwordx4 v[76:79], v40, s[98:99]
	v_add_u32_e32 v40, s1, v172
	v_med3_i32 v40, v40, 0, s75
	v_lshl_add_u32 v40, v40, 9, v152
	global_load_dwordx4 v[84:87], v40, s[98:99]
	v_add_u32_e32 v40, s1, v173
	v_med3_i32 v40, v40, 0, s75
	v_lshl_add_u32 v40, v40, 9, v152
	global_load_dwordx4 v[88:91], v40, s[98:99]
	v_add_u32_e32 v40, s1, v182
	s_min_i32 s1, s0, 0
	s_sub_i32 s1, 0, s1
	v_med3_i32 v40, v40, 0, s75
	v_lshl_add_u32 v40, v40, 9, v152
	global_load_dwordx4 v[92:95], v40, s[98:99]
	v_min_i32_e32 v40, s75, v56
	v_cmp_lt_i32_e32 vcc, -1, v56
	v_add_u32_e32 v56, 16, v56
	s_nop 0
	v_cndmask_b32_e32 v40, 0, v40, vcc
	v_med3_i32 v56, v56, 0, s75
	v_lshl_add_u32 v44, v40, 9, v158
	v_lshl_add_u32 v60, v56, 9, v158
	global_load_dwordx4 v[40:43], v44, s[100:101]
	s_nop 0
	global_load_dwordx4 v[44:47], v44, s[100:101] offset:64
	s_nop 0
	global_load_dwordx4 v[56:59], v60, s[100:101]
	s_nop 0
	global_load_dwordx4 v[60:63], v60, s[100:101] offset:64
	s_waitcnt vmcnt(15)
	ds_write_b128 v241, v[16:19]
	s_waitcnt vmcnt(14)
	ds_write_b128 v242, v[20:23]
	s_waitcnt vmcnt(13)
	ds_write_b128 v243, v[24:27]
	s_waitcnt vmcnt(12)
	ds_write_b128 v244, v[28:31]
	v_or_b32_e32 v24, 16, v166
	v_add_u32_e32 v24, s76, v24
	v_med3_i32 v16, v149, 0, s75
	v_lshl_add_u32 v16, v16, 9, v152
	global_load_dwordx4 v[64:67], v16, s[98:99]
	s_sub_i32 s0, s75, s0
	v_med3_i32 v16, v150, 0, s75
	v_lshl_add_u32 v16, v16, 9, v152
	global_load_dwordx4 v[68:71], v16, s[98:99]
	v_max_i32_e32 v147, s1, v250
	v_max_i32_e32 v148, s1, v249
	v_med3_i32 v16, v151, 0, s75
	v_lshl_add_u32 v16, v16, 9, v152
	global_load_dwordx4 v[72:75], v16, s[98:99]
	v_med3_i32 v16, v252, 0, s75
	v_lshl_add_u32 v16, v16, 9, v152
	global_load_dwordx4 v[80:83], v16, s[98:99]
	v_add_u32_e32 v16, s76, v166
	v_med3_i32 v16, v16, 0, s75
	v_med3_i32 v24, v24, 0, s75
	v_lshl_add_u32 v20, v16, 9, v158
	v_lshl_add_u32 v28, v24, 9, v158
	global_load_dwordx4 v[16:19], v20, s[100:101]
	s_nop 0
	global_load_dwordx4 v[20:23], v20, s[100:101] offset:64
	s_nop 0
	global_load_dwordx4 v[24:27], v28, s[100:101]
	s_nop 0
	global_load_dwordx4 v[28:31], v28, s[100:101] offset:64
	ds_read_b64_tr_b16 v[98:99], v169 offset:2304
	ds_read_b64_tr_b16 v[96:97], v169
	ds_read_b64_tr_b16 v[100:101], v169 offset:32
	ds_read_b64_tr_b16 v[102:103], v169 offset:2336
	ds_read_b64_tr_b16 v[116:117], v169 offset:64
	ds_read_b64_tr_b16 v[118:119], v169 offset:2368
	ds_read_b64_tr_b16 v[134:135], v169 offset:96
	ds_read_b64_tr_b16 v[136:137], v169 offset:2400
	s_waitcnt vmcnt(15)
	ds_write_b128 v241, v[76:79] offset:4608
	s_waitcnt vmcnt(14)
	ds_write_b128 v242, v[84:87] offset:4608
	s_waitcnt vmcnt(13)
	ds_write_b128 v243, v[88:91] offset:4608
	s_waitcnt vmcnt(12)
	ds_write_b128 v244, v[92:95] offset:4608
	v_mfma_f32_16x16x32_bf16 v[76:79], v[32:35], v[4:7], 0
	v_mfma_f32_16x16x32_bf16 v[32:35], v[32:35], v[12:15], 0
	v_mfma_f32_16x16x32_bf16 v[76:79], v[36:39], v[8:11], v[76:79]
	v_mfma_f32_16x16x32_bf16 v[84:87], v[48:51], v[4:7], 0
	v_mfma_f32_16x16x32_bf16 v[32:35], v[36:39], v[0:3], v[32:35]
	v_mfma_f32_16x16x32_bf16 v[36:39], v[48:51], v[12:15], 0
	v_add_u32_e32 v48, s22, v251
	v_min3_i32 v48, v48, s0, v245
	v_sub_u32_e32 v49, v154, v147
	v_sub_u32_e32 v146, v48, v147
	v_add_u32_e32 v48, s22, v144
	v_min3_i32 v48, v48, s0, v245
	v_add_u32_e32 v51, 1, v49
	v_sub_u32_e32 v145, v48, v148
	v_cmp_gt_u32_e64 s[0:1], v51, v146
	v_cmp_gt_u32_e32 vcc, v49, v146
	s_nop 0
	v_cndmask_b32_e64 v77, v77, v246, s[0:1]
	s_nop 0
	v_cndmask_b32_e32 v76, v76, v246, vcc
	v_max_f32_e32 v48, 0xf149f2ca, v76
	v_mfma_f32_16x16x32_bf16 v[84:87], v[52:55], v[8:11], v[84:87]
	v_max_f32_e32 v48, v48, v77
	v_add_u32_e32 v51, 2, v49
	v_cmp_gt_u32_e64 s[22:23], v51, v146
	v_mfma_f32_16x16x32_bf16 v[36:39], v[52:55], v[0:3], v[36:39]
	v_add_u32_e32 v52, 3, v49
	v_cmp_gt_u32_e64 s[24:25], v52, v146
	v_cndmask_b32_e64 v78, v78, v246, s[22:23]
	v_sub_u32_e32 v50, v154, v148
	v_cndmask_b32_e64 v79, v79, v246, s[24:25]
	v_max3_f32 v48, v48, v78, v79
	v_add_u32_e32 v51, 16, v49
	v_add_u32_e32 v52, 17, v49
	v_cmp_gt_u32_e64 s[26:27], v51, v146
	v_cmp_gt_u32_e64 s[28:29], v52, v146
	v_cmp_gt_u32_e64 s[38:39], v50, v145
	v_cndmask_b32_e64 v84, v84, v246, s[26:27]
	v_cndmask_b32_e64 v85, v85, v246, s[28:29]
	v_max3_f32 v48, v48, v84, v85
	v_add_u32_e32 v51, 18, v49
	v_add_u32_e32 v49, 19, v49
	v_cmp_gt_u32_e64 s[30:31], v51, v146
	v_cmp_gt_u32_e64 s[34:35], v49, v146
	v_add_u32_e32 v52, 3, v50
	v_cndmask_b32_e64 v86, v86, v246, s[30:31]
	v_cndmask_b32_e64 v87, v87, v246, s[34:35]
	v_max3_f32 v48, v48, v86, v87
	v_add_u32_e32 v51, 1, v50
	v_cmp_gt_u32_e64 s[40:41], v51, v145
	v_cndmask_b32_e64 v32, v32, v246, s[38:39]
	v_max_f32_e32 v49, 0xf149f2ca, v32
	v_cndmask_b32_e64 v33, v33, v246, s[40:41]
	v_max_f32_e32 v49, v49, v33
	v_add_u32_e32 v51, 2, v50
	v_cmp_gt_u32_e64 s[42:43], v51, v145
	v_cmp_gt_u32_e64 s[44:45], v52, v145
	s_nop 0
	v_cndmask_b32_e64 v34, v34, v246, s[42:43]
	v_cndmask_b32_e64 v35, v35, v246, s[44:45]
	v_max3_f32 v49, v49, v34, v35
	v_add_u32_e32 v51, 16, v50
	v_add_u32_e32 v52, 17, v50
	v_cmp_gt_u32_e64 s[46:47], v51, v145
	v_cmp_gt_u32_e64 s[48:49], v52, v145
	s_nop 0
	v_cndmask_b32_e64 v36, v36, v246, s[46:47]
	v_cndmask_b32_e64 v37, v37, v246, s[48:49]
	v_max3_f32 v49, v49, v36, v37
	v_add_u32_e32 v51, 18, v50
	v_add_u32_e32 v50, 19, v50
	v_cmp_gt_u32_e64 s[50:51], v51, v145
	v_cmp_gt_u32_e64 s[52:53], v50, v145
	s_nop 0
	v_cndmask_b32_e64 v38, v38, v246, s[50:51]
	v_cndmask_b32_e64 v39, v39, v246, s[52:53]
	v_max3_f32 v49, v49, v38, v39
	v_mov_b32_e32 v50, v48
	v_mov_b32_e32 v51, v48
	s_nop 1
	v_permlane32_swap_b32_e32 v50, v51
	v_max3_f32 v48, v48, v50, v51
	v_mov_b32_e32 v50, v49
	v_mov_b32_e32 v51, v49
	s_nop 1
	v_permlane32_swap_b32_e32 v50, v51
	v_max3_f32 v49, v49, v50, v51
	v_mov_b32_e32 v50, v48
	v_mov_b32_e32 v51, v48
	s_nop 1
	v_permlane16_swap_b32_e32 v50, v51
	v_max_f32_e32 v48, v48, v50
	v_mov_b32_e32 v50, v49
	v_mov_b32_e32 v88, v49
	s_nop 1
	v_permlane16_swap_b32_e32 v50, v88
	v_max3_f32 v129, v48, v51, s73
	v_sub_f32_e32 v48, 0xf149f2ca, v129
	v_max_f32_e32 v49, v49, v50
	v_exp_f32_e32 v50, v48
	v_sub_f32_e32 v48, v76, v129
	v_exp_f32_e32 v48, v48
	v_sub_f32_e32 v52, v77, v129
	v_max3_f32 v131, v49, v88, s73
	v_exp_f32_e32 v52, v52
	v_sub_f32_e32 v36, v36, v131
	v_sub_f32_e32 v53, v78, v129
	v_exp_f32_e32 v36, v36
	v_exp_f32_e32 v53, v53
	v_sub_f32_e32 v54, v79, v129
	v_cndmask_b32_e64 v51, v48, 0, vcc
	v_exp_f32_e32 v54, v54
	v_sub_f32_e32 v55, v84, v129
	v_add_f32_e32 v48, 0, v51
	v_exp_f32_e32 v55, v55
	v_sub_f32_e32 v76, v85, v129
	v_add_f32_e32 v48, v52, v48
	v_exp_f32_e32 v76, v76
	v_sub_f32_e32 v77, v86, v129
	v_cvt_pk_bf16_f32 v52, v51, v52
	v_cndmask_b32_e64 v51, v36, 0, s[46:47]
	v_sub_f32_e32 v36, v37, v131
	v_exp_f32_e32 v77, v77
	v_sub_f32_e32 v78, v87, v129
	v_exp_f32_e32 v36, v36
	v_add_f32_e32 v48, v53, v48
	v_exp_f32_e32 v78, v78
	v_add_f32_e32 v48, v54, v48
	v_sub_f32_e32 v32, v32, v131
	v_add_f32_e32 v48, v55, v48
	v_exp_f32_e32 v32, v32
	v_sub_f32_e32 v33, v33, v131
	v_add_f32_e32 v48, v76, v48
	v_cvt_pk_bf16_f32 v53, v53, v54
	v_cvt_pk_bf16_f32 v54, v55, v76
	v_exp_f32_e32 v33, v33
	v_sub_f32_e32 v34, v34, v131
	v_cndmask_b32_e64 v76, v36, 0, s[48:49]
	v_sub_f32_e32 v36, v38, v131
	v_add_f32_e32 v48, v77, v48
	v_exp_f32_e32 v34, v34
	v_sub_f32_e32 v35, v35, v131
	v_exp_f32_e32 v36, v36
	v_add_f32_e32 v130, v78, v48
	v_exp_f32_e32 v35, v35
	v_mul_f32_e32 v48, 0, v50
	v_fmac_f32_e32 v130, 0, v50
	v_cndmask_b32_e64 v50, v32, 0, s[38:39]
	v_add_f32_e32 v32, 0, v50
	v_cvt_pk_bf16_f32 v55, v77, v78
	v_add_f32_e32 v32, v33, v32
	v_cndmask_b32_e64 v77, v36, 0, s[50:51]
	v_sub_f32_e32 v36, v39, v131
	v_sub_f32_e32 v49, 0xf149f2ca, v131
	v_add_f32_e32 v32, v34, v32
	v_exp_f32_e32 v36, v36
	v_exp_f32_e32 v49, v49
	v_add_f32_e32 v32, v35, v32
	v_add_f32_e32 v32, v51, v32
	v_add_f32_e32 v32, v76, v32
	v_add_f32_e32 v32, v77, v32
	v_cndmask_b32_e64 v39, v36, 0, s[52:53]
	v_add_f32_e32 v132, v39, v32
	v_mul_f32_e32 v32, 0, v49
	v_fmac_f32_e32 v132, 0, v49
	v_cvt_pk_bf16_f32 v36, v50, v33
	v_cvt_pk_bf16_f32 v37, v34, v35
	v_cvt_pk_bf16_f32 v38, v51, v76
	v_cvt_pk_bf16_f32 v39, v77, v39
	v_mov_b32_e32 v49, v48
	v_mov_b32_e32 v50, v48
	v_mov_b32_e32 v51, v48
	v_mov_b32_e32 v33, v32
	v_mov_b32_e32 v34, v32
	v_mov_b32_e32 v35, v32
	s_waitcnt lgkmcnt(6)
	v_mfma_f32_16x16x32_bf16 v[112:115], v[116:119], v[52:55], v[48:51]
	v_mfma_f32_16x16x32_bf16 v[124:127], v[96:99], v[36:39], v[32:35]
	v_mfma_f32_16x16x32_bf16 v[108:111], v[100:103], v[36:39], v[32:35]
	v_mfma_f32_16x16x32_bf16 v[116:119], v[116:119], v[36:39], v[32:35]
	s_waitcnt lgkmcnt(4)
	v_mfma_f32_16x16x32_bf16 v[88:91], v[134:137], v[36:39], v[32:35]
	s_nop 2
	v_add_u32_e32 v32, 32, v155
	v_add_u32_e32 v32, s76, v32
	v_mfma_f32_16x16x32_bf16 v[120:123], v[96:99], v[52:55], v[48:51]
	s_nop 0
	v_med3_i32 v32, v32, 0, s75
	v_lshl_add_u32 v32, v32, 9, v152
	global_load_dwordx4 v[76:79], v32, s[98:99]
	v_add_u32_e32 v32, 32, v172
	v_add_u32_e32 v32, s76, v32
	v_mfma_f32_16x16x32_bf16 v[104:107], v[100:103], v[52:55], v[48:51]
	s_nop 0
	v_med3_i32 v32, v32, 0, s75
	v_lshl_add_u32 v32, v32, 9, v152
	global_load_dwordx4 v[84:87], v32, s[98:99]
	v_add_u32_e32 v32, 32, v173
	v_add_u32_e32 v32, s76, v32
	v_mfma_f32_16x16x32_bf16 v[96:99], v[134:137], v[52:55], v[48:51]
	s_nop 0
	v_med3_i32 v32, v32, 0, s75
	v_lshl_add_u32 v32, v32, 9, v152
	global_load_dwordx4 v[92:95], v32, s[98:99]
	v_add_u32_e32 v32, 32, v182
	v_add_u32_e32 v32, s76, v32
	v_or_b32_e32 v48, 48, v166
	v_add_u32_e32 v48, s76, v48
	v_med3_i32 v32, v32, 0, s75
	v_lshl_add_u32 v32, v32, 9, v152
	global_load_dwordx4 v[100:103], v32, s[98:99]
	v_add_u32_e32 v32, s76, v128
	s_nop 0
	v_med3_i32 v32, v32, 0, s75
	v_med3_i32 v48, v48, 0, s75
	v_lshl_add_u32 v36, v32, 9, v158
	v_lshl_add_u32 v52, v48, 9, v158
	global_load_dwordx4 v[32:35], v36, s[100:101]
	s_nop 0
	global_load_dwordx4 v[36:39], v36, s[100:101] offset:64
	s_nop 0
	global_load_dwordx4 v[48:51], v52, s[100:101]
	s_nop 0
	global_load_dwordx4 v[52:55], v52, s[100:101] offset:64
	ds_read_b64_tr_b16 v[136:137], v169 offset:6912
	ds_read_b64_tr_b16 v[134:135], v169 offset:4608
	ds_read_b64_tr_b16 v[138:139], v169 offset:4640
	ds_read_b64_tr_b16 v[140:141], v169 offset:6944
	ds_read_b64_tr_b16 v[176:177], v169 offset:4672
	ds_read_b64_tr_b16 v[178:179], v169 offset:6976
	ds_read_b64_tr_b16 v[188:189], v169 offset:4704
	ds_read_b64_tr_b16 v[190:191], v169 offset:7008
	s_waitcnt vmcnt(15)
	ds_write_b128 v241, v[64:67]
	s_waitcnt vmcnt(14)
	ds_write_b128 v242, v[68:71]
	s_waitcnt vmcnt(13)
	ds_write_b128 v243, v[72:75]
	s_waitcnt vmcnt(12)
	ds_write_b128 v244, v[80:83]
	v_mfma_f32_16x16x32_bf16 v[64:67], v[40:43], v[4:7], 0
	v_mfma_f32_16x16x32_bf16 v[40:43], v[40:43], v[12:15], 0
	v_mfma_f32_16x16x32_bf16 v[64:67], v[44:47], v[8:11], v[64:67]
	v_mfma_f32_16x16x32_bf16 v[68:71], v[56:59], v[4:7], 0
	v_mfma_f32_16x16x32_bf16 v[40:43], v[44:47], v[0:3], v[40:43]
	v_mfma_f32_16x16x32_bf16 v[44:47], v[56:59], v[12:15], 0
	v_sub_u32_e32 v56, v187, v147
	v_add_u32_e32 v59, 1, v56
	s_nop 2
	v_cmp_gt_u32_e64 s[0:1], v59, v146
	v_cmp_gt_u32_e32 vcc, v56, v146
	s_nop 0
	v_cndmask_b32_e64 v65, v65, v246, s[0:1]
	s_nop 0
	v_cndmask_b32_e32 v64, v64, v246, vcc
	v_max_f32_e32 v58, 0xf149f2ca, v64
	v_mfma_f32_16x16x32_bf16 v[68:71], v[60:63], v[8:11], v[68:71]
	v_max_f32_e32 v58, v58, v65
	v_add_u32_e32 v59, 2, v56
	v_cmp_gt_u32_e64 s[22:23], v59, v146
	v_mfma_f32_16x16x32_bf16 v[44:47], v[60:63], v[0:3], v[44:47]
	v_add_u32_e32 v60, 3, v56
	v_cmp_gt_u32_e64 s[24:25], v60, v146
	v_cndmask_b32_e64 v66, v66, v246, s[22:23]
	v_sub_u32_e32 v57, v187, v148
	v_cndmask_b32_e64 v67, v67, v246, s[24:25]
	v_max3_f32 v58, v58, v66, v67
	v_add_u32_e32 v59, 16, v56
	v_add_u32_e32 v60, 17, v56
	v_cmp_gt_u32_e64 s[26:27], v59, v146
	v_cmp_gt_u32_e64 s[28:29], v60, v146
	v_cmp_gt_u32_e64 s[38:39], v57, v145
	v_cndmask_b32_e64 v68, v68, v246, s[26:27]
	v_cndmask_b32_e64 v69, v69, v246, s[28:29]
	v_max3_f32 v58, v58, v68, v69
	v_add_u32_e32 v59, 18, v56
	v_add_u32_e32 v56, 19, v56
	v_cmp_gt_u32_e64 s[30:31], v59, v146
	v_cmp_gt_u32_e64 s[34:35], v56, v146
	v_add_u32_e32 v60, 3, v57
	v_cndmask_b32_e64 v70, v70, v246, s[30:31]
	v_cndmask_b32_e64 v71, v71, v246, s[34:35]
	v_max3_f32 v56, v58, v70, v71
	v_add_u32_e32 v59, 1, v57
	v_cmp_gt_u32_e64 s[40:41], v59, v145
	v_cndmask_b32_e64 v40, v40, v246, s[38:39]
	v_max_f32_e32 v58, 0xf149f2ca, v40
	v_cndmask_b32_e64 v41, v41, v246, s[40:41]
	v_max_f32_e32 v58, v58, v41
	v_add_u32_e32 v59, 2, v57
	v_cmp_gt_u32_e64 s[42:43], v59, v145
	v_cmp_gt_u32_e64 s[44:45], v60, v145
	s_nop 0
	v_cndmask_b32_e64 v42, v42, v246, s[42:43]
	v_cndmask_b32_e64 v43, v43, v246, s[44:45]
	v_max3_f32 v58, v58, v42, v43
	v_add_u32_e32 v59, 16, v57
	v_add_u32_e32 v60, 17, v57
	v_cmp_gt_u32_e64 s[46:47], v59, v145
	v_cmp_gt_u32_e64 s[48:49], v60, v145
	s_nop 0
	v_cndmask_b32_e64 v44, v44, v246, s[46:47]
	v_cndmask_b32_e64 v45, v45, v246, s[48:49]
	v_max3_f32 v58, v58, v44, v45
	v_add_u32_e32 v59, 18, v57
	v_add_u32_e32 v57, 19, v57
	v_cmp_gt_u32_e64 s[50:51], v59, v145
	v_cmp_gt_u32_e64 s[52:53], v57, v145
	s_nop 0
	v_cndmask_b32_e64 v46, v46, v246, s[50:51]
	v_cndmask_b32_e64 v47, v47, v246, s[52:53]
	v_max3_f32 v57, v58, v46, v47
	v_mov_b32_e32 v58, v56
	v_mov_b32_e32 v59, v56
	s_nop 1
	v_permlane32_swap_b32_e32 v58, v59
	v_max3_f32 v56, v56, v58, v59
	v_mov_b32_e32 v58, v57
	v_mov_b32_e32 v59, v57
	s_nop 1
	v_permlane32_swap_b32_e32 v58, v59
	v_max3_f32 v57, v57, v58, v59
	v_mov_b32_e32 v58, v56
	v_mov_b32_e32 v59, v56
	s_nop 1
	v_permlane16_swap_b32_e32 v58, v59
	v_max_f32_e32 v56, v56, v58
	v_mov_b32_e32 v58, v57
	v_mov_b32_e32 v61, v57
	v_max3_f32 v128, v129, v56, v59
	s_nop 0
	v_permlane16_swap_b32_e32 v58, v61
	v_sub_f32_e32 v56, v129, v128
	v_exp_f32_e32 v60, v56
	v_sub_f32_e32 v56, v64, v128
	v_max_f32_e32 v62, v57, v58
	v_exp_f32_e32 v56, v56
	v_sub_f32_e32 v58, v65, v128
	v_exp_f32_e32 v58, v58
	v_sub_f32_e32 v59, v66, v128
	v_exp_f32_e32 v59, v59
	v_sub_f32_e32 v63, v67, v128
	v_exp_f32_e32 v63, v63
	v_sub_f32_e32 v64, v68, v128
	v_exp_f32_e32 v64, v64
	v_sub_f32_e32 v65, v69, v128
	v_add_f32_e32 v57, 0, v56
	v_exp_f32_e32 v65, v65
	v_sub_f32_e32 v66, v70, v128
	v_add_f32_e32 v57, v58, v57
	v_exp_f32_e32 v66, v66
	v_sub_f32_e32 v67, v71, v128
	v_add_f32_e32 v57, v59, v57
	v_exp_f32_e32 v67, v67
	v_add_f32_e32 v57, v63, v57
	v_add_f32_e32 v57, v64, v57
	v_add_f32_e32 v57, v65, v57
	v_add_f32_e32 v57, v66, v57
	v_add_f32_e32 v129, v67, v57
	v_fmac_f32_e32 v129, v130, v60
	v_max3_f32 v130, v131, v62, v61
	v_sub_f32_e32 v40, v40, v130
	v_exp_f32_e32 v40, v40
	v_sub_f32_e32 v41, v41, v130
	v_exp_f32_e32 v41, v41
	v_sub_f32_e32 v42, v42, v130
	v_exp_f32_e32 v42, v42
	v_sub_f32_e32 v43, v43, v130
	v_exp_f32_e32 v43, v43
	v_sub_f32_e32 v44, v44, v130
	v_sub_f32_e32 v61, v131, v130
	v_exp_f32_e32 v44, v44
	v_sub_f32_e32 v45, v45, v130
	v_exp_f32_e32 v62, v61
	v_add_f32_e32 v61, 0, v40
	v_exp_f32_e32 v45, v45
	v_sub_f32_e32 v46, v46, v130
	v_add_f32_e32 v61, v41, v61
	v_exp_f32_e32 v46, v46
	v_sub_f32_e32 v47, v47, v130
	v_add_f32_e32 v61, v42, v61
	v_exp_f32_e32 v47, v47
	v_add_f32_e32 v61, v43, v61
	v_add_f32_e32 v61, v44, v61
	v_add_f32_e32 v61, v45, v61
	v_add_f32_e32 v61, v46, v61
	v_cvt_pk_bf16_f32 v56, v56, v58
	v_cvt_pk_bf16_f32 v57, v59, v63
	v_cvt_pk_bf16_f32 v58, v64, v65
	v_cvt_pk_bf16_f32 v59, v66, v67
	v_add_f32_e32 v131, v47, v61
	v_cvt_pk_bf16_f32 v40, v40, v41
	v_cvt_pk_bf16_f32 v41, v42, v43
	v_cvt_pk_bf16_f32 v42, v44, v45
	v_cvt_pk_bf16_f32 v43, v46, v47
	v_pk_mul_f32 v[46:47], v[122:123], v[60:61] op_sel_hi:[1,0]
	v_pk_mul_f32 v[44:45], v[120:121], v[60:61] op_sel_hi:[1,0]
	v_fmac_f32_e32 v131, v132, v62
	s_waitcnt lgkmcnt(10)
	v_mfma_f32_16x16x32_bf16 v[64:67], v[134:137], v[56:59], v[44:47]
	s_nop 2
	v_mul_f32_e64 v46, v126, v62
	v_mul_f32_e64 v47, v127, v62
	v_pk_mul_f32 v[44:45], v[124:125], v[62:63] op_sel_hi:[1,0]
	s_nop 1
	v_mfma_f32_16x16x32_bf16 v[68:71], v[134:137], v[40:43], v[44:47]
	s_nop 2
	v_mul_f32_e64 v46, v106, v60
	v_mul_f32_e64 v47, v107, v60
	v_pk_mul_f32 v[44:45], v[104:105], v[60:61] op_sel_hi:[1,0]
	s_waitcnt lgkmcnt(8)
	s_nop 0
	v_mfma_f32_16x16x32_bf16 v[104:107], v[138:141], v[56:59], v[44:47]
	s_nop 2
	v_mul_f32_e64 v46, v110, v62
	v_mul_f32_e64 v47, v111, v62
	v_pk_mul_f32 v[44:45], v[108:109], v[62:63] op_sel_hi:[1,0]
	s_nop 1
	v_mfma_f32_16x16x32_bf16 v[108:111], v[138:141], v[40:43], v[44:47]
	s_nop 2
	v_mul_f32_e64 v46, v114, v60
	v_mul_f32_e64 v47, v115, v60
	v_pk_mul_f32 v[44:45], v[112:113], v[60:61] op_sel_hi:[1,0]
	s_waitcnt lgkmcnt(6)
	s_nop 0
	v_mfma_f32_16x16x32_bf16 v[112:115], v[176:179], v[56:59], v[44:47]
	s_nop 2
	v_mul_f32_e64 v46, v118, v62
	v_mul_f32_e64 v47, v119, v62
	v_pk_mul_f32 v[44:45], v[116:117], v[62:63] op_sel_hi:[1,0]
	s_nop 1
	v_mfma_f32_16x16x32_bf16 v[116:119], v[176:179], v[40:43], v[44:47]
	s_nop 2
	v_mul_f32_e64 v46, v98, v60
	v_mul_f32_e64 v47, v99, v60
	v_pk_mul_f32 v[44:45], v[96:97], v[60:61] op_sel_hi:[1,0]
	s_waitcnt lgkmcnt(4)
	s_nop 0
	v_mfma_f32_16x16x32_bf16 v[120:123], v[188:191], v[56:59], v[44:47]
	v_or_b32_e32 v56, 0x50, v166
	v_add_u32_e32 v56, s76, v56
	s_nop 0
	v_pk_mul_f32 v[46:47], v[90:91], v[62:63] op_sel_hi:[1,0]
	v_pk_mul_f32 v[44:45], v[88:89], v[62:63] op_sel_hi:[1,0]
	s_nop 1
	v_mfma_f32_16x16x32_bf16 v[124:127], v[188:191], v[40:43], v[44:47]
	v_add_u32_e32 v40, 64, v155
	v_add_u32_e32 v40, s76, v40
	v_med3_i32 v40, v40, 0, s75
	v_lshl_add_u32 v40, v40, 9, v152
	global_load_dwordx4 v[72:75], v40, s[98:99]
	v_add_u32_e32 v40, 64, v172
	v_add_u32_e32 v40, s76, v40
	v_med3_i32 v40, v40, 0, s75
	v_lshl_add_u32 v40, v40, 9, v152
	global_load_dwordx4 v[80:83], v40, s[98:99]
	v_add_u32_e32 v40, 64, v173
	v_add_u32_e32 v40, s76, v40
	v_med3_i32 v40, v40, 0, s75
	v_lshl_add_u32 v40, v40, 9, v152
	global_load_dwordx4 v[88:91], v40, s[98:99]
	v_add_u32_e32 v40, 64, v182
	v_add_u32_e32 v40, s76, v40
	v_med3_i32 v40, v40, 0, s75
	v_lshl_add_u32 v40, v40, 9, v152
	global_load_dwordx4 v[96:99], v40, s[98:99]
	v_or_b32_e32 v40, 64, v166
	v_add_u32_e32 v40, s76, v40
	v_med3_i32 v40, v40, 0, s75
	v_med3_i32 v56, v56, 0, s75
	v_lshl_add_u32 v44, v40, 9, v158
	v_lshl_add_u32 v60, v56, 9, v158
	global_load_dwordx4 v[40:43], v44, s[100:101]
	s_nop 0
	global_load_dwordx4 v[44:47], v44, s[100:101] offset:64
	s_nop 0
	global_load_dwordx4 v[56:59], v60, s[100:101]
	s_nop 0
	global_load_dwordx4 v[60:63], v60, s[100:101] offset:64
	ds_read_b64_tr_b16 v[136:137], v169 offset:2304
	ds_read_b64_tr_b16 v[134:135], v169
	ds_read_b64_tr_b16 v[138:139], v169 offset:32
	ds_read_b64_tr_b16 v[140:141], v169 offset:2336
	ds_read_b64_tr_b16 v[176:177], v169 offset:64
	ds_read_b64_tr_b16 v[178:179], v169 offset:2368
	ds_read_b64_tr_b16 v[188:189], v169 offset:96
	ds_read_b64_tr_b16 v[190:191], v169 offset:2400
	s_waitcnt vmcnt(15)
	ds_write_b128 v241, v[76:79] offset:4608
	s_waitcnt vmcnt(14)
	ds_write_b128 v242, v[84:87] offset:4608
	s_waitcnt vmcnt(13)
	ds_write_b128 v243, v[92:95] offset:4608
	s_waitcnt vmcnt(12)
	ds_write_b128 v244, v[100:103] offset:4608
	v_mfma_f32_16x16x32_bf16 v[76:79], v[16:19], v[4:7], 0
	v_mfma_f32_16x16x32_bf16 v[16:19], v[16:19], v[12:15], 0
	v_mfma_f32_16x16x32_bf16 v[76:79], v[20:23], v[8:11], v[76:79]
	v_mfma_f32_16x16x32_bf16 v[84:87], v[24:27], v[4:7], 0
	v_mfma_f32_16x16x32_bf16 v[16:19], v[20:23], v[0:3], v[16:19]
	v_mfma_f32_16x16x32_bf16 v[20:23], v[24:27], v[12:15], 0
	v_sub_u32_e32 v24, v192, v147
	v_add_u32_e32 v27, 1, v24
	s_nop 2
	v_cmp_gt_u32_e64 s[0:1], v27, v146
	v_cmp_gt_u32_e32 vcc, v24, v146
	s_nop 0
	v_cndmask_b32_e64 v77, v77, v246, s[0:1]
	s_nop 0
	v_cndmask_b32_e32 v76, v76, v246, vcc
	v_max_f32_e32 v26, 0xf149f2ca, v76
	v_mfma_f32_16x16x32_bf16 v[84:87], v[28:31], v[8:11], v[84:87]
	v_max_f32_e32 v26, v26, v77
	v_add_u32_e32 v27, 2, v24
	v_cmp_gt_u32_e64 s[22:23], v27, v146
	v_mfma_f32_16x16x32_bf16 v[20:23], v[28:31], v[0:3], v[20:23]
	v_add_u32_e32 v28, 3, v24
	v_cmp_gt_u32_e64 s[24:25], v28, v146
	v_cndmask_b32_e64 v78, v78, v246, s[22:23]
	v_sub_u32_e32 v25, v192, v148
	v_cndmask_b32_e64 v79, v79, v246, s[24:25]
	v_max3_f32 v26, v26, v78, v79
	v_add_u32_e32 v27, 16, v24
	v_add_u32_e32 v28, 17, v24
	v_cmp_gt_u32_e64 s[26:27], v27, v146
	v_cmp_gt_u32_e64 s[28:29], v28, v146
	v_cmp_gt_u32_e64 s[38:39], v25, v145
	v_cndmask_b32_e64 v84, v84, v246, s[26:27]
	v_cndmask_b32_e64 v85, v85, v246, s[28:29]
	v_max3_f32 v26, v26, v84, v85
	v_add_u32_e32 v27, 18, v24
	v_add_u32_e32 v24, 19, v24
	v_cmp_gt_u32_e64 s[30:31], v27, v146
	v_cmp_gt_u32_e64 s[34:35], v24, v146
	v_add_u32_e32 v28, 3, v25
	v_cndmask_b32_e64 v86, v86, v246, s[30:31]
	v_cndmask_b32_e64 v87, v87, v246, s[34:35]
	v_max3_f32 v24, v26, v86, v87
	v_add_u32_e32 v27, 1, v25
	v_cmp_gt_u32_e64 s[40:41], v27, v145
	v_cndmask_b32_e64 v16, v16, v246, s[38:39]
	v_max_f32_e32 v26, 0xf149f2ca, v16
	v_cndmask_b32_e64 v17, v17, v246, s[40:41]
	v_max_f32_e32 v26, v26, v17
	v_add_u32_e32 v27, 2, v25
	v_cmp_gt_u32_e64 s[42:43], v27, v145
	v_cmp_gt_u32_e64 s[44:45], v28, v145
	s_nop 0
	v_cndmask_b32_e64 v18, v18, v246, s[42:43]
	v_cndmask_b32_e64 v19, v19, v246, s[44:45]
	v_max3_f32 v26, v26, v18, v19
	v_add_u32_e32 v27, 16, v25
	v_add_u32_e32 v28, 17, v25
	v_cmp_gt_u32_e64 s[46:47], v27, v145
	v_cmp_gt_u32_e64 s[48:49], v28, v145
	s_nop 0
	v_cndmask_b32_e64 v20, v20, v246, s[46:47]
	v_cndmask_b32_e64 v21, v21, v246, s[48:49]
	v_max3_f32 v26, v26, v20, v21
	v_add_u32_e32 v27, 18, v25
	v_add_u32_e32 v25, 19, v25
	v_cmp_gt_u32_e64 s[50:51], v27, v145
	v_cmp_gt_u32_e64 s[52:53], v25, v145
	s_nop 0
	v_cndmask_b32_e64 v22, v22, v246, s[50:51]
	v_cndmask_b32_e64 v23, v23, v246, s[52:53]
	v_max3_f32 v25, v26, v22, v23
	v_mov_b32_e32 v26, v24
	v_mov_b32_e32 v27, v24
	s_nop 1
	v_permlane32_swap_b32_e32 v26, v27
	v_max3_f32 v24, v24, v26, v27
	v_mov_b32_e32 v26, v25
	v_mov_b32_e32 v27, v25
	s_nop 1
	v_permlane32_swap_b32_e32 v26, v27
	v_max3_f32 v25, v25, v26, v27
	v_mov_b32_e32 v26, v24
	v_mov_b32_e32 v27, v24
	s_nop 1
	v_permlane16_swap_b32_e32 v26, v27
	v_max_f32_e32 v24, v24, v26
	v_mov_b32_e32 v26, v25
	v_mov_b32_e32 v28, v25
	v_max3_f32 v132, v128, v24, v27
	s_nop 0
	v_permlane16_swap_b32_e32 v26, v28
	v_sub_f32_e32 v24, v128, v132
	v_exp_f32_e32 v92, v24
	v_sub_f32_e32 v24, v76, v132
	v_max_f32_e32 v29, v25, v26
	v_exp_f32_e32 v24, v24
	v_sub_f32_e32 v26, v77, v132
	v_exp_f32_e32 v26, v26
	v_sub_f32_e32 v27, v78, v132
	v_exp_f32_e32 v27, v27
	v_sub_f32_e32 v30, v79, v132
	v_exp_f32_e32 v30, v30
	v_sub_f32_e32 v31, v84, v132
	v_exp_f32_e32 v31, v31
	v_sub_f32_e32 v76, v85, v132
	v_add_f32_e32 v25, 0, v24
	v_exp_f32_e32 v76, v76
	v_sub_f32_e32 v77, v86, v132
	v_add_f32_e32 v25, v26, v25
	v_exp_f32_e32 v77, v77
	v_sub_f32_e32 v78, v87, v132
	v_add_f32_e32 v25, v27, v25
	v_exp_f32_e32 v78, v78
	v_add_f32_e32 v25, v30, v25
	v_add_f32_e32 v25, v31, v25
	v_add_f32_e32 v25, v76, v25
	v_add_f32_e32 v25, v77, v25
	v_add_f32_e32 v128, v78, v25
	v_fmac_f32_e32 v128, v129, v92
	v_max3_f32 v129, v130, v29, v28
	v_sub_f32_e32 v16, v16, v129
	v_exp_f32_e32 v16, v16
	v_sub_f32_e32 v17, v17, v129
	v_exp_f32_e32 v17, v17
	v_sub_f32_e32 v18, v18, v129
	v_exp_f32_e32 v18, v18
	v_sub_f32_e32 v19, v19, v129
	v_exp_f32_e32 v19, v19
	v_sub_f32_e32 v20, v20, v129
	v_sub_f32_e32 v28, v130, v129
	v_exp_f32_e32 v20, v20
	v_sub_f32_e32 v21, v21, v129
	v_cvt_pk_bf16_f32 v24, v24, v26
	v_cvt_pk_bf16_f32 v26, v31, v76
	v_exp_f32_e32 v76, v28
	v_add_f32_e32 v28, 0, v16
	v_exp_f32_e32 v21, v21
	v_sub_f32_e32 v22, v22, v129
	v_add_f32_e32 v28, v17, v28
	v_exp_f32_e32 v22, v22
	v_sub_f32_e32 v23, v23, v129
	v_add_f32_e32 v28, v18, v28
	v_exp_f32_e32 v23, v23
	v_add_f32_e32 v28, v19, v28
	v_add_f32_e32 v28, v20, v28
	v_add_f32_e32 v28, v21, v28
	v_add_f32_e32 v28, v22, v28
	v_cvt_pk_bf16_f32 v25, v27, v30
	v_cvt_pk_bf16_f32 v27, v77, v78
	v_add_f32_e32 v130, v23, v28
	v_cvt_pk_bf16_f32 v28, v16, v17
	v_cvt_pk_bf16_f32 v29, v18, v19
	v_pk_mul_f32 v[18:19], v[66:67], v[92:93] op_sel_hi:[1,0]
	v_pk_mul_f32 v[16:17], v[64:65], v[92:93] op_sel_hi:[1,0]
	v_pk_mul_f32 v[66:67], v[106:107], v[92:93] op_sel_hi:[1,0]
	v_pk_mul_f32 v[64:65], v[104:105], v[92:93] op_sel_hi:[1,0]
	v_cvt_pk_bf16_f32 v30, v20, v21
	v_cvt_pk_bf16_f32 v31, v22, v23
	s_waitcnt lgkmcnt(8)
	v_mfma_f32_16x16x32_bf16 v[104:107], v[138:141], v[24:27], v[64:67]
	v_fmac_f32_e32 v130, v131, v76
	v_pk_mul_f32 v[22:23], v[70:71], v[76:77] op_sel_hi:[1,0]
	v_pk_mul_f32 v[20:21], v[68:69], v[76:77] op_sel_hi:[1,0]
	v_pk_mul_f32 v[66:67], v[110:111], v[76:77] op_sel_hi:[1,0]
	v_pk_mul_f32 v[64:65], v[108:109], v[76:77] op_sel_hi:[1,0]
	v_mfma_f32_16x16x32_bf16 v[16:19], v[134:137], v[24:27], v[16:19]
	s_nop 0
	v_mfma_f32_16x16x32_bf16 v[108:111], v[138:141], v[28:31], v[64:67]
	s_nop 2
	v_mul_f32_e64 v66, v114, v92
	v_mul_f32_e64 v67, v115, v92
	v_pk_mul_f32 v[64:65], v[112:113], v[92:93] op_sel_hi:[1,0]
	v_mfma_f32_16x16x32_bf16 v[20:23], v[134:137], v[28:31], v[20:23]
	s_waitcnt lgkmcnt(6)
	v_mfma_f32_16x16x32_bf16 v[112:115], v[176:179], v[24:27], v[64:67]
	s_nop 2
	v_mul_f32_e64 v66, v118, v76
	v_mul_f32_e64 v67, v119, v76
	v_pk_mul_f32 v[64:65], v[116:117], v[76:77] op_sel_hi:[1,0]
	s_nop 1
	v_mfma_f32_16x16x32_bf16 v[116:119], v[176:179], v[28:31], v[64:67]
	s_nop 2
	v_mul_f32_e64 v66, v122, v92
	v_mul_f32_e64 v67, v123, v92
	v_pk_mul_f32 v[64:65], v[120:121], v[92:93] op_sel_hi:[1,0]
	s_waitcnt lgkmcnt(4)
	s_nop 0
	v_mfma_f32_16x16x32_bf16 v[120:123], v[188:191], v[24:27], v[64:67]
	v_mul_f32_e64 v26, v126, v76
	v_mul_f32_e64 v27, v127, v76
	v_pk_mul_f32 v[24:25], v[124:125], v[76:77] op_sel_hi:[1,0]
	v_or_b32_e32 v64, 0x70, v166
	s_nop 0
	v_mfma_f32_16x16x32_bf16 v[124:127], v[188:191], v[28:31], v[24:27]
	v_add_u32_e32 v64, s76, v64
	s_nop 0
	s_nop 0
	v_add_u32_e32 v24, s76, v196
	v_med3_i32 v24, v24, 0, s75
	v_lshl_add_u32 v24, v24, 9, v152
	global_load_dwordx4 v[76:79], v24, s[98:99]
	v_add_u32_e32 v24, s76, v168
	v_med3_i32 v24, v24, 0, s75
	v_lshl_add_u32 v24, v24, 9, v152
	global_load_dwordx4 v[84:87], v24, s[98:99]
	v_add_u32_e32 v24, s76, v193
	v_med3_i32 v24, v24, 0, s75
	v_lshl_add_u32 v24, v24, 9, v152
	global_load_dwordx4 v[92:95], v24, s[98:99]
	v_add_u32_e32 v24, s76, v194
	v_med3_i32 v24, v24, 0, s75
	v_lshl_add_u32 v24, v24, 9, v152
	global_load_dwordx4 v[100:103], v24, s[98:99]
	v_or_b32_e32 v24, 0x60, v166
	v_add_u32_e32 v24, s76, v24
	v_med3_i32 v24, v24, 0, s75
	v_med3_i32 v64, v64, 0, s75
	v_lshl_add_u32 v28, v24, 9, v158
	v_lshl_add_u32 v68, v64, 9, v158
	global_load_dwordx4 v[24:27], v28, s[100:101]
	s_nop 0
	global_load_dwordx4 v[28:31], v28, s[100:101] offset:64
	s_nop 0
	global_load_dwordx4 v[64:67], v68, s[100:101]
	s_nop 0
	global_load_dwordx4 v[68:71], v68, s[100:101] offset:64
	ds_read_b64_tr_b16 v[136:137], v169 offset:6912
	ds_read_b64_tr_b16 v[134:135], v169 offset:4608
	ds_read_b64_tr_b16 v[138:139], v169 offset:4640
	ds_read_b64_tr_b16 v[140:141], v169 offset:6944
	ds_read_b64_tr_b16 v[176:177], v169 offset:4672
	ds_read_b64_tr_b16 v[178:179], v169 offset:6976
	ds_read_b64_tr_b16 v[188:189], v169 offset:4704
	ds_read_b64_tr_b16 v[190:191], v169 offset:7008
	s_waitcnt vmcnt(15)
	ds_write_b128 v241, v[72:75]
	s_waitcnt vmcnt(14)
	ds_write_b128 v242, v[80:83]
	s_waitcnt vmcnt(13)
	ds_write_b128 v243, v[88:91]
	s_waitcnt vmcnt(12)
	ds_write_b128 v244, v[96:99]
	v_mfma_f32_16x16x32_bf16 v[72:75], v[32:35], v[4:7], 0
	v_mfma_f32_16x16x32_bf16 v[32:35], v[32:35], v[12:15], 0
	v_mfma_f32_16x16x32_bf16 v[72:75], v[36:39], v[8:11], v[72:75]
	v_mfma_f32_16x16x32_bf16 v[80:83], v[48:51], v[4:7], 0
	v_mfma_f32_16x16x32_bf16 v[32:35], v[36:39], v[0:3], v[32:35]
	v_mfma_f32_16x16x32_bf16 v[36:39], v[48:51], v[12:15], 0
	v_sub_u32_e32 v48, v197, v147
	v_add_u32_e32 v51, 1, v48
	s_nop 2
	v_cmp_gt_u32_e64 s[0:1], v51, v146
	v_cmp_gt_u32_e32 vcc, v48, v146
	s_nop 0
	v_cndmask_b32_e64 v73, v73, v246, s[0:1]
	s_nop 0
	v_cndmask_b32_e32 v72, v72, v246, vcc
	v_max_f32_e32 v50, 0xf149f2ca, v72
	v_mfma_f32_16x16x32_bf16 v[80:83], v[52:55], v[8:11], v[80:83]
	v_max_f32_e32 v50, v50, v73
	v_add_u32_e32 v51, 2, v48
	v_cmp_gt_u32_e64 s[22:23], v51, v146
	v_mfma_f32_16x16x32_bf16 v[36:39], v[52:55], v[0:3], v[36:39]
	v_add_u32_e32 v52, 3, v48
	v_cmp_gt_u32_e64 s[24:25], v52, v146
	v_cndmask_b32_e64 v74, v74, v246, s[22:23]
	v_sub_u32_e32 v49, v197, v148
	v_cndmask_b32_e64 v75, v75, v246, s[24:25]
	v_max3_f32 v50, v50, v74, v75
	v_add_u32_e32 v51, 16, v48
	v_add_u32_e32 v52, 17, v48
	v_cmp_gt_u32_e64 s[26:27], v51, v146
	v_cmp_gt_u32_e64 s[28:29], v52, v146
	v_cmp_gt_u32_e64 s[38:39], v49, v145
	v_cndmask_b32_e64 v80, v80, v246, s[26:27]
	v_cndmask_b32_e64 v81, v81, v246, s[28:29]
	v_max3_f32 v50, v50, v80, v81
	v_add_u32_e32 v51, 18, v48
	v_add_u32_e32 v48, 19, v48
	v_cmp_gt_u32_e64 s[30:31], v51, v146
	v_cmp_gt_u32_e64 s[34:35], v48, v146
	v_add_u32_e32 v52, 3, v49
	v_cndmask_b32_e64 v82, v82, v246, s[30:31]
	v_cndmask_b32_e64 v83, v83, v246, s[34:35]
	v_max3_f32 v48, v50, v82, v83
	v_add_u32_e32 v51, 1, v49
	v_cmp_gt_u32_e64 s[40:41], v51, v145
	v_cndmask_b32_e64 v32, v32, v246, s[38:39]
	v_max_f32_e32 v50, 0xf149f2ca, v32
	v_cndmask_b32_e64 v33, v33, v246, s[40:41]
	v_max_f32_e32 v50, v50, v33
	v_add_u32_e32 v51, 2, v49
	v_cmp_gt_u32_e64 s[42:43], v51, v145
	v_cmp_gt_u32_e64 s[44:45], v52, v145
	s_nop 0
	v_cndmask_b32_e64 v34, v34, v246, s[42:43]
	v_cndmask_b32_e64 v35, v35, v246, s[44:45]
	v_max3_f32 v50, v50, v34, v35
	v_add_u32_e32 v51, 16, v49
	v_add_u32_e32 v52, 17, v49
	v_cmp_gt_u32_e64 s[46:47], v51, v145
	v_cmp_gt_u32_e64 s[48:49], v52, v145
	s_nop 0
	v_cndmask_b32_e64 v36, v36, v246, s[46:47]
	v_cndmask_b32_e64 v37, v37, v246, s[48:49]
	v_max3_f32 v50, v50, v36, v37
	v_add_u32_e32 v51, 18, v49
	v_add_u32_e32 v49, 19, v49
	v_cmp_gt_u32_e64 s[50:51], v51, v145
	v_cmp_gt_u32_e64 s[52:53], v49, v145
	s_nop 0
	v_cndmask_b32_e64 v38, v38, v246, s[50:51]
	v_cndmask_b32_e64 v39, v39, v246, s[52:53]
	v_max3_f32 v49, v50, v38, v39
	v_mov_b32_e32 v50, v48
	v_mov_b32_e32 v51, v48
	s_nop 1
	v_permlane32_swap_b32_e32 v50, v51
	v_max3_f32 v48, v48, v50, v51
	v_mov_b32_e32 v50, v49
	v_mov_b32_e32 v51, v49
	s_nop 1
	v_permlane32_swap_b32_e32 v50, v51
	v_max3_f32 v49, v49, v50, v51
	v_mov_b32_e32 v50, v48
	v_mov_b32_e32 v51, v48
	s_nop 1
	v_permlane16_swap_b32_e32 v50, v51
	v_max_f32_e32 v48, v48, v50
	v_mov_b32_e32 v50, v49
	v_mov_b32_e32 v53, v49
	v_max3_f32 v131, v132, v48, v51
	s_nop 0
	v_permlane16_swap_b32_e32 v50, v53
	v_sub_f32_e32 v48, v132, v131
	v_exp_f32_e32 v52, v48
	v_sub_f32_e32 v48, v72, v131
	v_max_f32_e32 v54, v49, v50
	v_exp_f32_e32 v48, v48
	v_sub_f32_e32 v50, v73, v131
	v_exp_f32_e32 v50, v50
	v_sub_f32_e32 v51, v74, v131
	v_exp_f32_e32 v51, v51
	v_sub_f32_e32 v55, v75, v131
	v_exp_f32_e32 v55, v55
	v_sub_f32_e32 v72, v80, v131
	v_exp_f32_e32 v72, v72
	v_sub_f32_e32 v73, v81, v131
	v_add_f32_e32 v49, 0, v48
	v_exp_f32_e32 v73, v73
	v_sub_f32_e32 v74, v82, v131
	v_add_f32_e32 v49, v50, v49
	v_exp_f32_e32 v74, v74
	v_sub_f32_e32 v75, v83, v131
	v_add_f32_e32 v49, v51, v49
	v_exp_f32_e32 v75, v75
	v_add_f32_e32 v49, v55, v49
	v_add_f32_e32 v49, v72, v49
	v_add_f32_e32 v49, v73, v49
	v_add_f32_e32 v49, v74, v49
	v_add_f32_e32 v132, v75, v49
	v_fmac_f32_e32 v132, v128, v52
	v_max3_f32 v128, v129, v54, v53
	v_sub_f32_e32 v32, v32, v128
	v_exp_f32_e32 v32, v32
	v_sub_f32_e32 v33, v33, v128
	v_exp_f32_e32 v33, v33
	v_sub_f32_e32 v34, v34, v128
	v_exp_f32_e32 v34, v34
	v_sub_f32_e32 v35, v35, v128
	v_exp_f32_e32 v35, v35
	v_sub_f32_e32 v36, v36, v128
	v_sub_f32_e32 v53, v129, v128
	v_exp_f32_e32 v36, v36
	v_sub_f32_e32 v37, v37, v128
	v_exp_f32_e32 v54, v53
	v_add_f32_e32 v53, 0, v32
	v_exp_f32_e32 v37, v37
	v_add_f32_e32 v53, v33, v53
	v_add_f32_e32 v53, v34, v53
	v_cvt_pk_bf16_f32 v49, v51, v55
	v_add_f32_e32 v53, v35, v53
	v_cndmask_b32_e64 v55, v36, 0, s[46:47]
	v_add_f32_e32 v36, v55, v53
	v_cndmask_b32_e64 v53, v37, 0, s[48:49]
	v_sub_f32_e32 v37, v38, v128
	v_exp_f32_e32 v37, v37
	v_cvt_pk_bf16_f32 v48, v48, v50
	v_cvt_pk_bf16_f32 v50, v72, v73
	v_add_f32_e32 v36, v53, v36
	v_cndmask_b32_e64 v72, v37, 0, s[50:51]
	v_sub_f32_e32 v37, v39, v128
	v_exp_f32_e32 v37, v37
	v_cvt_pk_bf16_f32 v51, v74, v75
	v_add_f32_e32 v36, v72, v36
	v_pk_mul_f32 v[18:19], v[18:19], v[52:53] op_sel_hi:[1,0]
	v_cndmask_b32_e64 v39, v37, 0, s[52:53]
	v_pk_mul_f32 v[16:17], v[16:17], v[52:53] op_sel_hi:[1,0]
	v_add_f32_e32 v129, v39, v36
	v_cvt_pk_bf16_f32 v36, v32, v33
	v_cvt_pk_bf16_f32 v37, v34, v35
	v_cvt_pk_bf16_f32 v38, v55, v53
	v_cvt_pk_bf16_f32 v39, v72, v39
	s_waitcnt lgkmcnt(10)
	v_mfma_f32_16x16x32_bf16 v[32:35], v[134:137], v[48:51], v[16:19]
	v_fmac_f32_e32 v129, v130, v54
	s_nop 1
	v_pk_mul_f32 v[18:19], v[22:23], v[54:55] op_sel_hi:[1,0]
	v_pk_mul_f32 v[16:17], v[20:21], v[54:55] op_sel_hi:[1,0]
	s_nop 1
	v_mfma_f32_16x16x32_bf16 v[96:99], v[134:137], v[36:39], v[16:19]
	s_nop 2
	v_mul_f32_e64 v18, v106, v52
	v_mul_f32_e64 v19, v107, v52
	v_pk_mul_f32 v[16:17], v[104:105], v[52:53] op_sel_hi:[1,0]
	s_waitcnt lgkmcnt(8)
	s_nop 0
	v_mfma_f32_16x16x32_bf16 v[104:107], v[138:141], v[48:51], v[16:19]
	s_nop 2
	v_mul_f32_e64 v18, v110, v54
	v_mul_f32_e64 v19, v111, v54
	v_pk_mul_f32 v[16:17], v[108:109], v[54:55] op_sel_hi:[1,0]
	s_nop 1
	v_mfma_f32_16x16x32_bf16 v[108:111], v[138:141], v[36:39], v[16:19]
	s_nop 2
	v_mul_f32_e64 v18, v114, v52
	v_mul_f32_e64 v19, v115, v52
	v_pk_mul_f32 v[16:17], v[112:113], v[52:53] op_sel_hi:[1,0]
	s_waitcnt lgkmcnt(6)
	s_nop 0
	v_mfma_f32_16x16x32_bf16 v[112:115], v[176:179], v[48:51], v[16:19]
	s_nop 2
	v_mul_f32_e64 v18, v118, v54
	v_mul_f32_e64 v19, v119, v54
	v_pk_mul_f32 v[16:17], v[116:117], v[54:55] op_sel_hi:[1,0]
	s_nop 1
	v_mfma_f32_16x16x32_bf16 v[116:119], v[176:179], v[36:39], v[16:19]
	s_nop 2
	v_mul_f32_e64 v18, v122, v52
	v_mul_f32_e64 v19, v123, v52
	v_pk_mul_f32 v[16:17], v[120:121], v[52:53] op_sel_hi:[1,0]
	s_waitcnt lgkmcnt(4)
	s_nop 0
	v_mfma_f32_16x16x32_bf16 v[120:123], v[188:191], v[48:51], v[16:19]
	v_or_b32_e32 v48, 0x90, v166
	v_add_u32_e32 v48, s76, v48
	s_nop 0
	v_pk_mul_f32 v[18:19], v[126:127], v[54:55] op_sel_hi:[1,0]
	v_pk_mul_f32 v[16:17], v[124:125], v[54:55] op_sel_hi:[1,0]
	s_nop 1
	v_mfma_f32_16x16x32_bf16 v[124:127], v[188:191], v[36:39], v[16:19]
	s_nop 2
	v_add_u32_e32 v16, 0x80, v149
	v_med3_i32 v16, v16, 0, s75
	v_lshl_add_u32 v16, v16, 9, v152
	global_load_dwordx4 v[36:39], v16, s[98:99]
	v_add_u32_e32 v16, 0x80, v150
	v_med3_i32 v16, v16, 0, s75
	v_lshl_add_u32 v16, v16, 9, v152
	global_load_dwordx4 v[72:75], v16, s[98:99]
	v_add_u32_e32 v16, 0x80, v151
	v_med3_i32 v16, v16, 0, s75
	v_lshl_add_u32 v16, v16, 9, v152
	global_load_dwordx4 v[80:83], v16, s[98:99]
	v_add_u32_e32 v16, 0x80, v252
	v_med3_i32 v16, v16, 0, s75
	v_lshl_add_u32 v16, v16, 9, v152
	global_load_dwordx4 v[88:91], v16, s[98:99]
	v_or_b32_e32 v16, 0x80, v166
	v_add_u32_e32 v16, s76, v16
	v_med3_i32 v16, v16, 0, s75
	v_med3_i32 v48, v48, 0, s75
	v_lshl_add_u32 v20, v16, 9, v158
	v_lshl_add_u32 v52, v48, 9, v158
	global_load_dwordx4 v[16:19], v20, s[100:101]
	s_nop 0
	global_load_dwordx4 v[20:23], v20, s[100:101] offset:64
	s_nop 0
	global_load_dwordx4 v[48:51], v52, s[100:101]
	s_nop 0
	global_load_dwordx4 v[52:55], v52, s[100:101] offset:64
	ds_read_b64_tr_b16 v[136:137], v169 offset:2304
	ds_read_b64_tr_b16 v[134:135], v169
	ds_read_b64_tr_b16 v[138:139], v169 offset:32
	ds_read_b64_tr_b16 v[140:141], v169 offset:2336
	ds_read_b64_tr_b16 v[188:189], v169 offset:64
	ds_read_b64_tr_b16 v[190:191], v169 offset:2368
	ds_read_b64_tr_b16 v[200:201], v169 offset:96
	ds_read_b64_tr_b16 v[202:203], v169 offset:2400
	s_waitcnt vmcnt(15)
	ds_write_b128 v241, v[76:79] offset:4608
	s_waitcnt vmcnt(14)
	ds_write_b128 v242, v[84:87] offset:4608
	s_waitcnt vmcnt(13)
	ds_write_b128 v243, v[92:95] offset:4608
	s_waitcnt vmcnt(12)
	ds_write_b128 v244, v[100:103] offset:4608
	v_mfma_f32_16x16x32_bf16 v[76:79], v[40:43], v[4:7], 0
	v_mfma_f32_16x16x32_bf16 v[40:43], v[40:43], v[12:15], 0
	v_mfma_f32_16x16x32_bf16 v[76:79], v[44:47], v[8:11], v[76:79]
	v_mfma_f32_16x16x32_bf16 v[84:87], v[56:59], v[4:7], 0
	v_mfma_f32_16x16x32_bf16 v[40:43], v[44:47], v[0:3], v[40:43]
	v_mfma_f32_16x16x32_bf16 v[44:47], v[56:59], v[12:15], 0
	v_sub_u32_e32 v56, v198, v147
	v_add_u32_e32 v59, 1, v56
	s_nop 2
	v_cmp_gt_u32_e64 s[0:1], v59, v146
	v_cmp_gt_u32_e32 vcc, v56, v146
	s_nop 0
	v_cndmask_b32_e64 v77, v77, v246, s[0:1]
	s_nop 0
	v_cndmask_b32_e32 v76, v76, v246, vcc
	v_max_f32_e32 v58, 0xf149f2ca, v76
	v_mfma_f32_16x16x32_bf16 v[84:87], v[60:63], v[8:11], v[84:87]
	v_max_f32_e32 v58, v58, v77
	v_add_u32_e32 v59, 2, v56
	v_cmp_gt_u32_e64 s[22:23], v59, v146
	v_mfma_f32_16x16x32_bf16 v[44:47], v[60:63], v[0:3], v[44:47]
	v_add_u32_e32 v60, 3, v56
	v_cmp_gt_u32_e64 s[24:25], v60, v146
	v_cndmask_b32_e64 v78, v78, v246, s[22:23]
	v_sub_u32_e32 v57, v198, v148
	v_cndmask_b32_e64 v79, v79, v246, s[24:25]
	v_max3_f32 v58, v58, v78, v79
	v_add_u32_e32 v59, 16, v56
	v_add_u32_e32 v60, 17, v56
	v_cmp_gt_u32_e64 s[26:27], v59, v146
	v_cmp_gt_u32_e64 s[28:29], v60, v146
	v_cmp_gt_u32_e64 s[38:39], v57, v145
	v_cndmask_b32_e64 v84, v84, v246, s[26:27]
	v_cndmask_b32_e64 v85, v85, v246, s[28:29]
	v_max3_f32 v58, v58, v84, v85
	v_add_u32_e32 v59, 18, v56
	v_add_u32_e32 v56, 19, v56
	v_cmp_gt_u32_e64 s[30:31], v59, v146
	v_cmp_gt_u32_e64 s[34:35], v56, v146
	v_add_u32_e32 v60, 3, v57
	v_cndmask_b32_e64 v86, v86, v246, s[30:31]
	v_cndmask_b32_e64 v87, v87, v246, s[34:35]
	v_max3_f32 v56, v58, v86, v87
	v_add_u32_e32 v59, 1, v57
	v_cmp_gt_u32_e64 s[40:41], v59, v145
	v_cndmask_b32_e64 v40, v40, v246, s[38:39]
	v_max_f32_e32 v58, 0xf149f2ca, v40
	v_cndmask_b32_e64 v41, v41, v246, s[40:41]
	v_max_f32_e32 v58, v58, v41
	v_add_u32_e32 v59, 2, v57
	v_cmp_gt_u32_e64 s[42:43], v59, v145
	v_cmp_gt_u32_e64 s[44:45], v60, v145
	s_nop 0
	v_cndmask_b32_e64 v42, v42, v246, s[42:43]
	v_cndmask_b32_e64 v43, v43, v246, s[44:45]
	v_max3_f32 v58, v58, v42, v43
	v_add_u32_e32 v59, 16, v57
	v_add_u32_e32 v60, 17, v57
	v_cmp_gt_u32_e64 s[46:47], v59, v145
	v_cmp_gt_u32_e64 s[48:49], v60, v145
	s_nop 0
	v_cndmask_b32_e64 v44, v44, v246, s[46:47]
	v_cndmask_b32_e64 v45, v45, v246, s[48:49]
	v_max3_f32 v58, v58, v44, v45
	v_add_u32_e32 v59, 18, v57
	v_add_u32_e32 v57, 19, v57
	v_cmp_gt_u32_e64 s[50:51], v59, v145
	v_cmp_gt_u32_e64 s[52:53], v57, v145
	s_nop 0
	v_cndmask_b32_e64 v46, v46, v246, s[50:51]
	v_cndmask_b32_e64 v47, v47, v246, s[52:53]
	v_max3_f32 v57, v58, v46, v47
	v_mov_b32_e32 v58, v56
	v_mov_b32_e32 v59, v56
	s_nop 1
	v_permlane32_swap_b32_e32 v58, v59
	v_max3_f32 v56, v56, v58, v59
	v_mov_b32_e32 v58, v57
	v_mov_b32_e32 v59, v57
	s_nop 1
	v_permlane32_swap_b32_e32 v58, v59
	v_max3_f32 v57, v57, v58, v59
	v_mov_b32_e32 v58, v56
	v_mov_b32_e32 v59, v56
	s_nop 1
	v_permlane16_swap_b32_e32 v58, v59
	v_max_f32_e32 v56, v56, v58
	v_mov_b32_e32 v58, v57
	v_mov_b32_e32 v61, v57
	s_nop 1
	v_permlane16_swap_b32_e32 v58, v61
	v_max_f32_e32 v62, v57, v58
	v_max3_f32 v175, v131, v56, v59
	v_sub_f32_e32 v56, v131, v175
	v_max3_f32 v177, v128, v62, v61
	v_exp_f32_e32 v60, v56
	v_sub_f32_e32 v56, v76, v175
	v_sub_f32_e32 v40, v40, v177
	v_exp_f32_e32 v56, v56
	v_sub_f32_e32 v58, v77, v175
	v_exp_f32_e32 v40, v40
	v_sub_f32_e32 v41, v41, v177
	v_exp_f32_e32 v58, v58
	v_sub_f32_e32 v59, v78, v175
	v_exp_f32_e32 v41, v41
	v_sub_f32_e32 v42, v42, v177
	v_exp_f32_e32 v59, v59
	v_sub_f32_e32 v63, v79, v175
	v_exp_f32_e32 v42, v42
	v_sub_f32_e32 v43, v43, v177
	v_exp_f32_e32 v63, v63
	v_sub_f32_e32 v76, v84, v175
	v_exp_f32_e32 v43, v43
	v_sub_f32_e32 v44, v44, v177
	v_exp_f32_e32 v76, v76
	v_sub_f32_e32 v77, v85, v175
	v_sub_f32_e32 v61, v128, v177
	v_exp_f32_e32 v44, v44
	v_sub_f32_e32 v45, v45, v177
	v_add_f32_e32 v57, 0, v56
	v_exp_f32_e32 v77, v77
	v_sub_f32_e32 v78, v86, v175
	v_exp_f32_e32 v62, v61
	v_add_f32_e32 v61, 0, v40
	v_exp_f32_e32 v45, v45
	v_sub_f32_e32 v46, v46, v177
	v_add_f32_e32 v57, v58, v57
	v_exp_f32_e32 v78, v78
	v_sub_f32_e32 v79, v87, v175
	v_add_f32_e32 v61, v41, v61
	v_exp_f32_e32 v46, v46
	v_add_f32_e32 v57, v59, v57
	v_exp_f32_e32 v79, v79
	v_add_f32_e32 v61, v42, v61
	v_sub_f32_e32 v47, v47, v177
	v_add_f32_e32 v57, v63, v57
	v_add_f32_e32 v61, v43, v61
	v_exp_f32_e32 v47, v47
	v_add_f32_e32 v57, v76, v57
	v_add_f32_e32 v61, v44, v61
	v_add_f32_e32 v57, v77, v57
	v_add_f32_e32 v61, v45, v61
	v_add_f32_e32 v57, v78, v57
	v_add_f32_e32 v61, v46, v61
	v_add_f32_e32 v176, v79, v57
	v_cvt_pk_bf16_f32 v56, v56, v58
	v_cvt_pk_bf16_f32 v57, v59, v63
	v_cvt_pk_bf16_f32 v58, v76, v77
	v_cvt_pk_bf16_f32 v59, v78, v79
	v_pk_mul_f32 v[34:35], v[34:35], v[60:61] op_sel_hi:[1,0]
	v_pk_mul_f32 v[32:33], v[32:33], v[60:61] op_sel_hi:[1,0]
	v_add_f32_e32 v178, v47, v61
	v_cvt_pk_bf16_f32 v40, v40, v41
	v_cvt_pk_bf16_f32 v41, v42, v43
	v_cvt_pk_bf16_f32 v42, v44, v45
	v_cvt_pk_bf16_f32 v43, v46, v47
	s_waitcnt lgkmcnt(10)
	v_mfma_f32_16x16x32_bf16 v[44:47], v[134:137], v[56:59], v[32:35]
	v_fmac_f32_e32 v176, v132, v60
	v_fmac_f32_e32 v178, v129, v62
	s_nop 0
	v_pk_mul_f32 v[34:35], v[98:99], v[62:63] op_sel_hi:[1,0]
	v_pk_mul_f32 v[32:33], v[96:97], v[62:63] op_sel_hi:[1,0]
	s_nop 1
	v_mfma_f32_16x16x32_bf16 v[100:103], v[134:137], v[40:43], v[32:35]
	s_nop 2
	v_mul_f32_e64 v34, v106, v60
	v_mul_f32_e64 v35, v107, v60
	v_pk_mul_f32 v[32:33], v[104:105], v[60:61] op_sel_hi:[1,0]
	s_waitcnt lgkmcnt(8)
	s_nop 0
	v_mfma_f32_16x16x32_bf16 v[104:107], v[138:141], v[56:59], v[32:35]
	s_nop 2
	v_mul_f32_e64 v34, v110, v62
	v_mul_f32_e64 v35, v111, v62
	v_pk_mul_f32 v[32:33], v[108:109], v[62:63] op_sel_hi:[1,0]
	s_nop 1
	v_mfma_f32_16x16x32_bf16 v[108:111], v[138:141], v[40:43], v[32:35]
	s_nop 2
	v_mul_f32_e64 v34, v114, v60
	v_mul_f32_e64 v35, v115, v60
	v_pk_mul_f32 v[32:33], v[112:113], v[60:61] op_sel_hi:[1,0]
	s_waitcnt lgkmcnt(6)
	s_nop 0
	v_mfma_f32_16x16x32_bf16 v[112:115], v[188:191], v[56:59], v[32:35]
	s_nop 2
	v_mul_f32_e64 v34, v118, v62
	v_mul_f32_e64 v35, v119, v62
	v_pk_mul_f32 v[32:33], v[116:117], v[62:63] op_sel_hi:[1,0]
	s_nop 1
	v_mfma_f32_16x16x32_bf16 v[116:119], v[188:191], v[40:43], v[32:35]
	v_add_u32_e32 v188, s76, v207
	s_nop 1
	v_pk_mul_f32 v[34:35], v[122:123], v[60:61] op_sel_hi:[1,0]
	v_pk_mul_f32 v[32:33], v[120:121], v[60:61] op_sel_hi:[1,0]
	s_waitcnt lgkmcnt(4)
	s_nop 0
	v_mfma_f32_16x16x32_bf16 v[120:123], v[200:203], v[56:59], v[32:35]
	v_or_b32_e32 v56, 0xb0, v166
	v_add_u32_e32 v56, s76, v56
	s_nop 0
	v_pk_mul_f32 v[34:35], v[126:127], v[62:63] op_sel_hi:[1,0]
	v_pk_mul_f32 v[32:33], v[124:125], v[62:63] op_sel_hi:[1,0]
	s_nop 1
	v_mfma_f32_16x16x32_bf16 v[124:127], v[200:203], v[40:43], v[32:35]
	s_nop 2
	v_add_u32_e32 v32, 0xa0, v149
	v_med3_i32 v32, v32, 0, s75
	v_lshl_add_u32 v32, v32, 9, v152
	global_load_dwordx4 v[76:79], v32, s[98:99]
	v_add_u32_e32 v32, 0xa0, v150
	v_med3_i32 v32, v32, 0, s75
	v_lshl_add_u32 v32, v32, 9, v152
	global_load_dwordx4 v[84:87], v32, s[98:99]
	v_add_u32_e32 v32, 0xa0, v151
	v_med3_i32 v32, v32, 0, s75
	v_lshl_add_u32 v32, v32, 9, v152
	global_load_dwordx4 v[92:95], v32, s[98:99]
	v_add_u32_e32 v32, 0xa0, v252
	v_med3_i32 v32, v32, 0, s75
	v_lshl_add_u32 v32, v32, 9, v152
	global_load_dwordx4 v[96:99], v32, s[98:99]
	v_or_b32_e32 v32, 0xa0, v166
	v_add_u32_e32 v32, s76, v32
	v_med3_i32 v32, v32, 0, s75
	v_med3_i32 v56, v56, 0, s75
	v_lshl_add_u32 v40, v32, 9, v158
	v_lshl_add_u32 v60, v56, 9, v158
	global_load_dwordx4 v[32:35], v40, s[100:101]
	s_nop 0
	global_load_dwordx4 v[40:43], v40, s[100:101] offset:64
	s_nop 0
	global_load_dwordx4 v[56:59], v60, s[100:101]
	s_nop 0
	global_load_dwordx4 v[60:63], v60, s[100:101] offset:64
	ds_read_b64_tr_b16 v[142:143], v169 offset:6912
	ds_read_b64_tr_b16 v[140:141], v169 offset:4608
	ds_read_b64_tr_b16 v[136:137], v169 offset:4640
	ds_read_b64_tr_b16 v[138:139], v169 offset:6944
	ds_read_b64_tr_b16 v[132:133], v169 offset:4672
	ds_read_b64_tr_b16 v[134:135], v169 offset:6976
	ds_read_b64_tr_b16 v[128:129], v169 offset:4704
	ds_read_b64_tr_b16 v[130:131], v169 offset:7008
	s_waitcnt vmcnt(15)
	ds_write_b128 v241, v[36:39]
	s_waitcnt vmcnt(14)
	ds_write_b128 v242, v[72:75]
	s_waitcnt vmcnt(13)
	ds_write_b128 v243, v[80:83]
	s_waitcnt vmcnt(12)
	ds_write_b128 v244, v[88:91]
	v_mfma_f32_16x16x32_bf16 v[36:39], v[24:27], v[4:7], 0
	v_mfma_f32_16x16x32_bf16 v[24:27], v[24:27], v[12:15], 0
	v_mfma_f32_16x16x32_bf16 v[36:39], v[28:31], v[8:11], v[36:39]
	v_mfma_f32_16x16x32_bf16 v[72:75], v[64:67], v[4:7], 0
	v_mfma_f32_16x16x32_bf16 v[24:27], v[28:31], v[0:3], v[24:27]
	v_mfma_f32_16x16x32_bf16 v[28:31], v[64:67], v[12:15], 0
	v_sub_u32_e32 v64, v199, v147
	v_add_u32_e32 v67, 1, v64
	s_nop 2
	v_cmp_gt_u32_e64 s[0:1], v67, v146
	v_cmp_gt_u32_e32 vcc, v64, v146
	s_nop 0
	v_cndmask_b32_e64 v37, v37, v246, s[0:1]
	s_nop 0
	v_cndmask_b32_e32 v36, v36, v246, vcc
	v_max_f32_e32 v66, 0xf149f2ca, v36
	v_mfma_f32_16x16x32_bf16 v[72:75], v[68:71], v[8:11], v[72:75]
	v_max_f32_e32 v66, v66, v37
	v_add_u32_e32 v67, 2, v64
	v_cmp_gt_u32_e64 s[22:23], v67, v146
	v_mfma_f32_16x16x32_bf16 v[28:31], v[68:71], v[0:3], v[28:31]
	v_add_u32_e32 v68, 3, v64
	v_cmp_gt_u32_e64 s[24:25], v68, v146
	v_cndmask_b32_e64 v38, v38, v246, s[22:23]
	v_sub_u32_e32 v65, v199, v148
	v_cndmask_b32_e64 v39, v39, v246, s[24:25]
	v_max3_f32 v66, v66, v38, v39
	v_add_u32_e32 v67, 16, v64
	v_add_u32_e32 v68, 17, v64
	v_cmp_gt_u32_e64 s[26:27], v67, v146
	v_cmp_gt_u32_e64 s[28:29], v68, v146
	v_cmp_gt_u32_e64 s[38:39], v65, v145
	v_cndmask_b32_e64 v72, v72, v246, s[26:27]
	v_cndmask_b32_e64 v73, v73, v246, s[28:29]
	v_max3_f32 v66, v66, v72, v73
	v_add_u32_e32 v67, 18, v64
	v_add_u32_e32 v64, 19, v64
	v_cmp_gt_u32_e64 s[30:31], v67, v146
	v_cmp_gt_u32_e64 s[34:35], v64, v146
	v_add_u32_e32 v68, 3, v65
	v_cndmask_b32_e64 v74, v74, v246, s[30:31]
	v_cndmask_b32_e64 v75, v75, v246, s[34:35]
	v_max3_f32 v64, v66, v74, v75
	v_add_u32_e32 v67, 1, v65
	v_cmp_gt_u32_e64 s[40:41], v67, v145
	v_cndmask_b32_e64 v24, v24, v246, s[38:39]
	v_max_f32_e32 v66, 0xf149f2ca, v24
	v_cndmask_b32_e64 v25, v25, v246, s[40:41]
	v_max_f32_e32 v66, v66, v25
	v_add_u32_e32 v67, 2, v65
	v_cmp_gt_u32_e64 s[42:43], v67, v145
	v_cmp_gt_u32_e64 s[44:45], v68, v145
	s_nop 0
	v_cndmask_b32_e64 v26, v26, v246, s[42:43]
	v_cndmask_b32_e64 v27, v27, v246, s[44:45]
	v_max3_f32 v66, v66, v26, v27
	v_add_u32_e32 v67, 16, v65
	v_add_u32_e32 v68, 17, v65
	v_cmp_gt_u32_e64 s[46:47], v67, v145
	v_cmp_gt_u32_e64 s[48:49], v68, v145
	s_nop 0
	v_cndmask_b32_e64 v28, v28, v246, s[46:47]
	v_cndmask_b32_e64 v29, v29, v246, s[48:49]
	v_max3_f32 v66, v66, v28, v29
	v_add_u32_e32 v67, 18, v65
	v_add_u32_e32 v65, 19, v65
	v_cmp_gt_u32_e64 s[50:51], v67, v145
	v_cmp_gt_u32_e64 s[52:53], v65, v145
	s_nop 0
	v_cndmask_b32_e64 v30, v30, v246, s[50:51]
	v_cndmask_b32_e64 v31, v31, v246, s[52:53]
	v_max3_f32 v65, v66, v30, v31
	v_mov_b32_e32 v66, v64
	v_mov_b32_e32 v67, v64
	s_nop 1
	v_permlane32_swap_b32_e32 v66, v67
	v_max3_f32 v64, v64, v66, v67
	v_mov_b32_e32 v66, v65
	v_mov_b32_e32 v67, v65
	s_nop 1
	v_permlane32_swap_b32_e32 v66, v67
	v_max3_f32 v65, v65, v66, v67
	v_mov_b32_e32 v66, v64
	v_mov_b32_e32 v67, v64
	s_nop 1
	v_permlane16_swap_b32_e32 v66, v67
	v_max_f32_e32 v64, v64, v66
	v_max3_f32 v179, v175, v64, v67
	v_sub_f32_e32 v36, v36, v179
	v_exp_f32_e32 v36, v36
	v_sub_f32_e32 v37, v37, v179
	v_mov_b32_e32 v66, v65
	v_mov_b32_e32 v68, v65
	v_exp_f32_e32 v37, v37
	v_sub_f32_e32 v38, v38, v179
	v_permlane16_swap_b32_e32 v66, v68
	v_exp_f32_e32 v38, v38
	v_sub_f32_e32 v39, v39, v179
	v_exp_f32_e32 v39, v39
	v_sub_f32_e32 v67, v72, v179
	v_max_f32_e32 v65, v65, v66
	v_exp_f32_e32 v67, v67
	v_sub_f32_e32 v69, v73, v179
	v_add_f32_e32 v66, 0, v36
	v_exp_f32_e32 v69, v69
	v_sub_f32_e32 v70, v74, v179
	v_max3_f32 v181, v177, v65, v68
	v_add_f32_e32 v66, v37, v66
	v_exp_f32_e32 v70, v70
	v_sub_f32_e32 v71, v75, v179
	v_sub_f32_e32 v24, v24, v181
	v_add_f32_e32 v66, v38, v66
	v_exp_f32_e32 v71, v71
	v_exp_f32_e32 v24, v24
	v_sub_f32_e32 v25, v25, v181
	v_add_f32_e32 v66, v39, v66
	v_exp_f32_e32 v25, v25
	v_sub_f32_e32 v26, v26, v181
	v_add_f32_e32 v66, v67, v66
	v_exp_f32_e32 v26, v26
	v_sub_f32_e32 v27, v27, v181
	v_add_f32_e32 v66, v69, v66
	v_exp_f32_e32 v27, v27
	v_sub_f32_e32 v28, v28, v181
	v_add_f32_e32 v66, v70, v66
	v_sub_f32_e32 v65, v177, v181
	v_exp_f32_e32 v28, v28
	v_sub_f32_e32 v29, v29, v181
	v_add_f32_e32 v180, v71, v66
	v_exp_f32_e32 v66, v65
	v_add_f32_e32 v65, 0, v24
	v_exp_f32_e32 v29, v29
	v_sub_f32_e32 v30, v30, v181
	v_add_f32_e32 v65, v25, v65
	v_exp_f32_e32 v30, v30
	v_sub_f32_e32 v31, v31, v181
	v_sub_f32_e32 v64, v175, v179
	v_add_f32_e32 v65, v26, v65
	v_exp_f32_e32 v31, v31
	v_exp_f32_e32 v64, v64
	v_add_f32_e32 v65, v27, v65
	v_add_f32_e32 v65, v28, v65
	v_add_f32_e32 v65, v29, v65
	v_add_f32_e32 v65, v30, v65
	v_cvt_pk_bf16_f32 v36, v36, v37
	v_cvt_pk_bf16_f32 v37, v38, v39
	v_cvt_pk_bf16_f32 v38, v67, v69
	v_cvt_pk_bf16_f32 v39, v70, v71
	v_add_f32_e32 v183, v31, v65
	v_cvt_pk_bf16_f32 v24, v24, v25
	v_cvt_pk_bf16_f32 v25, v26, v27
	v_cvt_pk_bf16_f32 v26, v28, v29
	v_cvt_pk_bf16_f32 v27, v30, v31
	v_pk_mul_f32 v[30:31], v[46:47], v[64:65] op_sel_hi:[1,0]
	v_pk_mul_f32 v[28:29], v[44:45], v[64:65] op_sel_hi:[1,0]
	v_fmac_f32_e32 v180, v176, v64
	v_fmac_f32_e32 v183, v178, v66
	s_waitcnt lgkmcnt(10)
	v_mfma_f32_16x16x32_bf16 v[68:71], v[140:143], v[36:39], v[28:31]
	s_nop 2
	v_mul_f32_e64 v30, v102, v66
	v_mul_f32_e64 v31, v103, v66
	v_pk_mul_f32 v[28:29], v[100:101], v[66:67] op_sel_hi:[1,0]
	s_nop 1
	v_mfma_f32_16x16x32_bf16 v[72:75], v[140:143], v[24:27], v[28:31]
	s_nop 2
	v_mul_f32_e64 v30, v106, v64
	v_mul_f32_e64 v31, v107, v64
	v_pk_mul_f32 v[28:29], v[104:105], v[64:65] op_sel_hi:[1,0]
	s_waitcnt lgkmcnt(8)
	s_nop 0
	v_mfma_f32_16x16x32_bf16 v[80:83], v[136:139], v[36:39], v[28:31]
	s_nop 2
	v_mul_f32_e64 v30, v110, v66
	v_mul_f32_e64 v31, v111, v66
	v_pk_mul_f32 v[28:29], v[108:109], v[66:67] op_sel_hi:[1,0]
	s_nop 1
	v_mfma_f32_16x16x32_bf16 v[108:111], v[136:139], v[24:27], v[28:31]
	s_nop 2
	v_mul_f32_e64 v30, v114, v64
	v_mul_f32_e64 v31, v115, v64
	v_pk_mul_f32 v[28:29], v[112:113], v[64:65] op_sel_hi:[1,0]
	s_waitcnt lgkmcnt(6)
	s_nop 0
	v_mfma_f32_16x16x32_bf16 v[112:115], v[132:135], v[36:39], v[28:31]
	s_nop 2
	v_mul_f32_e64 v30, v118, v66
	v_mul_f32_e64 v31, v119, v66
	v_pk_mul_f32 v[28:29], v[116:117], v[66:67] op_sel_hi:[1,0]
	s_nop 1
	v_mfma_f32_16x16x32_bf16 v[116:119], v[132:135], v[24:27], v[28:31]
	s_nop 2
	v_mul_f32_e64 v30, v122, v64
	v_mul_f32_e64 v31, v123, v64
	v_pk_mul_f32 v[28:29], v[120:121], v[64:65] op_sel_hi:[1,0]
	s_waitcnt lgkmcnt(4)
	s_nop 0
	v_mfma_f32_16x16x32_bf16 v[120:123], v[128:131], v[36:39], v[28:31]
	s_nop 2
	v_mul_f32_e64 v30, v126, v66
	v_mul_f32_e64 v31, v127, v66
	v_pk_mul_f32 v[28:29], v[124:125], v[66:67] op_sel_hi:[1,0]
	s_nop 1
	v_mfma_f32_16x16x32_bf16 v[124:127], v[128:131], v[24:27], v[28:31]
	v_add_u32_e32 v24, 0xc0, v149
	v_med3_i32 v24, v24, 0, s75
	v_lshl_add_u32 v24, v24, 9, v152
	global_load_dwordx4 v[64:67], v24, s[98:99]
	v_add_u32_e32 v24, 0xc0, v150
	v_med3_i32 v24, v24, 0, s75
	v_lshl_add_u32 v24, v24, 9, v152
	global_load_dwordx4 v[88:91], v24, s[98:99]
	v_add_u32_e32 v24, 0xc0, v151
	v_med3_i32 v24, v24, 0, s75
	v_lshl_add_u32 v24, v24, 9, v152
	global_load_dwordx4 v[100:103], v24, s[98:99]
	v_add_u32_e32 v24, 0xc0, v252
	v_med3_i32 v24, v24, 0, s75
	v_lshl_add_u32 v24, v24, 9, v152
	global_load_dwordx4 v[104:107], v24, s[98:99]
	v_or_b32_e32 v24, 0xc0, v166
	v_add_u32_e32 v24, s76, v24
	v_med3_i32 v24, v24, 0, s75
	v_lshl_add_u32 v24, v24, 9, v158
	global_load_dwordx4 v[36:39], v24, s[100:101]
	global_load_dwordx4 v[44:47], v24, s[100:101] offset:64
	v_or_b32_e32 v24, 0xd0, v166
	v_add_u32_e32 v24, s76, v24
	v_med3_i32 v24, v24, 0, s75
	v_lshl_add_u32 v28, v24, 9, v158
	global_load_dwordx4 v[24:27], v28, s[100:101]
	s_nop 0
	global_load_dwordx4 v[28:31], v28, s[100:101] offset:64
	ds_read_b64_tr_b16 v[142:143], v169 offset:2304
	ds_read_b64_tr_b16 v[140:141], v169
	ds_read_b64_tr_b16 v[136:137], v169 offset:32
	ds_read_b64_tr_b16 v[138:139], v169 offset:2336
	ds_read_b64_tr_b16 v[132:133], v169 offset:64
	ds_read_b64_tr_b16 v[134:135], v169 offset:2368
	ds_read_b64_tr_b16 v[128:129], v169 offset:96
	ds_read_b64_tr_b16 v[130:131], v169 offset:2400
	s_waitcnt vmcnt(15)
	ds_write_b128 v241, v[76:79] offset:4608
	s_waitcnt vmcnt(14)
	ds_write_b128 v242, v[84:87] offset:4608
	s_waitcnt vmcnt(13)
	ds_write_b128 v243, v[92:95] offset:4608
	s_waitcnt vmcnt(12)
	ds_write_b128 v244, v[96:99] offset:4608
	v_mfma_f32_16x16x32_bf16 v[76:79], v[16:19], v[4:7], 0
	v_mfma_f32_16x16x32_bf16 v[16:19], v[16:19], v[12:15], 0
	v_mfma_f32_16x16x32_bf16 v[76:79], v[20:23], v[8:11], v[76:79]
	v_mfma_f32_16x16x32_bf16 v[84:87], v[48:51], v[4:7], 0
	v_mfma_f32_16x16x32_bf16 v[16:19], v[20:23], v[0:3], v[16:19]
	v_mfma_f32_16x16x32_bf16 v[20:23], v[48:51], v[12:15], 0
	v_add_u32_e32 v49, 0xc0, v154
	v_sub_u32_e32 v48, v49, v147
	v_add_u32_e32 v51, 1, v48
	s_nop 1
	v_cmp_gt_u32_e64 s[0:1], v51, v146
	v_cmp_gt_u32_e32 vcc, v48, v146
	s_nop 0
	v_cndmask_b32_e64 v77, v77, v246, s[0:1]
	s_nop 0
	v_cndmask_b32_e32 v76, v76, v246, vcc
	v_max_f32_e32 v50, 0xf149f2ca, v76
	v_mfma_f32_16x16x32_bf16 v[84:87], v[52:55], v[8:11], v[84:87]
	v_max_f32_e32 v50, v50, v77
	v_add_u32_e32 v51, 2, v48
	v_cmp_gt_u32_e64 s[22:23], v51, v146
	v_mfma_f32_16x16x32_bf16 v[20:23], v[52:55], v[0:3], v[20:23]
	v_add_u32_e32 v52, 3, v48
	v_cmp_gt_u32_e64 s[24:25], v52, v146
	v_cndmask_b32_e64 v78, v78, v246, s[22:23]
	v_sub_u32_e32 v49, v49, v148
	v_cndmask_b32_e64 v79, v79, v246, s[24:25]
	v_max3_f32 v50, v50, v78, v79
	v_add_u32_e32 v51, 16, v48
	v_add_u32_e32 v52, 17, v48
	v_cmp_gt_u32_e64 s[26:27], v51, v146
	v_cmp_gt_u32_e64 s[28:29], v52, v146
	v_cmp_gt_u32_e64 s[38:39], v49, v145
	v_cndmask_b32_e64 v84, v84, v246, s[26:27]
	v_cndmask_b32_e64 v85, v85, v246, s[28:29]
	v_max3_f32 v50, v50, v84, v85
	v_add_u32_e32 v51, 18, v48
	v_add_u32_e32 v48, 19, v48
	v_cmp_gt_u32_e64 s[30:31], v51, v146
	v_cmp_gt_u32_e64 s[34:35], v48, v146
	v_add_u32_e32 v52, 3, v49
	v_cndmask_b32_e64 v86, v86, v246, s[30:31]
	v_cndmask_b32_e64 v87, v87, v246, s[34:35]
	v_max3_f32 v48, v50, v86, v87
	v_add_u32_e32 v51, 1, v49
	v_cmp_gt_u32_e64 s[40:41], v51, v145
	v_cndmask_b32_e64 v16, v16, v246, s[38:39]
	v_max_f32_e32 v50, 0xf149f2ca, v16
	v_cndmask_b32_e64 v17, v17, v246, s[40:41]
	v_max_f32_e32 v50, v50, v17
	v_add_u32_e32 v51, 2, v49
	v_cmp_gt_u32_e64 s[42:43], v51, v145
	v_cmp_gt_u32_e64 s[44:45], v52, v145
	s_nop 0
	v_cndmask_b32_e64 v18, v18, v246, s[42:43]
	v_cndmask_b32_e64 v19, v19, v246, s[44:45]
	v_max3_f32 v50, v50, v18, v19
	v_add_u32_e32 v51, 16, v49
	v_add_u32_e32 v52, 17, v49
	v_cmp_gt_u32_e64 s[46:47], v51, v145
	v_cmp_gt_u32_e64 s[48:49], v52, v145
	s_nop 0
	v_cndmask_b32_e64 v20, v20, v246, s[46:47]
	v_cndmask_b32_e64 v21, v21, v246, s[48:49]
	v_max3_f32 v50, v50, v20, v21
	v_add_u32_e32 v51, 18, v49
	v_add_u32_e32 v49, 19, v49
	v_cmp_gt_u32_e64 s[50:51], v51, v145
	v_cmp_gt_u32_e64 s[52:53], v49, v145
	s_nop 0
	v_cndmask_b32_e64 v22, v22, v246, s[50:51]
	v_cndmask_b32_e64 v23, v23, v246, s[52:53]
	v_max3_f32 v49, v50, v22, v23
	v_mov_b32_e32 v50, v48
	v_mov_b32_e32 v51, v48
	s_nop 1
	v_permlane32_swap_b32_e32 v50, v51
	v_max3_f32 v48, v48, v50, v51
	v_mov_b32_e32 v50, v49
	v_mov_b32_e32 v51, v49
	s_nop 1
	v_permlane32_swap_b32_e32 v50, v51
	v_max3_f32 v49, v49, v50, v51
	v_mov_b32_e32 v50, v48
	v_mov_b32_e32 v51, v48
	s_nop 1
	v_permlane16_swap_b32_e32 v50, v51
	v_max_f32_e32 v48, v48, v50
	v_mov_b32_e32 v50, v49
	v_mov_b32_e32 v53, v49
	s_nop 1
	v_permlane16_swap_b32_e32 v50, v53
	v_max_f32_e32 v54, v49, v50
	v_max3_f32 v175, v179, v48, v51
	v_sub_f32_e32 v48, v179, v175
	v_max3_f32 v177, v181, v54, v53
	v_exp_f32_e32 v52, v48
	v_sub_f32_e32 v48, v76, v175
	v_sub_f32_e32 v16, v16, v177
	v_exp_f32_e32 v48, v48
	v_sub_f32_e32 v50, v77, v175
	v_exp_f32_e32 v16, v16
	v_sub_f32_e32 v17, v17, v177
	v_exp_f32_e32 v50, v50
	v_sub_f32_e32 v51, v78, v175
	v_exp_f32_e32 v17, v17
	v_sub_f32_e32 v18, v18, v177
	v_exp_f32_e32 v51, v51
	v_sub_f32_e32 v55, v79, v175
	v_exp_f32_e32 v18, v18
	v_sub_f32_e32 v19, v19, v177
	v_exp_f32_e32 v55, v55
	v_sub_f32_e32 v76, v84, v175
	v_exp_f32_e32 v19, v19
	v_sub_f32_e32 v20, v20, v177
	v_exp_f32_e32 v76, v76
	v_sub_f32_e32 v77, v85, v175
	v_sub_f32_e32 v53, v181, v177
	v_exp_f32_e32 v20, v20
	v_sub_f32_e32 v21, v21, v177
	v_add_f32_e32 v49, 0, v48
	v_exp_f32_e32 v77, v77
	v_sub_f32_e32 v78, v86, v175
	v_exp_f32_e32 v54, v53
	v_add_f32_e32 v53, 0, v16
	v_exp_f32_e32 v21, v21
	v_sub_f32_e32 v22, v22, v177
	v_add_f32_e32 v49, v50, v49
	v_exp_f32_e32 v78, v78
	v_sub_f32_e32 v79, v87, v175
	v_add_f32_e32 v53, v17, v53
	v_exp_f32_e32 v22, v22
	v_sub_f32_e32 v23, v23, v177
	v_add_f32_e32 v49, v51, v49
	v_exp_f32_e32 v79, v79
	v_add_f32_e32 v53, v18, v53
	v_exp_f32_e32 v23, v23
	v_add_f32_e32 v49, v55, v49
	v_add_f32_e32 v53, v19, v53
	v_add_f32_e32 v49, v76, v49
	v_add_f32_e32 v53, v20, v53
	v_add_f32_e32 v49, v77, v49
	v_add_f32_e32 v53, v21, v53
	v_add_f32_e32 v49, v78, v49
	v_add_f32_e32 v53, v22, v53
	v_add_f32_e32 v176, v79, v49
	v_cvt_pk_bf16_f32 v48, v48, v50
	v_cvt_pk_bf16_f32 v49, v51, v55
	v_cvt_pk_bf16_f32 v50, v76, v77
	v_cvt_pk_bf16_f32 v51, v78, v79
	v_add_f32_e32 v178, v23, v53
	v_cvt_pk_bf16_f32 v16, v16, v17
	v_cvt_pk_bf16_f32 v17, v18, v19
	v_cvt_pk_bf16_f32 v18, v20, v21
	v_cvt_pk_bf16_f32 v19, v22, v23
	v_pk_mul_f32 v[22:23], v[70:71], v[52:53] op_sel_hi:[1,0]
	v_pk_mul_f32 v[20:21], v[68:69], v[52:53] op_sel_hi:[1,0]
	v_fmac_f32_e32 v176, v180, v52
	v_fmac_f32_e32 v178, v183, v54
	s_waitcnt lgkmcnt(10)
	v_mfma_f32_16x16x32_bf16 v[76:79], v[140:143], v[48:51], v[20:23]
	v_add_u32_e32 v180, 0x100, v149
	v_add_u32_e32 v179, 0x100, v150
	s_nop 0
	v_pk_mul_f32 v[22:23], v[74:75], v[54:55] op_sel_hi:[1,0]
	v_pk_mul_f32 v[20:21], v[72:73], v[54:55] op_sel_hi:[1,0]
	s_nop 1
	v_mfma_f32_16x16x32_bf16 v[92:95], v[140:143], v[16:19], v[20:23]
	s_nop 2
	v_mul_f32_e64 v22, v82, v52
	v_mul_f32_e64 v23, v83, v52
	v_pk_mul_f32 v[20:21], v[80:81], v[52:53] op_sel_hi:[1,0]
	s_waitcnt lgkmcnt(8)
	s_nop 0
	v_mfma_f32_16x16x32_bf16 v[96:99], v[136:139], v[48:51], v[20:23]
	s_nop 2
	v_mul_f32_e64 v22, v110, v54
	v_mul_f32_e64 v23, v111, v54
	v_pk_mul_f32 v[20:21], v[108:109], v[54:55] op_sel_hi:[1,0]
	s_nop 1
	v_mfma_f32_16x16x32_bf16 v[108:111], v[136:139], v[16:19], v[20:23]
	s_nop 2
	v_mul_f32_e64 v22, v114, v52
	v_mul_f32_e64 v23, v115, v52
	v_pk_mul_f32 v[20:21], v[112:113], v[52:53] op_sel_hi:[1,0]
	s_waitcnt lgkmcnt(6)
	s_nop 0
	v_mfma_f32_16x16x32_bf16 v[112:115], v[132:135], v[48:51], v[20:23]
	s_nop 2
	v_mul_f32_e64 v22, v118, v54
	v_mul_f32_e64 v23, v119, v54
	v_pk_mul_f32 v[20:21], v[116:117], v[54:55] op_sel_hi:[1,0]
	s_nop 1
	v_mfma_f32_16x16x32_bf16 v[116:119], v[132:135], v[16:19], v[20:23]
	s_nop 2
	v_mul_f32_e64 v22, v122, v52
	v_mul_f32_e64 v23, v123, v52
	v_pk_mul_f32 v[20:21], v[120:121], v[52:53] op_sel_hi:[1,0]
	s_waitcnt lgkmcnt(4)
	s_nop 0
	v_mfma_f32_16x16x32_bf16 v[120:123], v[128:131], v[48:51], v[20:23]
	s_nop 2
	v_mul_f32_e64 v22, v126, v54
	v_mul_f32_e64 v23, v127, v54
	v_pk_mul_f32 v[20:21], v[124:125], v[54:55] op_sel_hi:[1,0]
	s_nop 1
	v_mfma_f32_16x16x32_bf16 v[124:127], v[128:131], v[16:19], v[20:23]
	v_add_u32_e32 v16, 0xe0, v149
	v_med3_i32 v16, v16, 0, s75
	v_lshl_add_u32 v16, v16, 9, v152
	global_load_dwordx4 v[68:71], v16, s[98:99]
	v_add_u32_e32 v16, 0xe0, v150
	v_med3_i32 v16, v16, 0, s75
	v_lshl_add_u32 v16, v16, 9, v152
	global_load_dwordx4 v[72:75], v16, s[98:99]
	v_add_u32_e32 v16, 0xe0, v151
	v_med3_i32 v16, v16, 0, s75
	v_lshl_add_u32 v16, v16, 9, v152
	global_load_dwordx4 v[80:83], v16, s[98:99]
	v_add_u32_e32 v16, 0xe0, v252
	v_med3_i32 v16, v16, 0, s75
	v_lshl_add_u32 v16, v16, 9, v152
	global_load_dwordx4 v[84:87], v16, s[98:99]
	v_or_b32_e32 v16, 0xe0, v166
	v_add_u32_e32 v16, s76, v16
	v_med3_i32 v16, v16, 0, s75
	v_lshl_add_u32 v16, v16, 9, v158
	global_load_dwordx4 v[48:51], v16, s[100:101]
	global_load_dwordx4 v[52:55], v16, s[100:101] offset:64
	v_or_b32_e32 v16, 0xf0, v166
	v_add_u32_e32 v16, s76, v16
	v_med3_i32 v16, v16, 0, s75
	v_lshl_add_u32 v20, v16, 9, v158
	global_load_dwordx4 v[16:19], v20, s[100:101]
	s_nop 0
	global_load_dwordx4 v[20:23], v20, s[100:101] offset:64
	ds_read_b64_tr_b16 v[142:143], v169 offset:6912
	ds_read_b64_tr_b16 v[140:141], v169 offset:4608
	ds_read_b64_tr_b16 v[136:137], v169 offset:4640
	ds_read_b64_tr_b16 v[138:139], v169 offset:6944
	ds_read_b64_tr_b16 v[132:133], v169 offset:4672
	ds_read_b64_tr_b16 v[134:135], v169 offset:6976
	ds_read_b64_tr_b16 v[128:129], v169 offset:4704
	ds_read_b64_tr_b16 v[130:131], v169 offset:7008
	s_waitcnt vmcnt(15)
	ds_write_b128 v241, v[64:67]
	s_waitcnt vmcnt(14)
	ds_write_b128 v242, v[88:91]
	s_waitcnt vmcnt(13)
	ds_write_b128 v243, v[100:103]
	s_waitcnt vmcnt(12)
	ds_write_b128 v244, v[104:107]
	v_mfma_f32_16x16x32_bf16 v[64:67], v[32:35], v[4:7], 0
	v_mfma_f32_16x16x32_bf16 v[32:35], v[32:35], v[12:15], 0
	v_mfma_f32_16x16x32_bf16 v[64:67], v[40:43], v[8:11], v[64:67]
	v_mfma_f32_16x16x32_bf16 v[88:91], v[56:59], v[4:7], 0
	v_mfma_f32_16x16x32_bf16 v[32:35], v[40:43], v[0:3], v[32:35]
	v_mfma_f32_16x16x32_bf16 v[40:43], v[56:59], v[12:15], 0
	v_add_u32_e32 v57, 0xe0, v154
	v_sub_u32_e32 v56, v57, v147
	v_add_u32_e32 v59, 1, v56
	s_nop 1
	v_cmp_gt_u32_e64 s[0:1], v59, v146
	v_cmp_gt_u32_e32 vcc, v56, v146
	s_nop 0
	v_cndmask_b32_e64 v65, v65, v246, s[0:1]
	s_nop 0
	v_cndmask_b32_e32 v64, v64, v246, vcc
	v_max_f32_e32 v58, 0xf149f2ca, v64
	v_mfma_f32_16x16x32_bf16 v[88:91], v[60:63], v[8:11], v[88:91]
	v_max_f32_e32 v58, v58, v65
	v_add_u32_e32 v59, 2, v56
	v_cmp_gt_u32_e64 s[22:23], v59, v146
	v_mfma_f32_16x16x32_bf16 v[40:43], v[60:63], v[0:3], v[40:43]
	v_add_u32_e32 v60, 3, v56
	v_cmp_gt_u32_e64 s[24:25], v60, v146
	v_cndmask_b32_e64 v66, v66, v246, s[22:23]
	v_sub_u32_e32 v57, v57, v148
	v_cndmask_b32_e64 v67, v67, v246, s[24:25]
	v_max3_f32 v58, v58, v66, v67
	v_add_u32_e32 v59, 16, v56
	v_add_u32_e32 v60, 17, v56
	v_cmp_gt_u32_e64 s[26:27], v59, v146
	v_cmp_gt_u32_e64 s[28:29], v60, v146
	v_cmp_gt_u32_e64 s[38:39], v57, v145
	v_cndmask_b32_e64 v88, v88, v246, s[26:27]
	v_cndmask_b32_e64 v89, v89, v246, s[28:29]
	v_max3_f32 v58, v58, v88, v89
	v_add_u32_e32 v59, 18, v56
	v_add_u32_e32 v56, 19, v56
	v_cmp_gt_u32_e64 s[30:31], v59, v146
	v_cmp_gt_u32_e64 s[34:35], v56, v146
	v_add_u32_e32 v60, 3, v57
	v_cndmask_b32_e64 v90, v90, v246, s[30:31]
	v_cndmask_b32_e64 v91, v91, v246, s[34:35]
	v_max3_f32 v56, v58, v90, v91
	v_add_u32_e32 v59, 1, v57
	v_cmp_gt_u32_e64 s[40:41], v59, v145
	v_cndmask_b32_e64 v32, v32, v246, s[38:39]
	v_max_f32_e32 v58, 0xf149f2ca, v32
	v_cndmask_b32_e64 v33, v33, v246, s[40:41]
	v_max_f32_e32 v58, v58, v33
	v_add_u32_e32 v59, 2, v57
	v_cmp_gt_u32_e64 s[42:43], v59, v145
	v_cmp_gt_u32_e64 s[44:45], v60, v145
	s_nop 0
	v_cndmask_b32_e64 v34, v34, v246, s[42:43]
	v_cndmask_b32_e64 v35, v35, v246, s[44:45]
	v_max3_f32 v58, v58, v34, v35
	v_add_u32_e32 v59, 16, v57
	v_add_u32_e32 v60, 17, v57
	v_cmp_gt_u32_e64 s[46:47], v59, v145
	v_cmp_gt_u32_e64 s[48:49], v60, v145
	s_nop 0
	v_cndmask_b32_e64 v40, v40, v246, s[46:47]
	v_cndmask_b32_e64 v41, v41, v246, s[48:49]
	v_max3_f32 v58, v58, v40, v41
	v_add_u32_e32 v59, 18, v57
	v_add_u32_e32 v57, 19, v57
	v_cmp_gt_u32_e64 s[50:51], v59, v145
	v_cmp_gt_u32_e64 s[52:53], v57, v145
	s_nop 0
	v_cndmask_b32_e64 v42, v42, v246, s[50:51]
	v_cndmask_b32_e64 v43, v43, v246, s[52:53]
	v_max3_f32 v57, v58, v42, v43
	v_mov_b32_e32 v58, v56
	v_mov_b32_e32 v59, v56
	s_nop 1
	v_permlane32_swap_b32_e32 v58, v59
	v_max3_f32 v56, v56, v58, v59
	v_mov_b32_e32 v58, v57
	v_mov_b32_e32 v59, v57
	s_nop 1
	v_permlane32_swap_b32_e32 v58, v59
	v_max3_f32 v57, v57, v58, v59
	v_mov_b32_e32 v58, v56
	v_mov_b32_e32 v59, v56
	s_nop 1
	v_permlane16_swap_b32_e32 v58, v59
	v_max_f32_e32 v56, v56, v58
	v_mov_b32_e32 v58, v57
	v_mov_b32_e32 v61, v57
	s_nop 1
	v_permlane16_swap_b32_e32 v58, v61
	v_max_f32_e32 v62, v57, v58
	v_max3_f32 v181, v175, v56, v59
	v_sub_f32_e32 v56, v175, v181
	v_max3_f32 v184, v177, v62, v61
	v_exp_f32_e32 v60, v56
	v_sub_f32_e32 v56, v64, v181
	v_sub_f32_e32 v32, v32, v184
	v_exp_f32_e32 v56, v56
	v_sub_f32_e32 v58, v65, v181
	v_exp_f32_e32 v32, v32
	v_sub_f32_e32 v33, v33, v184
	v_exp_f32_e32 v58, v58
	v_sub_f32_e32 v59, v66, v181
	v_exp_f32_e32 v33, v33
	v_sub_f32_e32 v34, v34, v184
	v_exp_f32_e32 v59, v59
	v_sub_f32_e32 v63, v67, v181
	v_exp_f32_e32 v34, v34
	v_sub_f32_e32 v35, v35, v184
	v_exp_f32_e32 v63, v63
	v_sub_f32_e32 v64, v88, v181
	v_exp_f32_e32 v35, v35
	v_sub_f32_e32 v40, v40, v184
	v_exp_f32_e32 v64, v64
	v_sub_f32_e32 v65, v89, v181
	v_sub_f32_e32 v61, v177, v184
	v_exp_f32_e32 v40, v40
	v_sub_f32_e32 v41, v41, v184
	v_add_f32_e32 v57, 0, v56
	v_exp_f32_e32 v65, v65
	v_sub_f32_e32 v66, v90, v181
	v_exp_f32_e32 v62, v61
	v_add_f32_e32 v61, 0, v32
	v_exp_f32_e32 v41, v41
	v_sub_f32_e32 v42, v42, v184
	v_add_f32_e32 v57, v58, v57
	v_exp_f32_e32 v66, v66
	v_sub_f32_e32 v67, v91, v181
	v_add_f32_e32 v61, v33, v61
	v_exp_f32_e32 v42, v42
	v_sub_f32_e32 v43, v43, v184
	v_add_f32_e32 v57, v59, v57
	v_exp_f32_e32 v67, v67
	v_add_f32_e32 v61, v34, v61
	v_exp_f32_e32 v43, v43
	v_add_f32_e32 v57, v63, v57
	v_add_f32_e32 v61, v35, v61
	v_add_f32_e32 v57, v64, v57
	v_add_f32_e32 v61, v40, v61
	v_add_f32_e32 v57, v65, v57
	v_add_f32_e32 v61, v41, v61
	v_add_f32_e32 v57, v66, v57
	v_add_f32_e32 v61, v42, v61
	v_add_f32_e32 v183, v67, v57
	v_cvt_pk_bf16_f32 v56, v56, v58
	v_cvt_pk_bf16_f32 v57, v59, v63
	v_cvt_pk_bf16_f32 v58, v64, v65
	v_cvt_pk_bf16_f32 v59, v66, v67
	v_add_f32_e32 v185, v43, v61
	v_cvt_pk_bf16_f32 v32, v32, v33
	v_cvt_pk_bf16_f32 v33, v34, v35
	v_cvt_pk_bf16_f32 v34, v40, v41
	v_cvt_pk_bf16_f32 v35, v42, v43
	v_pk_mul_f32 v[42:43], v[78:79], v[60:61] op_sel_hi:[1,0]
	v_pk_mul_f32 v[40:41], v[76:77], v[60:61] op_sel_hi:[1,0]
	v_fmac_f32_e32 v185, v178, v62
	s_waitcnt lgkmcnt(10)
	v_mfma_f32_16x16x32_bf16 v[100:103], v[140:143], v[56:59], v[40:43]
	v_add_u32_e32 v178, 0x100, v151
	v_fmac_f32_e32 v183, v176, v60
	v_add_u32_e32 v177, 0x100, v252
	v_pk_mul_f32 v[42:43], v[94:95], v[62:63] op_sel_hi:[1,0]
	v_pk_mul_f32 v[40:41], v[92:93], v[62:63] op_sel_hi:[1,0]
	s_nop 1
	v_mfma_f32_16x16x32_bf16 v[92:95], v[140:143], v[32:35], v[40:43]
	s_nop 2
	v_mul_f32_e64 v42, v98, v60
	v_mul_f32_e64 v43, v99, v60
	v_pk_mul_f32 v[40:41], v[96:97], v[60:61] op_sel_hi:[1,0]
	s_waitcnt lgkmcnt(8)
	s_nop 0
	v_mfma_f32_16x16x32_bf16 v[104:107], v[136:139], v[56:59], v[40:43]
	s_nop 2
	v_mul_f32_e64 v42, v110, v62
	v_mul_f32_e64 v43, v111, v62
	v_pk_mul_f32 v[40:41], v[108:109], v[62:63] op_sel_hi:[1,0]
	s_nop 1
	v_mfma_f32_16x16x32_bf16 v[108:111], v[136:139], v[32:35], v[40:43]
	s_nop 2
	v_mul_f32_e64 v42, v114, v60
	v_mul_f32_e64 v43, v115, v60
	v_pk_mul_f32 v[40:41], v[112:113], v[60:61] op_sel_hi:[1,0]
	s_waitcnt lgkmcnt(6)
	s_nop 0
	v_mfma_f32_16x16x32_bf16 v[112:115], v[132:135], v[56:59], v[40:43]
	s_nop 2
	v_mul_f32_e64 v42, v118, v62
	v_mul_f32_e64 v43, v119, v62
	v_pk_mul_f32 v[40:41], v[116:117], v[62:63] op_sel_hi:[1,0]
	s_nop 1
	v_mfma_f32_16x16x32_bf16 v[116:119], v[132:135], v[32:35], v[40:43]
	s_nop 2
	v_mul_f32_e64 v42, v122, v60
	v_mul_f32_e64 v43, v123, v60
	v_pk_mul_f32 v[40:41], v[120:121], v[60:61] op_sel_hi:[1,0]
	s_waitcnt lgkmcnt(4)
	s_nop 0
	v_mfma_f32_16x16x32_bf16 v[120:123], v[128:131], v[56:59], v[40:43]
	s_nop 2
	v_mul_f32_e64 v42, v126, v62
	v_mul_f32_e64 v43, v127, v62
	v_pk_mul_f32 v[40:41], v[124:125], v[62:63] op_sel_hi:[1,0]
	s_nop 1
	v_mfma_f32_16x16x32_bf16 v[124:127], v[128:131], v[32:35], v[40:43]
	v_med3_i32 v32, v180, 0, s75
	v_lshl_add_u32 v32, v32, 9, v152
	global_load_dwordx4 v[56:59], v32, s[98:99]
	v_med3_i32 v32, v179, 0, s75
	v_lshl_add_u32 v32, v32, 9, v152
	global_load_dwordx4 v[60:63], v32, s[98:99]
	v_med3_i32 v32, v178, 0, s75
	v_lshl_add_u32 v32, v32, 9, v152
	global_load_dwordx4 v[88:91], v32, s[98:99]
	v_med3_i32 v32, v177, 0, s75
	v_lshl_add_u32 v32, v32, 9, v152
	global_load_dwordx4 v[96:99], v32, s[98:99]
	v_or_b32_e32 v32, 0x100, v166
	v_add_u32_e32 v32, s76, v32
	v_med3_i32 v32, v32, 0, s75
	v_lshl_add_u32 v32, v32, 9, v158
	global_load_dwordx4 v[76:79], v32, s[100:101]
	global_load_dwordx4 v[64:67], v32, s[100:101] offset:64
	v_or_b32_e32 v32, 0x110, v166
	v_add_u32_e32 v32, s76, v32
	v_med3_i32 v32, v32, 0, s75
	v_lshl_add_u32 v32, v32, 9, v158
	global_load_dwordx4 v[40:43], v32, s[100:101]
	s_nop 0
	global_load_dwordx4 v[32:35], v32, s[100:101] offset:64
	ds_read_b64_tr_b16 v[142:143], v169 offset:2304
	ds_read_b64_tr_b16 v[140:141], v169
	ds_read_b64_tr_b16 v[136:137], v169 offset:32
	ds_read_b64_tr_b16 v[138:139], v169 offset:2336
	ds_read_b64_tr_b16 v[132:133], v169 offset:64
	ds_read_b64_tr_b16 v[134:135], v169 offset:2368
	ds_read_b64_tr_b16 v[128:129], v169 offset:96
	ds_read_b64_tr_b16 v[130:131], v169 offset:2400
	s_waitcnt vmcnt(15)
	ds_write_b128 v241, v[68:71] offset:4608
	s_waitcnt vmcnt(14)
	ds_write_b128 v242, v[72:75] offset:4608
	s_waitcnt vmcnt(13)
	ds_write_b128 v243, v[80:83] offset:4608
	s_waitcnt vmcnt(12)
	ds_write_b128 v244, v[84:87] offset:4608
	v_mfma_f32_16x16x32_bf16 v[68:71], v[36:39], v[4:7], 0
	v_mfma_f32_16x16x32_bf16 v[72:75], v[24:27], v[4:7], 0
	v_mfma_f32_16x16x32_bf16 v[24:27], v[24:27], v[12:15], 0
	v_mfma_f32_16x16x32_bf16 v[68:71], v[44:47], v[8:11], v[68:71]
	v_mfma_f32_16x16x32_bf16 v[72:75], v[28:31], v[8:11], v[72:75]
	v_mfma_f32_16x16x32_bf16 v[24:27], v[28:31], v[0:3], v[24:27]
	v_add_u32_e32 v29, 0x100, v154
	v_sub_u32_e32 v28, v29, v147
	v_add_u32_e32 v31, 1, v28
	v_mfma_f32_16x16x32_bf16 v[36:39], v[36:39], v[12:15], 0
	s_nop 1
	v_cmp_gt_u32_e64 s[0:1], v31, v146
	v_cmp_gt_u32_e32 vcc, v28, v146
	s_nop 0
	v_cndmask_b32_e64 v69, v69, v246, s[0:1]
	s_nop 0
	v_cndmask_b32_e32 v68, v68, v246, vcc
	v_max_f32_e32 v30, 0xf149f2ca, v68
	v_mfma_f32_16x16x32_bf16 v[36:39], v[44:47], v[0:3], v[36:39]
	v_max_f32_e32 v30, v30, v69
	v_add_u32_e32 v31, 2, v28
	v_add_u32_e32 v44, 3, v28
	v_cmp_gt_u32_e64 s[22:23], v31, v146
	v_cmp_gt_u32_e64 s[24:25], v44, v146
	v_sub_u32_e32 v29, v29, v148
	v_cndmask_b32_e64 v70, v70, v246, s[22:23]
	v_cndmask_b32_e64 v71, v71, v246, s[24:25]
	v_max3_f32 v30, v30, v70, v71
	v_add_u32_e32 v31, 16, v28
	v_add_u32_e32 v44, 17, v28
	v_cmp_gt_u32_e64 s[26:27], v31, v146
	v_cmp_gt_u32_e64 s[28:29], v44, v146
	v_cmp_gt_u32_e64 s[38:39], v29, v145
	v_cndmask_b32_e64 v72, v72, v246, s[26:27]
	v_cndmask_b32_e64 v73, v73, v246, s[28:29]
	v_max3_f32 v30, v30, v72, v73
	v_add_u32_e32 v31, 18, v28
	v_add_u32_e32 v28, 19, v28
	v_cmp_gt_u32_e64 s[30:31], v31, v146
	v_cmp_gt_u32_e64 s[34:35], v28, v146
	v_add_u32_e32 v44, 3, v29
	v_cndmask_b32_e64 v74, v74, v246, s[30:31]
	v_cndmask_b32_e64 v75, v75, v246, s[34:35]
	v_max3_f32 v28, v30, v74, v75
	v_add_u32_e32 v31, 1, v29
	v_cmp_gt_u32_e64 s[40:41], v31, v145
	v_cndmask_b32_e64 v36, v36, v246, s[38:39]
	v_max_f32_e32 v30, 0xf149f2ca, v36
	v_cndmask_b32_e64 v37, v37, v246, s[40:41]
	v_max_f32_e32 v30, v30, v37
	v_add_u32_e32 v31, 2, v29
	v_cmp_gt_u32_e64 s[42:43], v31, v145
	v_cmp_gt_u32_e64 s[44:45], v44, v145
	s_nop 0
	v_cndmask_b32_e64 v38, v38, v246, s[42:43]
	v_cndmask_b32_e64 v39, v39, v246, s[44:45]
	v_max3_f32 v30, v30, v38, v39
	v_add_u32_e32 v31, 16, v29
	v_add_u32_e32 v44, 17, v29
	v_cmp_gt_u32_e64 s[46:47], v31, v145
	v_cmp_gt_u32_e64 s[48:49], v44, v145
	s_nop 0
	v_cndmask_b32_e64 v24, v24, v246, s[46:47]
	v_cndmask_b32_e64 v25, v25, v246, s[48:49]
	v_max3_f32 v30, v30, v24, v25
	v_add_u32_e32 v31, 18, v29
	v_add_u32_e32 v29, 19, v29
	v_cmp_gt_u32_e64 s[50:51], v31, v145
	v_cmp_gt_u32_e64 s[52:53], v29, v145
	s_nop 0
	v_cndmask_b32_e64 v26, v26, v246, s[50:51]
	v_cndmask_b32_e64 v27, v27, v246, s[52:53]
	v_max3_f32 v29, v30, v26, v27
	v_mov_b32_e32 v30, v28
	v_mov_b32_e32 v31, v28
	s_nop 1
	v_permlane32_swap_b32_e32 v30, v31
	v_max3_f32 v28, v28, v30, v31
	v_mov_b32_e32 v30, v29
	v_mov_b32_e32 v31, v29
	s_nop 1
	v_permlane32_swap_b32_e32 v30, v31
	v_max3_f32 v29, v29, v30, v31
	v_mov_b32_e32 v30, v28
	v_mov_b32_e32 v31, v28
	s_nop 1
	v_permlane16_swap_b32_e32 v30, v31
	v_max_f32_e32 v28, v28, v30
	v_mov_b32_e32 v30, v29
	v_mov_b32_e32 v45, v29
	v_max3_f32 v175, v181, v28, v31
	s_nop 0
	v_permlane16_swap_b32_e32 v30, v45
	v_sub_f32_e32 v28, v181, v175
	v_exp_f32_e32 v44, v28
	v_sub_f32_e32 v28, v68, v175
	v_max_f32_e32 v46, v29, v30
	v_exp_f32_e32 v28, v28
	v_sub_f32_e32 v30, v69, v175
	v_exp_f32_e32 v30, v30
	v_sub_f32_e32 v31, v70, v175
	v_exp_f32_e32 v31, v31
	v_sub_f32_e32 v47, v71, v175
	v_max3_f32 v181, v184, v46, v45
	v_exp_f32_e32 v47, v47
	v_sub_f32_e32 v68, v72, v175
	v_sub_f32_e32 v36, v36, v181
	v_exp_f32_e32 v68, v68
	v_sub_f32_e32 v69, v73, v175
	v_exp_f32_e32 v36, v36
	v_sub_f32_e32 v37, v37, v181
	v_add_f32_e32 v29, 0, v28
	v_exp_f32_e32 v69, v69
	v_sub_f32_e32 v70, v74, v175
	v_exp_f32_e32 v37, v37
	v_sub_f32_e32 v38, v38, v181
	v_add_f32_e32 v29, v30, v29
	v_exp_f32_e32 v70, v70
	v_sub_f32_e32 v71, v75, v175
	v_exp_f32_e32 v38, v38
	v_sub_f32_e32 v39, v39, v181
	v_add_f32_e32 v29, v31, v29
	v_exp_f32_e32 v71, v71
	v_exp_f32_e32 v39, v39
	v_sub_f32_e32 v24, v24, v181
	v_add_f32_e32 v29, v47, v29
	v_sub_f32_e32 v45, v184, v181
	v_exp_f32_e32 v24, v24
	v_sub_f32_e32 v25, v25, v181
	v_add_f32_e32 v29, v68, v29
	v_exp_f32_e32 v46, v45
	v_add_f32_e32 v45, 0, v36
	v_exp_f32_e32 v25, v25
	v_add_f32_e32 v29, v69, v29
	v_add_f32_e32 v45, v37, v45
	v_add_f32_e32 v29, v70, v29
	v_add_f32_e32 v45, v38, v45
	v_add_f32_e32 v176, v71, v29
	v_cvt_pk_bf16_f32 v29, v31, v47
	v_add_f32_e32 v45, v39, v45
	v_cndmask_b32_e64 v47, v24, 0, s[46:47]
	v_add_f32_e32 v24, v47, v45
	v_cndmask_b32_e64 v45, v25, 0, s[48:49]
	v_sub_f32_e32 v25, v26, v181
	v_exp_f32_e32 v25, v25
	v_cvt_pk_bf16_f32 v28, v28, v30
	v_cvt_pk_bf16_f32 v30, v68, v69
	v_add_f32_e32 v24, v45, v24
	v_cndmask_b32_e64 v68, v25, 0, s[50:51]
	v_sub_f32_e32 v25, v27, v181
	v_exp_f32_e32 v25, v25
	v_add_f32_e32 v24, v68, v24
	v_fmac_f32_e32 v176, v183, v44
	v_cvt_pk_bf16_f32 v31, v70, v71
	v_cndmask_b32_e64 v27, v25, 0, s[52:53]
	v_add_f32_e32 v183, v27, v24
	v_cvt_pk_bf16_f32 v24, v36, v37
	v_cvt_pk_bf16_f32 v25, v38, v39
	v_pk_mul_f32 v[38:39], v[102:103], v[44:45] op_sel_hi:[1,0]
	v_pk_mul_f32 v[36:37], v[100:101], v[44:45] op_sel_hi:[1,0]
	v_cvt_pk_bf16_f32 v26, v47, v45
	v_cvt_pk_bf16_f32 v27, v68, v27
	s_waitcnt lgkmcnt(10)
	v_mfma_f32_16x16x32_bf16 v[80:83], v[140:143], v[28:31], v[36:39]
	v_fmac_f32_e32 v183, v185, v46
	v_add_u32_e32 v184, s76, v204
	v_add_u32_e32 v185, s76, v205
	v_pk_mul_f32 v[38:39], v[94:95], v[46:47] op_sel_hi:[1,0]
	v_pk_mul_f32 v[36:37], v[92:93], v[46:47] op_sel_hi:[1,0]
	s_nop 1
	v_mfma_f32_16x16x32_bf16 v[84:87], v[140:143], v[24:27], v[36:39]
	s_nop 2
	v_mul_f32_e64 v38, v106, v44
	v_mul_f32_e64 v39, v107, v44
	v_pk_mul_f32 v[36:37], v[104:105], v[44:45] op_sel_hi:[1,0]
	s_waitcnt lgkmcnt(8)
	s_nop 0
	v_mfma_f32_16x16x32_bf16 v[104:107], v[136:139], v[28:31], v[36:39]
	s_nop 2
	v_mul_f32_e64 v38, v110, v46
	v_mul_f32_e64 v39, v111, v46
	v_pk_mul_f32 v[36:37], v[108:109], v[46:47] op_sel_hi:[1,0]
	s_nop 1
	v_mfma_f32_16x16x32_bf16 v[108:111], v[136:139], v[24:27], v[36:39]
	s_nop 2
	v_mul_f32_e64 v38, v114, v44
	v_mul_f32_e64 v39, v115, v44
	v_pk_mul_f32 v[36:37], v[112:113], v[44:45] op_sel_hi:[1,0]
	s_waitcnt lgkmcnt(6)
	s_nop 0
	v_mfma_f32_16x16x32_bf16 v[112:115], v[132:135], v[28:31], v[36:39]
	s_nop 2
	v_mul_f32_e64 v38, v118, v46
	v_mul_f32_e64 v39, v119, v46
	v_pk_mul_f32 v[36:37], v[116:117], v[46:47] op_sel_hi:[1,0]
	s_nop 1
	v_mfma_f32_16x16x32_bf16 v[116:119], v[132:135], v[24:27], v[36:39]
	s_nop 2
	v_mul_f32_e64 v38, v122, v44
	v_mul_f32_e64 v39, v123, v44
	v_pk_mul_f32 v[36:37], v[120:121], v[44:45] op_sel_hi:[1,0]
	s_waitcnt lgkmcnt(4)
	s_nop 0
	v_mfma_f32_16x16x32_bf16 v[120:123], v[128:131], v[28:31], v[36:39]
	v_mul_f32_e64 v30, v126, v46
	v_mul_f32_e64 v31, v127, v46
	v_pk_mul_f32 v[28:29], v[124:125], v[46:47] op_sel_hi:[1,0]
	s_nop 1
	v_mfma_f32_16x16x32_bf16 v[124:127], v[128:131], v[24:27], v[28:31]
	v_add_u32_e32 v24, 0x120, v149
	v_med3_i32 v24, v24, 0, s75
	v_lshl_add_u32 v24, v24, 9, v152
	global_load_dwordx4 v[28:31], v24, s[98:99]
	v_add_u32_e32 v24, 0x120, v150
	v_med3_i32 v24, v24, 0, s75
	v_lshl_add_u32 v24, v24, 9, v152
	global_load_dwordx4 v[44:47], v24, s[98:99]
	v_add_u32_e32 v24, 0x120, v151
	v_med3_i32 v24, v24, 0, s75
	v_lshl_add_u32 v24, v24, 9, v152
	global_load_dwordx4 v[92:95], v24, s[98:99]
	v_add_u32_e32 v24, 0x120, v252
	v_med3_i32 v24, v24, 0, s75
	v_lshl_add_u32 v24, v24, 9, v152
	global_load_dwordx4 v[100:103], v24, s[98:99]
	v_or_b32_e32 v24, 0x120, v166
	v_add_u32_e32 v24, s76, v24
	v_med3_i32 v24, v24, 0, s75
	v_lshl_add_u32 v24, v24, 9, v158
	global_load_dwordx4 v[72:75], v24, s[100:101]
	global_load_dwordx4 v[68:71], v24, s[100:101] offset:64
	v_or_b32_e32 v24, 0x130, v166
	v_add_u32_e32 v24, s76, v24
	v_med3_i32 v24, v24, 0, s75
	v_lshl_add_u32 v24, v24, 9, v158
	global_load_dwordx4 v[36:39], v24, s[100:101]
	s_nop 0
	global_load_dwordx4 v[24:27], v24, s[100:101] offset:64
	ds_read_b64_tr_b16 v[142:143], v169 offset:6912
	ds_read_b64_tr_b16 v[140:141], v169 offset:4608
	ds_read_b64_tr_b16 v[136:137], v169 offset:4640
	ds_read_b64_tr_b16 v[138:139], v169 offset:6944
	ds_read_b64_tr_b16 v[132:133], v169 offset:4672
	ds_read_b64_tr_b16 v[134:135], v169 offset:6976
	ds_read_b64_tr_b16 v[128:129], v169 offset:4704
	ds_read_b64_tr_b16 v[130:131], v169 offset:7008
	s_waitcnt vmcnt(15)
	ds_write_b128 v241, v[56:59]
	s_waitcnt vmcnt(14)
	ds_write_b128 v242, v[60:63]
	s_waitcnt vmcnt(13)
	ds_write_b128 v243, v[88:91]
	s_waitcnt vmcnt(12)
	ds_write_b128 v244, v[96:99]
	v_mfma_f32_16x16x32_bf16 v[56:59], v[48:51], v[4:7], 0
	v_mfma_f32_16x16x32_bf16 v[60:63], v[16:19], v[4:7], 0
	v_mfma_f32_16x16x32_bf16 v[16:19], v[16:19], v[12:15], 0
	v_mfma_f32_16x16x32_bf16 v[56:59], v[52:55], v[8:11], v[56:59]
	v_mfma_f32_16x16x32_bf16 v[60:63], v[20:23], v[8:11], v[60:63]
	v_mfma_f32_16x16x32_bf16 v[16:19], v[20:23], v[0:3], v[16:19]
	v_sub_u32_e32 v20, v195, v147
	v_add_u32_e32 v23, 1, v20
	s_nop 3
	v_mfma_f32_16x16x32_bf16 v[48:51], v[48:51], v[12:15], 0
	v_cmp_gt_u32_e64 s[0:1], v23, v146
	v_cmp_gt_u32_e32 vcc, v20, v146
	s_nop 0
	v_cndmask_b32_e64 v57, v57, v246, s[0:1]
	s_nop 0
	v_cndmask_b32_e32 v56, v56, v246, vcc
	v_max_f32_e32 v22, 0xf149f2ca, v56
	v_mfma_f32_16x16x32_bf16 v[48:51], v[52:55], v[0:3], v[48:51]
	v_max_f32_e32 v22, v22, v57
	v_add_u32_e32 v23, 2, v20
	v_add_u32_e32 v52, 3, v20
	v_cmp_gt_u32_e64 s[22:23], v23, v146
	v_cmp_gt_u32_e64 s[24:25], v52, v146
	v_sub_u32_e32 v21, v195, v148
	v_cndmask_b32_e64 v58, v58, v246, s[22:23]
	v_cndmask_b32_e64 v59, v59, v246, s[24:25]
	v_max3_f32 v22, v22, v58, v59
	v_add_u32_e32 v23, 16, v20
	v_add_u32_e32 v52, 17, v20
	v_cmp_gt_u32_e64 s[26:27], v23, v146
	v_cmp_gt_u32_e64 s[28:29], v52, v146
	v_cmp_gt_u32_e64 s[38:39], v21, v145
	v_cndmask_b32_e64 v60, v60, v246, s[26:27]
	v_cndmask_b32_e64 v61, v61, v246, s[28:29]
	v_max3_f32 v22, v22, v60, v61
	v_add_u32_e32 v23, 18, v20
	v_add_u32_e32 v20, 19, v20
	v_cmp_gt_u32_e64 s[30:31], v23, v146
	v_cmp_gt_u32_e64 s[34:35], v20, v146
	v_add_u32_e32 v52, 3, v21
	v_cndmask_b32_e64 v62, v62, v246, s[30:31]
	v_cndmask_b32_e64 v63, v63, v246, s[34:35]
	v_max3_f32 v20, v22, v62, v63
	v_add_u32_e32 v23, 1, v21
	v_cmp_gt_u32_e64 s[40:41], v23, v145
	v_cndmask_b32_e64 v48, v48, v246, s[38:39]
	v_max_f32_e32 v22, 0xf149f2ca, v48
	v_cndmask_b32_e64 v49, v49, v246, s[40:41]
	v_max_f32_e32 v22, v22, v49
	v_add_u32_e32 v23, 2, v21
	v_cmp_gt_u32_e64 s[42:43], v23, v145
	v_cmp_gt_u32_e64 s[44:45], v52, v145
	s_nop 0
	v_cndmask_b32_e64 v50, v50, v246, s[42:43]
	v_cndmask_b32_e64 v51, v51, v246, s[44:45]
	v_max3_f32 v22, v22, v50, v51
	v_add_u32_e32 v23, 16, v21
	v_add_u32_e32 v52, 17, v21
	v_cmp_gt_u32_e64 s[46:47], v23, v145
	v_cmp_gt_u32_e64 s[48:49], v52, v145
	s_nop 0
	v_cndmask_b32_e64 v16, v16, v246, s[46:47]
	v_cndmask_b32_e64 v17, v17, v246, s[48:49]
	v_max3_f32 v22, v22, v16, v17
	v_add_u32_e32 v23, 18, v21
	v_add_u32_e32 v21, 19, v21
	v_cmp_gt_u32_e64 s[50:51], v23, v145
	v_cmp_gt_u32_e64 s[52:53], v21, v145
	s_nop 0
	v_cndmask_b32_e64 v18, v18, v246, s[50:51]
	v_cndmask_b32_e64 v19, v19, v246, s[52:53]
	v_max3_f32 v21, v22, v18, v19
	v_mov_b32_e32 v22, v20
	v_mov_b32_e32 v23, v20
	s_nop 1
	v_permlane32_swap_b32_e32 v22, v23
	v_max3_f32 v20, v20, v22, v23
	v_mov_b32_e32 v22, v21
	v_mov_b32_e32 v23, v21
	s_nop 1
	v_permlane32_swap_b32_e32 v22, v23
	v_max3_f32 v21, v21, v22, v23
	v_mov_b32_e32 v22, v20
	v_mov_b32_e32 v23, v20
	s_nop 1
	v_permlane16_swap_b32_e32 v22, v23
	v_max_f32_e32 v20, v20, v22
	v_max3_f32 v149, v175, v20, v23
	v_sub_f32_e32 v20, v175, v149
	v_exp_f32_e32 v88, v20
	v_sub_f32_e32 v20, v56, v149
	v_sub_f32_e32 v56, v61, v149
	v_exp_f32_e32 v56, v56
	v_exp_f32_e32 v20, v20
	v_sub_f32_e32 v23, v57, v149
	v_exp_f32_e32 v23, v23
	v_sub_f32_e32 v53, v58, v149
	v_cndmask_b32_e64 v58, v56, 0, s[28:29]
	v_sub_f32_e32 v56, v62, v149
	v_mov_b32_e32 v22, v21
	v_mov_b32_e32 v52, v21
	v_exp_f32_e32 v53, v53
	v_sub_f32_e32 v54, v59, v149
	v_exp_f32_e32 v56, v56
	v_permlane16_swap_b32_e32 v22, v52
	v_exp_f32_e32 v54, v54
	v_sub_f32_e32 v55, v60, v149
	v_exp_f32_e32 v55, v55
	v_max_f32_e32 v21, v21, v22
	v_add_f32_e32 v22, 0, v20
	v_add_f32_e32 v22, v23, v22
	v_cndmask_b32_e64 v59, v56, 0, s[30:31]
	v_sub_f32_e32 v56, v63, v149
	v_add_f32_e32 v22, v53, v22
	v_exp_f32_e32 v56, v56
	v_add_f32_e32 v22, v54, v22
	v_add_f32_e32 v22, v55, v22
	v_add_f32_e32 v22, v58, v22
	v_max3_f32 v151, v181, v21, v52
	v_add_f32_e32 v22, v59, v22
	v_cndmask_b32_e64 v60, v56, 0, s[34:35]
	v_cvt_pk_bf16_f32 v56, v20, v23
	v_sub_f32_e32 v20, v181, v151
	v_add_f32_e32 v150, v60, v22
	v_cvt_pk_bf16_f32 v59, v59, v60
	v_exp_f32_e32 v60, v20
	v_sub_f32_e32 v20, v48, v151
	v_exp_f32_e32 v20, v20
	v_sub_f32_e32 v22, v49, v151
	v_exp_f32_e32 v22, v22
	v_sub_f32_e32 v23, v50, v151
	v_exp_f32_e32 v23, v23
	v_sub_f32_e32 v48, v51, v151
	v_exp_f32_e32 v48, v48
	v_sub_f32_e32 v16, v16, v151
	v_exp_f32_e32 v16, v16
	v_sub_f32_e32 v17, v17, v151
	v_add_f32_e32 v21, 0, v20
	v_exp_f32_e32 v17, v17
	v_add_f32_e32 v21, v22, v21
	v_add_f32_e32 v21, v23, v21
	v_add_f32_e32 v21, v48, v21
	v_cndmask_b32_e64 v49, v16, 0, s[46:47]
	v_add_f32_e32 v16, v49, v21
	v_cndmask_b32_e64 v21, v17, 0, s[48:49]
	v_sub_f32_e32 v17, v18, v151
	v_exp_f32_e32 v17, v17
	v_add_f32_e32 v16, v21, v16
	v_cvt_pk_bf16_f32 v18, v49, v21
	v_cvt_pk_bf16_f32 v57, v53, v54
	v_cndmask_b32_e64 v50, v17, 0, s[50:51]
	v_sub_f32_e32 v17, v19, v151
	v_exp_f32_e32 v17, v17
	v_add_f32_e32 v16, v50, v16
	v_cvt_pk_bf16_f32 v58, v55, v58
	v_fmac_f32_e32 v150, v176, v88
	v_cndmask_b32_e64 v19, v17, 0, s[52:53]
	v_add_f32_e32 v175, v19, v16
	v_cvt_pk_bf16_f32 v16, v20, v22
	v_cvt_pk_bf16_f32 v17, v23, v48
	v_cvt_pk_bf16_f32 v19, v50, v19
	v_pk_mul_f32 v[50:51], v[86:87], v[60:61] op_sel_hi:[1,0]
	v_pk_mul_f32 v[48:49], v[84:85], v[60:61] op_sel_hi:[1,0]
	v_pk_mul_f32 v[22:23], v[82:83], v[88:89] op_sel_hi:[1,0]
	v_pk_mul_f32 v[20:21], v[80:81], v[88:89] op_sel_hi:[1,0]
	s_waitcnt lgkmcnt(10)
	v_mfma_f32_16x16x32_bf16 v[52:55], v[140:143], v[16:19], v[48:51]
	v_fmac_f32_e32 v175, v183, v60
	s_nop 1
	v_pk_mul_f32 v[50:51], v[106:107], v[88:89] op_sel_hi:[1,0]
	v_pk_mul_f32 v[48:49], v[104:105], v[88:89] op_sel_hi:[1,0]
	v_mfma_f32_16x16x32_bf16 v[20:23], v[140:143], v[56:59], v[20:23]
	s_waitcnt lgkmcnt(8)
	v_mfma_f32_16x16x32_bf16 v[104:107], v[136:139], v[56:59], v[48:51]
	s_nop 2
	v_mul_f32_e64 v50, v110, v60
	v_mul_f32_e64 v51, v111, v60
	v_pk_mul_f32 v[48:49], v[108:109], v[60:61] op_sel_hi:[1,0]
	s_nop 1
	v_mfma_f32_16x16x32_bf16 v[108:111], v[136:139], v[16:19], v[48:51]
	s_nop 2
	v_mul_f32_e64 v50, v114, v88
	v_mul_f32_e64 v51, v115, v88
	v_pk_mul_f32 v[48:49], v[112:113], v[88:89] op_sel_hi:[1,0]
	s_waitcnt lgkmcnt(6)
	s_nop 0
	v_mfma_f32_16x16x32_bf16 v[112:115], v[132:135], v[56:59], v[48:51]
	s_nop 2
	v_mul_f32_e64 v50, v118, v60
	v_mul_f32_e64 v51, v119, v60
	v_pk_mul_f32 v[48:49], v[116:117], v[60:61] op_sel_hi:[1,0]
	s_nop 1
	v_mfma_f32_16x16x32_bf16 v[116:119], v[132:135], v[16:19], v[48:51]
	s_nop 2
	v_mul_f32_e64 v50, v122, v88
	v_mul_f32_e64 v51, v123, v88
	v_pk_mul_f32 v[48:49], v[120:121], v[88:89] op_sel_hi:[1,0]
	s_waitcnt lgkmcnt(4)
	s_nop 0
	v_mfma_f32_16x16x32_bf16 v[120:123], v[128:131], v[56:59], v[48:51]
	v_add_u32_e32 v56, 0xffffff00, v206
	v_add_u32_e32 v56, s76, v56
	s_nop 0
	v_pk_mul_f32 v[50:51], v[126:127], v[60:61] op_sel_hi:[1,0]
	v_pk_mul_f32 v[48:49], v[124:125], v[60:61] op_sel_hi:[1,0]
	s_nop 1
	v_mfma_f32_16x16x32_bf16 v[124:127], v[128:131], v[16:19], v[48:51]
	v_add_u32_e32 v16, 0xffffff00, v204
	v_add_u32_e32 v16, s76, v16
	s_nop 0
	v_add_u32_e32 v48, 0xffffff00, v205
	v_add_u32_e32 v48, s76, v48
	v_med3_i32 v16, v16, 0, s75
	v_med3_i32 v48, v48, 0, s75
	v_med3_i32 v56, v56, 0, s75
	v_lshl_add_u32 v56, v56, 9, v152
	global_load_dwordx4 v[88:91], v56, s[98:99]
	v_add_u32_e32 v56, 0xffffff00, v207
	v_add_u32_e32 v56, s76, v56
	v_med3_i32 v56, v56, 0, s75
	v_lshl_add_u32 v56, v56, 9, v152
	global_load_dwordx4 v[96:99], v56, s[98:99]
	v_add_u32_e32 v56, s76, v208
	v_lshl_add_u32 v16, v16, 9, v152
	v_lshl_add_u32 v48, v48, 9, v152
	v_med3_i32 v56, v56, 0, s75
	v_lshl_add_u32 v56, v56, 9, v158
	global_load_dwordx4 v[16:19], v16, s[98:99]
	s_nop 0
	global_load_dwordx4 v[48:51], v48, s[98:99]
	s_nop 0
	global_load_dwordx4 v[84:87], v56, s[100:101]
	global_load_dwordx4 v[80:83], v56, s[100:101] offset:64
	v_or_b32_e32 v56, 0xffffff40, v209
	v_add_u32_e32 v56, s76, v56
	v_med3_i32 v56, v56, 0, s75
	v_lshl_add_u32 v56, v56, 9, v158
	global_load_dwordx4 v[60:63], v56, s[100:101]
	s_nop 0
	global_load_dwordx4 v[56:59], v56, s[100:101] offset:64
	ds_read_b64_tr_b16 v[142:143], v169 offset:2304
	ds_read_b64_tr_b16 v[140:141], v169
	ds_read_b64_tr_b16 v[136:137], v169 offset:32
	ds_read_b64_tr_b16 v[138:139], v169 offset:2336
	ds_read_b64_tr_b16 v[132:133], v169 offset:64
	ds_read_b64_tr_b16 v[134:135], v169 offset:2368
	ds_read_b64_tr_b16 v[128:129], v169 offset:96
	ds_read_b64_tr_b16 v[130:131], v169 offset:2400
	s_waitcnt vmcnt(15)
	ds_write_b128 v241, v[28:31] offset:4608
	s_waitcnt vmcnt(14)
	ds_write_b128 v242, v[44:47] offset:4608
	s_waitcnt vmcnt(13)
	ds_write_b128 v243, v[92:95] offset:4608
	s_waitcnt vmcnt(12)
	ds_write_b128 v244, v[100:103] offset:4608
	v_mfma_f32_16x16x32_bf16 v[28:31], v[76:79], v[4:7], 0
	v_mfma_f32_16x16x32_bf16 v[44:47], v[40:43], v[4:7], 0
	v_mfma_f32_16x16x32_bf16 v[40:43], v[40:43], v[12:15], 0
	v_mfma_f32_16x16x32_bf16 v[28:31], v[64:67], v[8:11], v[28:31]
	v_mfma_f32_16x16x32_bf16 v[44:47], v[32:35], v[8:11], v[44:47]
	v_mfma_f32_16x16x32_bf16 v[32:35], v[32:35], v[0:3], v[40:43]
	s_nop 4
	v_sub_u32_e32 v40, v210, v147
	v_mfma_f32_16x16x32_bf16 v[76:79], v[76:79], v[12:15], 0
	v_add_u32_e32 v43, 1, v40
	v_cmp_gt_u32_e64 s[0:1], v43, v146
	v_cmp_gt_u32_e32 vcc, v40, v146
	s_nop 0
	v_cndmask_b32_e64 v29, v29, v246, s[0:1]
	s_nop 0
	v_cndmask_b32_e32 v28, v28, v246, vcc
	v_max_f32_e32 v42, 0xf149f2ca, v28
	v_mfma_f32_16x16x32_bf16 v[64:67], v[64:67], v[0:3], v[76:79]
	v_max_f32_e32 v42, v42, v29
	v_add_u32_e32 v43, 2, v40
	v_cmp_gt_u32_e64 s[22:23], v43, v146
	v_add_u32_e32 v76, 3, v40
	v_cmp_gt_u32_e64 s[24:25], v76, v146
	v_cndmask_b32_e64 v30, v30, v246, s[22:23]
	v_sub_u32_e32 v41, v210, v148
	v_cndmask_b32_e64 v31, v31, v246, s[24:25]
	v_max3_f32 v42, v42, v30, v31
	v_add_u32_e32 v43, 16, v40
	v_add_u32_e32 v76, 17, v40
	v_cmp_gt_u32_e64 s[26:27], v43, v146
	v_cmp_gt_u32_e64 s[28:29], v76, v146
	v_cmp_gt_u32_e64 s[38:39], v41, v145
	v_cndmask_b32_e64 v44, v44, v246, s[26:27]
	v_cndmask_b32_e64 v45, v45, v246, s[28:29]
	v_max3_f32 v42, v42, v44, v45
	v_add_u32_e32 v43, 18, v40
	v_add_u32_e32 v40, 19, v40
	v_cmp_gt_u32_e64 s[30:31], v43, v146
	v_cmp_gt_u32_e64 s[34:35], v40, v146
	v_add_u32_e32 v76, 3, v41
	v_cndmask_b32_e64 v46, v46, v246, s[30:31]
	v_cndmask_b32_e64 v47, v47, v246, s[34:35]
	v_max3_f32 v40, v42, v46, v47
	v_add_u32_e32 v43, 1, v41
	v_cmp_gt_u32_e64 s[40:41], v43, v145
	v_cndmask_b32_e64 v64, v64, v246, s[38:39]
	v_max_f32_e32 v42, 0xf149f2ca, v64
	v_cndmask_b32_e64 v65, v65, v246, s[40:41]
	v_max_f32_e32 v42, v42, v65
	v_add_u32_e32 v43, 2, v41
	v_cmp_gt_u32_e64 s[42:43], v43, v145
	v_cmp_gt_u32_e64 s[44:45], v76, v145
	s_nop 0
	v_cndmask_b32_e64 v66, v66, v246, s[42:43]
	v_cndmask_b32_e64 v67, v67, v246, s[44:45]
	v_max3_f32 v42, v42, v66, v67
	v_add_u32_e32 v43, 16, v41
	v_add_u32_e32 v76, 17, v41
	v_cmp_gt_u32_e64 s[46:47], v43, v145
	v_cmp_gt_u32_e64 s[48:49], v76, v145
	s_nop 0
	v_cndmask_b32_e64 v32, v32, v246, s[46:47]
	v_cndmask_b32_e64 v33, v33, v246, s[48:49]
	v_max3_f32 v42, v42, v32, v33
	v_add_u32_e32 v43, 18, v41
	v_add_u32_e32 v41, 19, v41
	v_cmp_gt_u32_e64 s[50:51], v43, v145
	v_cmp_gt_u32_e64 s[52:53], v41, v145
	s_nop 0
	v_cndmask_b32_e64 v34, v34, v246, s[50:51]
	v_cndmask_b32_e64 v35, v35, v246, s[52:53]
	v_max3_f32 v41, v42, v34, v35
	v_mov_b32_e32 v42, v40
	v_mov_b32_e32 v43, v40
	s_nop 1
	v_permlane32_swap_b32_e32 v42, v43
	v_max3_f32 v40, v40, v42, v43
	v_mov_b32_e32 v42, v41
	v_mov_b32_e32 v43, v41
	s_nop 1
	v_permlane32_swap_b32_e32 v42, v43
	v_max3_f32 v41, v41, v42, v43
	v_mov_b32_e32 v42, v40
	v_mov_b32_e32 v43, v40
	s_nop 1
	v_permlane16_swap_b32_e32 v42, v43
	v_max_f32_e32 v40, v40, v42
	v_max3_f32 v176, v149, v40, v43
	v_sub_f32_e32 v28, v28, v176
	v_mov_b32_e32 v42, v41
	v_mov_b32_e32 v77, v41
	v_exp_f32_e32 v28, v28
	v_sub_f32_e32 v29, v29, v176
	v_permlane16_swap_b32_e32 v42, v77
	v_exp_f32_e32 v29, v29
	v_sub_f32_e32 v30, v30, v176
	v_exp_f32_e32 v30, v30
	v_sub_f32_e32 v31, v31, v176
	v_max_f32_e32 v41, v41, v42
	v_exp_f32_e32 v31, v31
	v_sub_f32_e32 v42, v44, v176
	v_sub_f32_e32 v40, v149, v176
	v_exp_f32_e32 v42, v42
	v_sub_f32_e32 v43, v45, v176
	v_exp_f32_e32 v76, v40
	v_add_f32_e32 v40, 0, v28
	v_exp_f32_e32 v43, v43
	v_sub_f32_e32 v44, v46, v176
	v_add_f32_e32 v40, v29, v40
	v_exp_f32_e32 v44, v44
	v_sub_f32_e32 v45, v47, v176
	v_add_f32_e32 v40, v30, v40
	v_exp_f32_e32 v45, v45
	v_add_f32_e32 v40, v31, v40
	v_add_f32_e32 v40, v42, v40
	v_add_f32_e32 v40, v43, v40
	v_add_f32_e32 v40, v44, v40
	v_add_f32_e32 v149, v45, v40
	v_fmac_f32_e32 v149, v150, v76
	v_max3_f32 v150, v151, v41, v77
	v_sub_f32_e32 v40, v151, v150
	v_cvt_pk_bf16_f32 v28, v28, v29
	v_cvt_pk_bf16_f32 v29, v30, v31
	v_cvt_pk_bf16_f32 v31, v44, v45
	v_exp_f32_e32 v44, v40
	v_sub_f32_e32 v40, v64, v150
	v_cvt_pk_bf16_f32 v30, v42, v43
	v_exp_f32_e32 v40, v40
	v_sub_f32_e32 v42, v65, v150
	v_exp_f32_e32 v42, v42
	v_sub_f32_e32 v43, v66, v150
	v_exp_f32_e32 v43, v43
	v_sub_f32_e32 v45, v67, v150
	v_exp_f32_e32 v45, v45
	v_sub_f32_e32 v32, v32, v150
	v_exp_f32_e32 v32, v32
	v_sub_f32_e32 v33, v33, v150
	v_add_f32_e32 v41, 0, v40
	v_exp_f32_e32 v33, v33
	v_add_f32_e32 v41, v42, v41
	v_add_f32_e32 v41, v43, v41
	v_add_f32_e32 v41, v45, v41
	v_cndmask_b32_e64 v46, v32, 0, s[46:47]
	v_add_f32_e32 v32, v46, v41
	v_cndmask_b32_e64 v41, v33, 0, s[48:49]
	v_sub_f32_e32 v33, v34, v150
	v_exp_f32_e32 v33, v33
	v_add_f32_e32 v32, v41, v32
	v_pk_mul_f32 v[22:23], v[22:23], v[76:77] op_sel_hi:[1,0]
	v_pk_mul_f32 v[20:21], v[20:21], v[76:77] op_sel_hi:[1,0]
	v_cndmask_b32_e64 v47, v33, 0, s[50:51]
	v_sub_f32_e32 v33, v35, v150
	v_exp_f32_e32 v33, v33
	v_add_f32_e32 v32, v47, v32
	v_cvt_pk_bf16_f32 v34, v46, v41
	v_cndmask_b32_e64 v35, v33, 0, s[52:53]
	v_add_f32_e32 v151, v35, v32
	v_cvt_pk_bf16_f32 v32, v40, v42
	v_cvt_pk_bf16_f32 v33, v43, v45
	v_cvt_pk_bf16_f32 v35, v47, v35
	s_waitcnt lgkmcnt(10)
	v_mfma_f32_16x16x32_bf16 v[40:43], v[140:143], v[28:31], v[20:23]
	v_fmac_f32_e32 v151, v175, v44
	s_nop 1
	v_pk_mul_f32 v[22:23], v[54:55], v[44:45] op_sel_hi:[1,0]
	v_pk_mul_f32 v[20:21], v[52:53], v[44:45] op_sel_hi:[1,0]
	s_nop 1
	v_mfma_f32_16x16x32_bf16 v[92:95], v[140:143], v[32:35], v[20:23]
	s_nop 2
	v_mul_f32_e64 v22, v106, v76
	v_mul_f32_e64 v23, v107, v76
	v_pk_mul_f32 v[20:21], v[104:105], v[76:77] op_sel_hi:[1,0]
	s_waitcnt lgkmcnt(8)
	s_nop 0
	v_mfma_f32_16x16x32_bf16 v[104:107], v[136:139], v[28:31], v[20:23]
	s_nop 2
	v_mul_f32_e64 v22, v110, v44
	v_mul_f32_e64 v23, v111, v44
	v_pk_mul_f32 v[20:21], v[108:109], v[44:45] op_sel_hi:[1,0]
	s_nop 1
	v_mfma_f32_16x16x32_bf16 v[108:111], v[136:139], v[32:35], v[20:23]
	s_nop 2
	v_mul_f32_e64 v22, v114, v76
	v_mul_f32_e64 v23, v115, v76
	v_pk_mul_f32 v[20:21], v[112:113], v[76:77] op_sel_hi:[1,0]
	s_waitcnt lgkmcnt(6)
	s_nop 0
	v_mfma_f32_16x16x32_bf16 v[112:115], v[132:135], v[28:31], v[20:23]
	s_nop 2
	v_mul_f32_e64 v22, v118, v44
	v_mul_f32_e64 v23, v119, v44
	v_pk_mul_f32 v[20:21], v[116:117], v[44:45] op_sel_hi:[1,0]
	s_nop 1
	v_mfma_f32_16x16x32_bf16 v[116:119], v[132:135], v[32:35], v[20:23]
	s_nop 2
	v_mul_f32_e64 v22, v122, v76
	v_mul_f32_e64 v23, v123, v76
	v_pk_mul_f32 v[20:21], v[120:121], v[76:77] op_sel_hi:[1,0]
	s_waitcnt lgkmcnt(4)
	s_nop 0
	v_mfma_f32_16x16x32_bf16 v[120:123], v[128:131], v[28:31], v[20:23]
	s_nop 2
	v_mul_f32_e64 v22, v126, v44
	v_mul_f32_e64 v23, v127, v44
	v_pk_mul_f32 v[20:21], v[124:125], v[44:45] op_sel_hi:[1,0]
	s_nop 1
	v_mfma_f32_16x16x32_bf16 v[124:127], v[128:131], v[32:35], v[20:23]
	s_nop 2
	v_add_u32_e32 v20, 0xffffff80, v204
	v_add_u32_e32 v20, s76, v20
	v_med3_i32 v20, v20, 0, s75
	v_lshl_add_u32 v20, v20, 9, v152
	global_load_dwordx4 v[32:35], v20, s[98:99]
	v_add_u32_e32 v20, 0xffffff80, v205
	v_add_u32_e32 v20, s76, v20
	v_med3_i32 v20, v20, 0, s75
	v_lshl_add_u32 v20, v20, 9, v152
	global_load_dwordx4 v[64:67], v20, s[98:99]
	v_add_u32_e32 v20, 0xffffff80, v206
	v_add_u32_e32 v20, s76, v20
	v_med3_i32 v20, v20, 0, s75
	v_lshl_add_u32 v20, v20, 9, v152
	global_load_dwordx4 v[76:79], v20, s[98:99]
	v_add_u32_e32 v20, 0xffffff80, v207
	v_add_u32_e32 v20, s76, v20
	v_med3_i32 v20, v20, 0, s75
	v_lshl_add_u32 v20, v20, 9, v152
	global_load_dwordx4 v[100:103], v20, s[98:99]
	v_or_b32_e32 v20, 0xffffff80, v209
	v_add_u32_e32 v20, s76, v20
	v_med3_i32 v20, v20, 0, s75
	v_lshl_add_u32 v20, v20, 9, v158
	global_load_dwordx4 v[52:55], v20, s[100:101]
	global_load_dwordx4 v[44:47], v20, s[100:101] offset:64
	v_add_u32_e32 v20, s76, v211
	v_med3_i32 v20, v20, 0, s75
	v_lshl_add_u32 v20, v20, 9, v158
	global_load_dwordx4 v[28:31], v20, s[100:101]
	s_nop 0
	global_load_dwordx4 v[20:23], v20, s[100:101] offset:64
	ds_read_b64_tr_b16 v[142:143], v169 offset:6912
	ds_read_b64_tr_b16 v[140:141], v169 offset:4608
	ds_read_b64_tr_b16 v[136:137], v169 offset:4640
	ds_read_b64_tr_b16 v[138:139], v169 offset:6944
	ds_read_b64_tr_b16 v[132:133], v169 offset:4672
	ds_read_b64_tr_b16 v[134:135], v169 offset:6976
	ds_read_b64_tr_b16 v[128:129], v169 offset:4704
	ds_read_b64_tr_b16 v[130:131], v169 offset:7008
	s_waitcnt vmcnt(13)
	ds_write_b128 v241, v[16:19]
	s_waitcnt vmcnt(12)
	ds_write_b128 v242, v[48:51]
	ds_write_b128 v243, v[88:91]
	ds_write_b128 v244, v[96:99]
	v_mfma_f32_16x16x32_bf16 v[16:19], v[72:75], v[4:7], 0
	v_mfma_f32_16x16x32_bf16 v[48:51], v[36:39], v[4:7], 0
	v_mfma_f32_16x16x32_bf16 v[36:39], v[36:39], v[12:15], 0
	v_mfma_f32_16x16x32_bf16 v[16:19], v[68:71], v[8:11], v[16:19]
	v_mfma_f32_16x16x32_bf16 v[48:51], v[24:27], v[8:11], v[48:51]
	v_mfma_f32_16x16x32_bf16 v[24:27], v[24:27], v[0:3], v[36:39]
	s_nop 4
	v_sub_u32_e32 v36, v212, v147
	v_mfma_f32_16x16x32_bf16 v[72:75], v[72:75], v[12:15], 0
	v_add_u32_e32 v39, 1, v36
	v_cmp_gt_u32_e64 s[0:1], v39, v146
	v_cmp_gt_u32_e32 vcc, v36, v146
	s_nop 0
	v_cndmask_b32_e64 v17, v17, v246, s[0:1]
	s_nop 0
	v_cndmask_b32_e32 v16, v16, v246, vcc
	v_max_f32_e32 v38, 0xf149f2ca, v16
	v_mfma_f32_16x16x32_bf16 v[68:71], v[68:71], v[0:3], v[72:75]
	v_max_f32_e32 v38, v38, v17
	v_add_u32_e32 v39, 2, v36
	v_cmp_gt_u32_e64 s[22:23], v39, v146
	v_add_u32_e32 v72, 3, v36
	v_cmp_gt_u32_e64 s[24:25], v72, v146
	v_cndmask_b32_e64 v18, v18, v246, s[22:23]
	v_sub_u32_e32 v37, v212, v148
	v_cndmask_b32_e64 v19, v19, v246, s[24:25]
	v_max3_f32 v38, v38, v18, v19
	v_add_u32_e32 v39, 16, v36
	v_add_u32_e32 v72, 17, v36
	v_cmp_gt_u32_e64 s[26:27], v39, v146
	v_cmp_gt_u32_e64 s[28:29], v72, v146
	v_cmp_gt_u32_e64 s[38:39], v37, v145
	v_cndmask_b32_e64 v48, v48, v246, s[26:27]
	v_cndmask_b32_e64 v49, v49, v246, s[28:29]
	v_max3_f32 v38, v38, v48, v49
	v_add_u32_e32 v39, 18, v36
	v_add_u32_e32 v36, 19, v36
	v_cmp_gt_u32_e64 s[30:31], v39, v146
	v_cmp_gt_u32_e64 s[34:35], v36, v146
	v_add_u32_e32 v72, 3, v37
	v_cndmask_b32_e64 v50, v50, v246, s[30:31]
	v_cndmask_b32_e64 v51, v51, v246, s[34:35]
	v_max3_f32 v36, v38, v50, v51
	v_add_u32_e32 v39, 1, v37
	v_cmp_gt_u32_e64 s[40:41], v39, v145
	v_cndmask_b32_e64 v68, v68, v246, s[38:39]
	v_max_f32_e32 v38, 0xf149f2ca, v68
	v_cndmask_b32_e64 v69, v69, v246, s[40:41]
	v_max_f32_e32 v38, v38, v69
	v_add_u32_e32 v39, 2, v37
	v_cmp_gt_u32_e64 s[42:43], v39, v145
	v_cmp_gt_u32_e64 s[44:45], v72, v145
	s_nop 0
	v_cndmask_b32_e64 v70, v70, v246, s[42:43]
	v_cndmask_b32_e64 v71, v71, v246, s[44:45]
	v_max3_f32 v38, v38, v70, v71
	v_add_u32_e32 v39, 16, v37
	v_add_u32_e32 v72, 17, v37
	v_cmp_gt_u32_e64 s[46:47], v39, v145
	v_cmp_gt_u32_e64 s[48:49], v72, v145
	s_nop 0
	v_cndmask_b32_e64 v24, v24, v246, s[46:47]
	v_cndmask_b32_e64 v25, v25, v246, s[48:49]
	v_max3_f32 v38, v38, v24, v25
	v_add_u32_e32 v39, 18, v37
	v_add_u32_e32 v37, 19, v37
	v_cmp_gt_u32_e64 s[50:51], v39, v145
	v_cmp_gt_u32_e64 s[52:53], v37, v145
	s_nop 0
	v_cndmask_b32_e64 v26, v26, v246, s[50:51]
	v_cndmask_b32_e64 v27, v27, v246, s[52:53]
	v_max3_f32 v37, v38, v26, v27
	v_mov_b32_e32 v38, v36
	v_mov_b32_e32 v39, v36
	s_nop 1
	v_permlane32_swap_b32_e32 v38, v39
	v_max3_f32 v36, v36, v38, v39
	v_mov_b32_e32 v38, v37
	v_mov_b32_e32 v39, v37
	s_nop 1
	v_permlane32_swap_b32_e32 v38, v39
	v_max3_f32 v37, v37, v38, v39
	v_mov_b32_e32 v38, v36
	v_mov_b32_e32 v39, v36
	s_nop 1
	v_permlane16_swap_b32_e32 v38, v39
	v_max_f32_e32 v36, v36, v38
	v_max3_f32 v145, v176, v36, v39
	v_sub_f32_e32 v16, v16, v145
	v_mov_b32_e32 v38, v37
	v_mov_b32_e32 v72, v37
	v_exp_f32_e32 v16, v16
	v_sub_f32_e32 v17, v17, v145
	v_permlane16_swap_b32_e32 v38, v72
	v_exp_f32_e32 v17, v17
	v_sub_f32_e32 v18, v18, v145
	v_exp_f32_e32 v18, v18
	v_sub_f32_e32 v19, v19, v145
	v_max_f32_e32 v37, v37, v38
	v_exp_f32_e32 v19, v19
	v_sub_f32_e32 v38, v48, v145
	v_sub_f32_e32 v36, v176, v145
	v_exp_f32_e32 v38, v38
	v_sub_f32_e32 v39, v49, v145
	v_exp_f32_e32 v88, v36
	v_add_f32_e32 v36, 0, v16
	v_exp_f32_e32 v39, v39
	v_sub_f32_e32 v48, v50, v145
	v_add_f32_e32 v36, v17, v36
	v_exp_f32_e32 v48, v48
	v_sub_f32_e32 v49, v51, v145
	v_add_f32_e32 v36, v18, v36
	v_exp_f32_e32 v49, v49
	v_add_f32_e32 v36, v19, v36
	v_add_f32_e32 v36, v38, v36
	v_add_f32_e32 v36, v39, v36
	v_add_f32_e32 v36, v48, v36
	v_max3_f32 v147, v150, v37, v72
	v_add_f32_e32 v146, v49, v36
	v_sub_f32_e32 v36, v150, v147
	v_cvt_pk_bf16_f32 v16, v16, v17
	v_cvt_pk_bf16_f32 v17, v18, v19
	v_cvt_pk_bf16_f32 v19, v48, v49
	v_exp_f32_e32 v48, v36
	v_sub_f32_e32 v36, v68, v147
	v_cvt_pk_bf16_f32 v18, v38, v39
	v_exp_f32_e32 v36, v36
	v_sub_f32_e32 v38, v69, v147
	v_exp_f32_e32 v38, v38
	v_sub_f32_e32 v39, v70, v147
	v_exp_f32_e32 v39, v39
	v_sub_f32_e32 v49, v71, v147
	v_exp_f32_e32 v49, v49
	v_sub_f32_e32 v24, v24, v147
	v_exp_f32_e32 v24, v24
	v_sub_f32_e32 v25, v25, v147
	v_add_f32_e32 v37, 0, v36
	v_exp_f32_e32 v25, v25
	v_add_f32_e32 v37, v38, v37
	v_add_f32_e32 v37, v39, v37
	v_add_f32_e32 v37, v49, v37
	v_cndmask_b32_e64 v50, v24, 0, s[46:47]
	v_add_f32_e32 v24, v50, v37
	v_cndmask_b32_e64 v37, v25, 0, s[48:49]
	v_sub_f32_e32 v25, v26, v147
	v_exp_f32_e32 v25, v25
	v_add_f32_e32 v24, v37, v24
	v_cvt_pk_bf16_f32 v26, v50, v37
	v_cmp_lt_i32_e32 vcc, -1, v184
	v_cndmask_b32_e64 v51, v25, 0, s[50:51]
	v_sub_f32_e32 v25, v27, v147
	v_exp_f32_e32 v25, v25
	v_add_f32_e32 v24, v51, v24
	v_fmac_f32_e32 v146, v149, v88
	s_add_i32 s0, s76, 0xffffff00
	v_cndmask_b32_e64 v27, v25, 0, s[52:53]
	v_add_f32_e32 v183, v27, v24
	v_cvt_pk_bf16_f32 v24, v36, v38
	v_cvt_pk_bf16_f32 v25, v39, v49
	v_cvt_pk_bf16_f32 v27, v51, v27
	v_pk_mul_f32 v[38:39], v[42:43], v[88:89] op_sel_hi:[1,0]
	v_pk_mul_f32 v[36:37], v[40:41], v[88:89] op_sel_hi:[1,0]
	v_pk_mul_f32 v[42:43], v[94:95], v[48:49] op_sel_hi:[1,0]
	v_pk_mul_f32 v[40:41], v[92:93], v[48:49] op_sel_hi:[1,0]
	s_waitcnt lgkmcnt(10)
	v_mfma_f32_16x16x32_bf16 v[36:39], v[140:143], v[16:19], v[36:39]
	v_fmac_f32_e32 v183, v151, v48
	s_min_i32 s1, s0, 0
	s_sub_i32 s1, 3, s1
	v_mfma_f32_16x16x32_bf16 v[68:71], v[140:143], v[24:27], v[40:43]
	s_ashr_i32 s1, s1, 2
	s_sub_i32 s22, 0x200, s76
	s_sub_i32 s0, s75, s0
	v_pk_mul_f32 v[42:43], v[106:107], v[88:89] op_sel_hi:[1,0]
	v_pk_mul_f32 v[40:41], v[104:105], v[88:89] op_sel_hi:[1,0]
	s_ashr_i32 s0, s0, 2
	s_cmp_lt_i32 s76, 0
	s_waitcnt lgkmcnt(8)
	v_mfma_f32_16x16x32_bf16 v[72:75], v[136:139], v[16:19], v[40:43]
	s_nop 2
	v_mul_f32_e64 v42, v110, v48
	v_mul_f32_e64 v43, v111, v48
	v_pk_mul_f32 v[40:41], v[108:109], v[48:49] op_sel_hi:[1,0]
	s_nop 1
	v_mfma_f32_16x16x32_bf16 v[104:107], v[136:139], v[24:27], v[40:43]
	s_nop 2
	v_mul_f32_e64 v42, v114, v88
	v_mul_f32_e64 v43, v115, v88
	v_pk_mul_f32 v[40:41], v[112:113], v[88:89] op_sel_hi:[1,0]
	s_waitcnt lgkmcnt(6)
	s_nop 0
	v_mfma_f32_16x16x32_bf16 v[108:111], v[132:135], v[16:19], v[40:43]
	s_nop 2
	v_mul_f32_e64 v42, v118, v48
	v_mul_f32_e64 v43, v119, v48
	v_pk_mul_f32 v[40:41], v[116:117], v[48:49] op_sel_hi:[1,0]
	s_nop 1
	v_mfma_f32_16x16x32_bf16 v[112:115], v[132:135], v[24:27], v[40:43]
	s_nop 2
	v_mul_f32_e64 v42, v122, v88
	v_mul_f32_e64 v43, v123, v88
	v_pk_mul_f32 v[40:41], v[120:121], v[88:89] op_sel_hi:[1,0]
	s_waitcnt lgkmcnt(4)
	s_nop 0
	v_mfma_f32_16x16x32_bf16 v[116:119], v[128:131], v[16:19], v[40:43]
	v_mul_f32_e64 v18, v126, v48
	v_mul_f32_e64 v19, v127, v48
	v_pk_mul_f32 v[16:17], v[124:125], v[48:49] op_sel_hi:[1,0]
	s_nop 1
	v_mfma_f32_16x16x32_bf16 v[128:131], v[128:131], v[24:27], v[16:19]
	s_nop 2
	v_min_i32_e32 v16, s75, v184
	v_cndmask_b32_e32 v16, 0, v16, vcc
	v_lshl_add_u32 v16, v16, 9, v152
	global_load_dwordx4 v[88:91], v16, s[98:99]
	v_med3_i32 v16, v185, 0, s75
	v_lshl_add_u32 v16, v16, 9, v152
	global_load_dwordx4 v[92:95], v16, s[98:99]
	v_med3_i32 v16, v186, 0, s75
	v_lshl_add_u32 v16, v16, 9, v152
	global_load_dwordx4 v[120:123], v16, s[98:99]
	v_med3_i32 v16, v188, 0, s75
	v_lshl_add_u32 v16, v16, 9, v152
	global_load_dwordx4 v[124:127], v16, s[98:99]
	v_add_u32_e32 v16, s76, v209
	v_med3_i32 v16, v16, 0, s75
	v_lshl_add_u32 v16, v16, 9, v158
	global_load_dwordx4 v[48:51], v16, s[100:101]
	global_load_dwordx4 v[40:43], v16, s[100:101] offset:64
	v_or_b32_e32 v16, 64, v209
	v_add_u32_e32 v16, s76, v16
	v_med3_i32 v16, v16, 0, s75
	v_lshl_add_u32 v16, v16, 9, v158
	global_load_dwordx4 v[24:27], v16, s[100:101]
	s_nop 0
	global_load_dwordx4 v[16:19], v16, s[100:101] offset:64
	ds_read_b64_tr_b16 v[98:99], v169 offset:2304
	ds_read_b64_tr_b16 v[96:97], v169
	ds_read_b64_tr_b16 v[140:141], v169 offset:32
	ds_read_b64_tr_b16 v[142:143], v169 offset:2336
	ds_read_b64_tr_b16 v[136:137], v169 offset:64
	ds_read_b64_tr_b16 v[138:139], v169 offset:2368
	ds_read_b64_tr_b16 v[132:133], v169 offset:96
	ds_read_b64_tr_b16 v[134:135], v169 offset:2400
	s_waitcnt vmcnt(15)
	ds_write_b128 v241, v[32:35] offset:4608
	s_waitcnt vmcnt(14)
	ds_write_b128 v242, v[64:67] offset:4608
	s_waitcnt vmcnt(13)
	ds_write_b128 v243, v[76:79] offset:4608
	s_waitcnt vmcnt(12)
	ds_write_b128 v244, v[100:103] offset:4608
	v_mfma_f32_16x16x32_bf16 v[64:67], v[60:63], v[4:7], 0
	v_mfma_f32_16x16x32_bf16 v[60:63], v[60:63], v[12:15], 0
	v_mfma_f32_16x16x32_bf16 v[32:35], v[84:87], v[4:7], 0
	v_mfma_f32_16x16x32_bf16 v[64:67], v[56:59], v[8:11], v[64:67]
	v_mfma_f32_16x16x32_bf16 v[56:59], v[56:59], v[0:3], v[60:63]
	s_nop 4
	v_ashrrev_i32_e32 v60, 2, v250
	v_max_i32_e32 v176, s1, v60
	v_add_u32_e32 v60, s22, v251
	v_ashrrev_i32_e32 v60, 2, v60
	v_min3_i32 v60, v60, s0, v247
	v_mfma_f32_16x16x32_bf16 v[32:35], v[80:83], v[8:11], v[32:35]
	v_sub_u32_e32 v175, v60, v176
	v_ashrrev_i32_e32 v60, 2, v249
	v_max_i32_e32 v181, s1, v60
	v_add_u32_e32 v60, s22, v144
	v_sub_u32_e32 v61, v154, v176
	v_ashrrev_i32_e32 v60, 2, v60
	v_mfma_f32_16x16x32_bf16 v[76:79], v[84:87], v[12:15], 0
	v_min3_i32 v60, v60, s0, v247
	v_add_u32_e32 v63, 1, v61
	v_sub_u32_e32 v252, v60, v181
	v_cmp_gt_u32_e64 s[0:1], v63, v175
	v_cmp_gt_u32_e32 vcc, v61, v175
	s_nop 0
	v_cndmask_b32_e64 v33, v33, v246, s[0:1]
	s_nop 0
	v_cndmask_b32_e32 v32, v32, v246, vcc
	v_max_f32_e32 v60, 0xf149f2ca, v32
	v_mfma_f32_16x16x32_bf16 v[76:79], v[80:83], v[0:3], v[76:79]
	v_max_f32_e32 v60, v60, v33
	v_add_u32_e32 v63, 2, v61
	v_add_u32_e32 v80, 3, v61
	v_cmp_gt_u32_e64 s[22:23], v63, v175
	v_cmp_gt_u32_e64 s[24:25], v80, v175
	v_sub_u32_e32 v62, v154, v181
	v_cndmask_b32_e64 v34, v34, v246, s[22:23]
	v_cndmask_b32_e64 v35, v35, v246, s[24:25]
	v_max3_f32 v60, v60, v34, v35
	v_add_u32_e32 v63, 16, v61
	v_add_u32_e32 v80, 17, v61
	v_cmp_gt_u32_e64 s[26:27], v63, v175
	v_cmp_gt_u32_e64 s[28:29], v80, v175
	v_cmp_gt_u32_e64 s[38:39], v62, v252
	v_cndmask_b32_e64 v64, v64, v246, s[26:27]
	v_cndmask_b32_e64 v65, v65, v246, s[28:29]
	v_max3_f32 v60, v60, v64, v65
	v_add_u32_e32 v63, 18, v61
	v_add_u32_e32 v61, 19, v61
	v_cmp_gt_u32_e64 s[30:31], v63, v175
	v_cmp_gt_u32_e64 s[34:35], v61, v175
	v_add_u32_e32 v80, 3, v62
	v_cndmask_b32_e64 v66, v66, v246, s[30:31]
	v_cndmask_b32_e64 v67, v67, v246, s[34:35]
	v_max3_f32 v60, v60, v66, v67
	v_add_u32_e32 v63, 1, v62
	v_cmp_gt_u32_e64 s[40:41], v63, v252
	v_cndmask_b32_e64 v76, v76, v246, s[38:39]
	v_max_f32_e32 v61, 0xf149f2ca, v76
	v_cndmask_b32_e64 v77, v77, v246, s[40:41]
	v_max_f32_e32 v61, v61, v77
	v_add_u32_e32 v63, 2, v62
	v_cmp_gt_u32_e64 s[42:43], v63, v252
	v_cmp_gt_u32_e64 s[44:45], v80, v252
	s_nop 0
	v_cndmask_b32_e64 v78, v78, v246, s[42:43]
	v_cndmask_b32_e64 v79, v79, v246, s[44:45]
	v_max3_f32 v61, v61, v78, v79
	v_add_u32_e32 v63, 16, v62
	v_add_u32_e32 v80, 17, v62
	v_cmp_gt_u32_e64 s[46:47], v63, v252
	v_cmp_gt_u32_e64 s[48:49], v80, v252
	s_nop 0
	v_cndmask_b32_e64 v56, v56, v246, s[46:47]
	v_cndmask_b32_e64 v57, v57, v246, s[48:49]
	v_max3_f32 v61, v61, v56, v57
	v_add_u32_e32 v63, 18, v62
	v_add_u32_e32 v62, 19, v62
	v_cmp_gt_u32_e64 s[50:51], v63, v252
	v_cmp_gt_u32_e64 s[52:53], v62, v252
	s_nop 0
	v_cndmask_b32_e64 v58, v58, v246, s[50:51]
	v_cndmask_b32_e64 v59, v59, v246, s[52:53]
	v_max3_f32 v61, v61, v58, v59
	v_mov_b32_e32 v62, v60
	v_mov_b32_e32 v63, v60
	s_nop 1
	v_permlane32_swap_b32_e32 v62, v63
	v_max3_f32 v60, v60, v62, v63
	v_mov_b32_e32 v62, v61
	v_mov_b32_e32 v63, v61
	s_nop 1
	v_permlane32_swap_b32_e32 v62, v63
	v_max3_f32 v61, v61, v62, v63
	v_mov_b32_e32 v62, v60
	v_mov_b32_e32 v63, v60
	s_nop 1
	v_permlane16_swap_b32_e32 v62, v63
	v_max_f32_e32 v60, v60, v62
	v_max3_f32 v148, v145, v60, v63
	v_sub_f32_e32 v32, v32, v148
	v_exp_f32_e32 v32, v32
	v_sub_f32_e32 v33, v33, v148
	v_exp_f32_e32 v33, v33
	v_sub_f32_e32 v34, v34, v148
	v_mov_b32_e32 v62, v61
	v_mov_b32_e32 v80, v61
	v_exp_f32_e32 v34, v34
	v_sub_f32_e32 v35, v35, v148
	v_permlane16_swap_b32_e32 v62, v80
	v_exp_f32_e32 v35, v35
	v_sub_f32_e32 v63, v64, v148
	v_exp_f32_e32 v63, v63
	v_sub_f32_e32 v64, v65, v148
	v_max_f32_e32 v61, v61, v62
	v_add_f32_e32 v62, 0, v32
	v_exp_f32_e32 v64, v64
	v_sub_f32_e32 v65, v66, v148
	v_add_f32_e32 v62, v33, v62
	v_exp_f32_e32 v65, v65
	v_sub_f32_e32 v66, v67, v148
	v_add_f32_e32 v62, v34, v62
	v_exp_f32_e32 v66, v66
	v_add_f32_e32 v62, v35, v62
	v_add_f32_e32 v62, v63, v62
	v_add_f32_e32 v62, v64, v62
	v_max3_f32 v150, v147, v61, v80
	v_add_f32_e32 v62, v65, v62
	v_sub_f32_e32 v61, v147, v150
	v_add_f32_e32 v149, v66, v62
	v_exp_f32_e32 v62, v61
	v_sub_f32_e32 v61, v76, v150
	v_cvt_pk_bf16_f32 v32, v32, v33
	v_cvt_pk_bf16_f32 v33, v34, v35
	v_cvt_pk_bf16_f32 v34, v63, v64
	v_exp_f32_e32 v61, v61
	v_sub_f32_e32 v64, v77, v150
	v_cvt_pk_bf16_f32 v35, v65, v66
	v_exp_f32_e32 v64, v64
	v_sub_f32_e32 v65, v78, v150
	v_exp_f32_e32 v65, v65
	v_sub_f32_e32 v66, v79, v150
	v_exp_f32_e32 v66, v66
	v_sub_f32_e32 v56, v56, v150
	v_exp_f32_e32 v56, v56
	v_sub_f32_e32 v57, v57, v150
	v_add_f32_e32 v63, 0, v61
	v_exp_f32_e32 v57, v57
	v_add_f32_e32 v63, v64, v63
	v_add_f32_e32 v63, v65, v63
	v_add_f32_e32 v63, v66, v63
	v_cndmask_b32_e64 v67, v56, 0, s[46:47]
	v_add_f32_e32 v56, v67, v63
	v_cndmask_b32_e64 v63, v57, 0, s[48:49]
	v_sub_f32_e32 v57, v58, v150
	v_exp_f32_e32 v57, v57
	v_sub_f32_e32 v60, v145, v148
	v_exp_f32_e32 v60, v60
	v_add_f32_e32 v56, v63, v56
	v_cndmask_b32_e64 v76, v57, 0, s[50:51]
	v_sub_f32_e32 v57, v59, v150
	v_exp_f32_e32 v57, v57
	v_add_f32_e32 v56, v76, v56
	v_pk_mul_f32 v[38:39], v[38:39], v[60:61] op_sel_hi:[1,0]
	v_pk_mul_f32 v[36:37], v[36:37], v[60:61] op_sel_hi:[1,0]
	v_cndmask_b32_e64 v59, v57, 0, s[52:53]
	v_add_f32_e32 v151, v59, v56
	v_cvt_pk_bf16_f32 v56, v61, v64
	v_cvt_pk_bf16_f32 v57, v65, v66
	v_cvt_pk_bf16_f32 v58, v67, v63
	v_cvt_pk_bf16_f32 v59, v76, v59
	s_waitcnt lgkmcnt(10)
	v_mfma_f32_16x16x32_bf16 v[80:83], v[96:99], v[32:35], v[36:39]
	v_fmac_f32_e32 v149, v146, v60
	v_fmac_f32_e32 v151, v183, v62
	s_nop 0
	v_pk_mul_f32 v[38:39], v[70:71], v[62:63] op_sel_hi:[1,0]
	v_pk_mul_f32 v[36:37], v[68:69], v[62:63] op_sel_hi:[1,0]
	s_nop 1
	v_mfma_f32_16x16x32_bf16 v[84:87], v[96:99], v[56:59], v[36:39]
	s_nop 2
	v_mul_f32_e64 v38, v74, v60
	v_mul_f32_e64 v39, v75, v60
	v_pk_mul_f32 v[36:37], v[72:73], v[60:61] op_sel_hi:[1,0]
	s_waitcnt lgkmcnt(8)
	s_nop 0
	v_mfma_f32_16x16x32_bf16 v[96:99], v[140:143], v[32:35], v[36:39]
	s_nop 2
	v_mul_f32_e64 v38, v106, v62
	v_mul_f32_e64 v39, v107, v62
	v_pk_mul_f32 v[36:37], v[104:105], v[62:63] op_sel_hi:[1,0]
	s_nop 1
	v_mfma_f32_16x16x32_bf16 v[100:103], v[140:143], v[56:59], v[36:39]
	s_nop 2
	v_mul_f32_e64 v38, v110, v60
	v_mul_f32_e64 v39, v111, v60
	v_pk_mul_f32 v[36:37], v[108:109], v[60:61] op_sel_hi:[1,0]
	s_waitcnt lgkmcnt(6)
	s_nop 0
	v_mfma_f32_16x16x32_bf16 v[104:107], v[136:139], v[32:35], v[36:39]
	s_nop 2
	v_mul_f32_e64 v38, v114, v62
	v_mul_f32_e64 v39, v115, v62
	v_pk_mul_f32 v[36:37], v[112:113], v[62:63] op_sel_hi:[1,0]
	s_nop 1
	v_mfma_f32_16x16x32_bf16 v[108:111], v[136:139], v[56:59], v[36:39]
	s_nop 2
	v_mul_f32_e64 v38, v118, v60
	v_mul_f32_e64 v39, v119, v60
	v_pk_mul_f32 v[36:37], v[116:117], v[60:61] op_sel_hi:[1,0]
	s_waitcnt lgkmcnt(4)
	s_nop 0
	v_mfma_f32_16x16x32_bf16 v[112:115], v[132:135], v[32:35], v[36:39]
	v_mul_f32_e64 v34, v130, v62
	v_mul_f32_e64 v35, v131, v62
	v_pk_mul_f32 v[32:33], v[128:129], v[62:63] op_sel_hi:[1,0]
	s_nop 1
	v_mfma_f32_16x16x32_bf16 v[116:119], v[132:135], v[56:59], v[32:35]
	s_nop 2
	v_add_u32_e32 v32, 0x80, v184
	v_med3_i32 v32, v32, 0, s75
	v_lshl_add_u32 v32, v32, 9, v152
	global_load_dwordx4 v[64:67], v32, s[98:99]
	v_add_u32_e32 v32, 0x80, v185
	v_med3_i32 v32, v32, 0, s75
	v_lshl_add_u32 v32, v32, 9, v152
	global_load_dwordx4 v[68:71], v32, s[98:99]
	v_add_u32_e32 v32, 0x80, v186
	v_med3_i32 v32, v32, 0, s75
	v_lshl_add_u32 v32, v32, 9, v152
	global_load_dwordx4 v[72:75], v32, s[98:99]
	v_add_u32_e32 v32, 0x80, v188
	v_med3_i32 v32, v32, 0, s75
	v_lshl_add_u32 v32, v32, 9, v152
	global_load_dwordx4 v[76:79], v32, s[98:99]
	v_or_b32_e32 v32, 0x80, v209
	v_add_u32_e32 v32, s76, v32
	v_med3_i32 v32, v32, 0, s75
	v_lshl_add_u32 v32, v32, 9, v158
	global_load_dwordx4 v[60:63], v32, s[100:101]
	global_load_dwordx4 v[56:59], v32, s[100:101] offset:64
	v_or_b32_e32 v32, 0xc0, v209
	v_add_u32_e32 v32, s76, v32
	v_med3_i32 v32, v32, 0, s75
	v_lshl_add_u32 v32, v32, 9, v158
	global_load_dwordx4 v[36:39], v32, s[100:101]
	s_nop 0
	global_load_dwordx4 v[32:35], v32, s[100:101] offset:64
	ds_read_b64_tr_b16 v[134:135], v169 offset:6912
	ds_read_b64_tr_b16 v[132:133], v169 offset:4608
	ds_read_b64_tr_b16 v[128:129], v169 offset:4640
	ds_read_b64_tr_b16 v[130:131], v169 offset:6944
	ds_read_b64_tr_b16 v[136:137], v169 offset:4672
	ds_read_b64_tr_b16 v[138:139], v169 offset:6976
	ds_read_b64_tr_b16 v[144:145], v169 offset:4704
	ds_read_b64_tr_b16 v[146:147], v169 offset:7008
	s_waitcnt vmcnt(15)
	ds_write_b128 v241, v[88:91]
	s_waitcnt vmcnt(14)
	ds_write_b128 v242, v[92:95]
	s_waitcnt vmcnt(13)
	ds_write_b128 v243, v[120:123]
	s_waitcnt vmcnt(12)
	ds_write_b128 v244, v[124:127]
	v_mfma_f32_16x16x32_bf16 v[88:91], v[52:55], v[4:7], 0
	v_mfma_f32_16x16x32_bf16 v[92:95], v[28:31], v[4:7], 0
	v_mfma_f32_16x16x32_bf16 v[28:31], v[28:31], v[12:15], 0
	v_mfma_f32_16x16x32_bf16 v[88:91], v[44:47], v[8:11], v[88:91]
	v_mfma_f32_16x16x32_bf16 v[92:95], v[20:23], v[8:11], v[92:95]
	v_mfma_f32_16x16x32_bf16 v[20:23], v[20:23], v[0:3], v[28:31]
	s_nop 4
	v_sub_u32_e32 v28, v187, v176
	v_mfma_f32_16x16x32_bf16 v[52:55], v[52:55], v[12:15], 0
	v_add_u32_e32 v31, 1, v28
	v_cmp_gt_u32_e64 s[0:1], v31, v175
	v_cmp_gt_u32_e32 vcc, v28, v175
	s_nop 0
	v_cndmask_b32_e64 v89, v89, v246, s[0:1]
	s_nop 0
	v_cndmask_b32_e32 v88, v88, v246, vcc
	v_max_f32_e32 v30, 0xf149f2ca, v88
	v_mfma_f32_16x16x32_bf16 v[44:47], v[44:47], v[0:3], v[52:55]
	v_max_f32_e32 v30, v30, v89
	v_add_u32_e32 v31, 2, v28
	v_cmp_gt_u32_e64 s[22:23], v31, v175
	v_add_u32_e32 v52, 3, v28
	v_cmp_gt_u32_e64 s[24:25], v52, v175
	v_cndmask_b32_e64 v90, v90, v246, s[22:23]
	v_sub_u32_e32 v29, v187, v181
	v_cndmask_b32_e64 v91, v91, v246, s[24:25]
	v_max3_f32 v30, v30, v90, v91
	v_add_u32_e32 v31, 16, v28
	v_add_u32_e32 v52, 17, v28
	v_cmp_gt_u32_e64 s[26:27], v31, v175
	v_cmp_gt_u32_e64 s[28:29], v52, v175
	v_cmp_gt_u32_e64 s[38:39], v29, v252
	v_cndmask_b32_e64 v92, v92, v246, s[26:27]
	v_cndmask_b32_e64 v93, v93, v246, s[28:29]
	v_max3_f32 v30, v30, v92, v93
	v_add_u32_e32 v31, 18, v28
	v_add_u32_e32 v28, 19, v28
	v_cmp_gt_u32_e64 s[30:31], v31, v175
	v_cmp_gt_u32_e64 s[34:35], v28, v175
	v_add_u32_e32 v52, 3, v29
	v_cndmask_b32_e64 v94, v94, v246, s[30:31]
	v_cndmask_b32_e64 v95, v95, v246, s[34:35]
	v_max3_f32 v28, v30, v94, v95
	v_add_u32_e32 v31, 1, v29
	v_cmp_gt_u32_e64 s[40:41], v31, v252
	v_cndmask_b32_e64 v44, v44, v246, s[38:39]
	v_max_f32_e32 v30, 0xf149f2ca, v44
	v_cndmask_b32_e64 v45, v45, v246, s[40:41]
	v_max_f32_e32 v30, v30, v45
	v_add_u32_e32 v31, 2, v29
	v_cmp_gt_u32_e64 s[42:43], v31, v252
	v_cmp_gt_u32_e64 s[44:45], v52, v252
	s_nop 0
	v_cndmask_b32_e64 v46, v46, v246, s[42:43]
	v_cndmask_b32_e64 v47, v47, v246, s[44:45]
	v_max3_f32 v30, v30, v46, v47
	v_add_u32_e32 v31, 16, v29
	v_add_u32_e32 v52, 17, v29
	v_cmp_gt_u32_e64 s[46:47], v31, v252
	v_cmp_gt_u32_e64 s[48:49], v52, v252
	s_nop 0
	v_cndmask_b32_e64 v20, v20, v246, s[46:47]
	v_cndmask_b32_e64 v21, v21, v246, s[48:49]
	v_max3_f32 v30, v30, v20, v21
	v_add_u32_e32 v31, 18, v29
	v_add_u32_e32 v29, 19, v29
	v_cmp_gt_u32_e64 s[50:51], v31, v252
	v_cmp_gt_u32_e64 s[52:53], v29, v252
	s_nop 0
	v_cndmask_b32_e64 v22, v22, v246, s[50:51]
	v_cndmask_b32_e64 v23, v23, v246, s[52:53]
	v_max3_f32 v29, v30, v22, v23
	v_mov_b32_e32 v30, v28
	v_mov_b32_e32 v31, v28
	s_nop 1
	v_permlane32_swap_b32_e32 v30, v31
	v_max3_f32 v28, v28, v30, v31
	v_mov_b32_e32 v30, v29
	v_mov_b32_e32 v31, v29
	s_nop 1
	v_permlane32_swap_b32_e32 v30, v31
	v_max3_f32 v29, v29, v30, v31
	v_mov_b32_e32 v30, v28
	v_mov_b32_e32 v31, v28
	s_nop 1
	v_permlane16_swap_b32_e32 v30, v31
	v_max_f32_e32 v28, v28, v30
	v_mov_b32_e32 v30, v29
	v_mov_b32_e32 v53, v29
	v_max3_f32 v183, v148, v28, v31
	s_nop 0
	v_permlane16_swap_b32_e32 v30, v53
	v_sub_f32_e32 v28, v148, v183
	v_exp_f32_e32 v52, v28
	v_sub_f32_e32 v28, v88, v183
	v_max_f32_e32 v54, v29, v30
	v_exp_f32_e32 v28, v28
	v_sub_f32_e32 v30, v89, v183
	v_exp_f32_e32 v30, v30
	v_sub_f32_e32 v31, v90, v183
	v_exp_f32_e32 v31, v31
	v_sub_f32_e32 v55, v91, v183
	v_max3_f32 v185, v150, v54, v53
	v_exp_f32_e32 v55, v55
	v_sub_f32_e32 v88, v92, v183
	v_sub_f32_e32 v44, v44, v185
	v_exp_f32_e32 v88, v88
	v_sub_f32_e32 v89, v93, v183
	v_exp_f32_e32 v44, v44
	v_sub_f32_e32 v45, v45, v185
	v_add_f32_e32 v29, 0, v28
	v_exp_f32_e32 v89, v89
	v_sub_f32_e32 v90, v94, v183
	v_exp_f32_e32 v45, v45
	v_sub_f32_e32 v46, v46, v185
	v_add_f32_e32 v29, v30, v29
	v_exp_f32_e32 v90, v90
	v_sub_f32_e32 v91, v95, v183
	v_exp_f32_e32 v46, v46
	v_sub_f32_e32 v47, v47, v185
	v_add_f32_e32 v29, v31, v29
	v_exp_f32_e32 v91, v91
	v_exp_f32_e32 v47, v47
	v_sub_f32_e32 v20, v20, v185
	v_add_f32_e32 v29, v55, v29
	v_sub_f32_e32 v53, v150, v185
	v_exp_f32_e32 v20, v20
	v_sub_f32_e32 v21, v21, v185
	v_add_f32_e32 v29, v88, v29
	v_exp_f32_e32 v54, v53
	v_add_f32_e32 v53, 0, v44
	v_exp_f32_e32 v21, v21
	v_add_f32_e32 v29, v89, v29
	v_add_f32_e32 v53, v45, v53
	v_add_f32_e32 v29, v90, v29
	v_add_f32_e32 v53, v46, v53
	v_add_f32_e32 v184, v91, v29
	v_cvt_pk_bf16_f32 v29, v31, v55
	v_add_f32_e32 v53, v47, v53
	v_cndmask_b32_e64 v55, v20, 0, s[46:47]
	v_add_f32_e32 v20, v55, v53
	v_cndmask_b32_e64 v53, v21, 0, s[48:49]
	v_sub_f32_e32 v21, v22, v185
	v_exp_f32_e32 v21, v21
	v_cvt_pk_bf16_f32 v28, v28, v30
	v_cvt_pk_bf16_f32 v30, v88, v89
	v_add_f32_e32 v20, v53, v20
	v_cndmask_b32_e64 v88, v21, 0, s[50:51]
	v_sub_f32_e32 v21, v23, v185
	v_exp_f32_e32 v21, v21
	v_add_f32_e32 v20, v88, v20
	v_cvt_pk_bf16_f32 v31, v90, v91
	v_cvt_pk_bf16_f32 v22, v55, v53
	v_cndmask_b32_e64 v23, v21, 0, s[52:53]
	v_add_f32_e32 v186, v23, v20
	v_cvt_pk_bf16_f32 v20, v44, v45
	v_cvt_pk_bf16_f32 v21, v46, v47
	v_pk_mul_f32 v[46:47], v[82:83], v[52:53] op_sel_hi:[1,0]
	v_pk_mul_f32 v[44:45], v[80:81], v[52:53] op_sel_hi:[1,0]
	v_cvt_pk_bf16_f32 v23, v88, v23
	v_fmac_f32_e32 v184, v149, v52
	s_waitcnt lgkmcnt(10)
	v_mfma_f32_16x16x32_bf16 v[120:123], v[132:135], v[28:31], v[44:47]
	v_fmac_f32_e32 v186, v151, v54
	s_nop 1
	v_pk_mul_f32 v[46:47], v[86:87], v[54:55] op_sel_hi:[1,0]
	v_pk_mul_f32 v[44:45], v[84:85], v[54:55] op_sel_hi:[1,0]
	s_nop 1
	v_mfma_f32_16x16x32_bf16 v[124:127], v[132:135], v[20:23], v[44:47]
	s_nop 2
	v_mul_f32_e64 v46, v98, v52
	v_mul_f32_e64 v47, v99, v52
	v_pk_mul_f32 v[44:45], v[96:97], v[52:53] op_sel_hi:[1,0]
	s_waitcnt lgkmcnt(8)
	s_nop 0
	v_mfma_f32_16x16x32_bf16 v[96:99], v[128:131], v[28:31], v[44:47]
	s_nop 2
	v_mul_f32_e64 v46, v102, v54
	v_mul_f32_e64 v47, v103, v54
	v_pk_mul_f32 v[44:45], v[100:101], v[54:55] op_sel_hi:[1,0]
	s_nop 1
	v_mfma_f32_16x16x32_bf16 v[128:131], v[128:131], v[20:23], v[44:47]
	s_nop 2
	v_mul_f32_e64 v46, v106, v52
	v_mul_f32_e64 v47, v107, v52
	v_pk_mul_f32 v[44:45], v[104:105], v[52:53] op_sel_hi:[1,0]
	s_waitcnt lgkmcnt(6)
	s_nop 0
	v_mfma_f32_16x16x32_bf16 v[132:135], v[136:139], v[28:31], v[44:47]
	s_nop 2
	v_mul_f32_e64 v46, v110, v54
	v_mul_f32_e64 v47, v111, v54
	v_pk_mul_f32 v[44:45], v[108:109], v[54:55] op_sel_hi:[1,0]
	s_nop 1
	v_mfma_f32_16x16x32_bf16 v[136:139], v[136:139], v[20:23], v[44:47]
	s_nop 2
	v_mul_f32_e64 v46, v114, v52
	v_mul_f32_e64 v47, v115, v52
	v_pk_mul_f32 v[44:45], v[112:113], v[52:53] op_sel_hi:[1,0]
	s_waitcnt lgkmcnt(4)
	s_nop 0
	v_mfma_f32_16x16x32_bf16 v[140:143], v[144:147], v[28:31], v[44:47]
	v_mul_f32_e64 v30, v118, v54
	v_mul_f32_e64 v31, v119, v54
	v_pk_mul_f32 v[28:29], v[116:117], v[54:55] op_sel_hi:[1,0]
	s_nop 1
	v_mfma_f32_16x16x32_bf16 v[144:147], v[144:147], v[20:23], v[28:31]
	v_lshl_add_u32 v20, v155, 1, v155
	v_add_u32_e32 v20, v180, v20
	v_med3_i32 v20, v20, 0, s75
	v_lshl_add_u32 v20, v20, 9, v152
	global_load_dwordx4 v[80:83], v20, s[98:99]
	v_lshl_add_u32 v20, v172, 1, v172
	v_add_u32_e32 v20, v179, v20
	v_med3_i32 v20, v20, 0, s75
	v_lshl_add_u32 v20, v20, 9, v152
	global_load_dwordx4 v[84:87], v20, s[98:99]
	v_lshl_add_u32 v20, v173, 1, v173
	v_add_u32_e32 v20, v178, v20
	v_med3_i32 v20, v20, 0, s75
	v_lshl_add_u32 v20, v20, 9, v152
	global_load_dwordx4 v[88:91], v20, s[98:99]
	v_lshl_add_u32 v20, v182, 1, v182
	v_add_u32_e32 v20, v177, v20
	v_med3_i32 v20, v20, 0, s75
	v_lshl_add_u32 v20, v20, 9, v152
	global_load_dwordx4 v[92:95], v20, s[98:99]
	v_or_b32_e32 v20, 0x100, v209
	v_add_u32_e32 v20, s76, v20
	v_med3_i32 v20, v20, 0, s75
	v_lshl_add_u32 v20, v20, 9, v158
	global_load_dwordx4 v[52:55], v20, s[100:101]
	global_load_dwordx4 v[44:47], v20, s[100:101] offset:64
	v_or_b32_e32 v20, 0x140, v209
	v_add_u32_e32 v20, s76, v20
	v_med3_i32 v20, v20, 0, s75
	v_lshl_add_u32 v20, v20, 9, v158
	global_load_dwordx4 v[28:31], v20, s[100:101]
	s_nop 0
	global_load_dwordx4 v[20:23], v20, s[100:101] offset:64
	ds_read_b64_tr_b16 v[102:103], v169 offset:2304
	ds_read_b64_tr_b16 v[100:101], v169
	ds_read_b64_tr_b16 v[108:109], v169 offset:32
	ds_read_b64_tr_b16 v[110:111], v169 offset:2336
	ds_read_b64_tr_b16 v[116:117], v169 offset:64
	ds_read_b64_tr_b16 v[118:119], v169 offset:2368
	ds_read_b64_tr_b16 v[148:149], v169 offset:96
	ds_read_b64_tr_b16 v[150:151], v169 offset:2400
	s_waitcnt vmcnt(15)
	ds_write_b128 v241, v[64:67] offset:4608
	s_waitcnt vmcnt(14)
	ds_write_b128 v242, v[68:71] offset:4608
	s_waitcnt vmcnt(13)
	ds_write_b128 v243, v[72:75] offset:4608
	s_waitcnt vmcnt(12)
	ds_write_b128 v244, v[76:79] offset:4608
	v_mfma_f32_16x16x32_bf16 v[64:67], v[48:51], v[4:7], 0
	v_mfma_f32_16x16x32_bf16 v[68:71], v[24:27], v[4:7], 0
	v_mfma_f32_16x16x32_bf16 v[24:27], v[24:27], v[12:15], 0
	v_mfma_f32_16x16x32_bf16 v[64:67], v[40:43], v[8:11], v[64:67]
	v_mfma_f32_16x16x32_bf16 v[68:71], v[16:19], v[8:11], v[68:71]
	v_mfma_f32_16x16x32_bf16 v[16:19], v[16:19], v[0:3], v[24:27]
	s_nop 4
	v_sub_u32_e32 v24, v192, v176
	v_mfma_f32_16x16x32_bf16 v[48:51], v[48:51], v[12:15], 0
	v_add_u32_e32 v27, 1, v24
	v_cmp_gt_u32_e64 s[0:1], v27, v175
	v_cmp_gt_u32_e32 vcc, v24, v175
	s_nop 0
	v_cndmask_b32_e64 v65, v65, v246, s[0:1]
	s_nop 0
	v_cndmask_b32_e32 v64, v64, v246, vcc
	v_max_f32_e32 v26, 0xf149f2ca, v64
	v_mfma_f32_16x16x32_bf16 v[40:43], v[40:43], v[0:3], v[48:51]
	v_max_f32_e32 v26, v26, v65
	v_add_u32_e32 v27, 2, v24
	v_cmp_gt_u32_e64 s[22:23], v27, v175
	v_add_u32_e32 v48, 3, v24
	v_cmp_gt_u32_e64 s[24:25], v48, v175
	v_cndmask_b32_e64 v66, v66, v246, s[22:23]
	v_sub_u32_e32 v25, v192, v181
	v_cndmask_b32_e64 v67, v67, v246, s[24:25]
	v_max3_f32 v26, v26, v66, v67
	v_add_u32_e32 v27, 16, v24
	v_add_u32_e32 v48, 17, v24
	v_cmp_gt_u32_e64 s[26:27], v27, v175
	v_cmp_gt_u32_e64 s[28:29], v48, v175
	v_cmp_gt_u32_e64 s[38:39], v25, v252
	v_cndmask_b32_e64 v68, v68, v246, s[26:27]
	v_cndmask_b32_e64 v69, v69, v246, s[28:29]
	v_max3_f32 v26, v26, v68, v69
	v_add_u32_e32 v27, 18, v24
	v_add_u32_e32 v24, 19, v24
	v_cmp_gt_u32_e64 s[30:31], v27, v175
	v_cmp_gt_u32_e64 s[34:35], v24, v175
	v_add_u32_e32 v48, 3, v25
	v_cndmask_b32_e64 v70, v70, v246, s[30:31]
	v_cndmask_b32_e64 v71, v71, v246, s[34:35]
	v_max3_f32 v24, v26, v70, v71
	v_add_u32_e32 v27, 1, v25
	v_cmp_gt_u32_e64 s[40:41], v27, v252
	v_cndmask_b32_e64 v40, v40, v246, s[38:39]
	v_max_f32_e32 v26, 0xf149f2ca, v40
	v_cndmask_b32_e64 v41, v41, v246, s[40:41]
	v_max_f32_e32 v26, v26, v41
	v_add_u32_e32 v27, 2, v25
	v_cmp_gt_u32_e64 s[42:43], v27, v252
	v_cmp_gt_u32_e64 s[44:45], v48, v252
	s_nop 0
	v_cndmask_b32_e64 v42, v42, v246, s[42:43]
	v_cndmask_b32_e64 v43, v43, v246, s[44:45]
	v_max3_f32 v26, v26, v42, v43
	v_add_u32_e32 v27, 16, v25
	v_add_u32_e32 v48, 17, v25
	v_cmp_gt_u32_e64 s[46:47], v27, v252
	v_cmp_gt_u32_e64 s[48:49], v48, v252
	s_nop 0
	v_cndmask_b32_e64 v16, v16, v246, s[46:47]
	v_cndmask_b32_e64 v17, v17, v246, s[48:49]
	v_max3_f32 v26, v26, v16, v17
	v_add_u32_e32 v27, 18, v25
	v_add_u32_e32 v25, 19, v25
	v_cmp_gt_u32_e64 s[50:51], v27, v252
	v_cmp_gt_u32_e64 s[52:53], v25, v252
	s_nop 0
	v_cndmask_b32_e64 v18, v18, v246, s[50:51]
	v_cndmask_b32_e64 v19, v19, v246, s[52:53]
	v_max3_f32 v25, v26, v18, v19
	v_mov_b32_e32 v26, v24
	v_mov_b32_e32 v27, v24
	s_nop 1
	v_permlane32_swap_b32_e32 v26, v27
	v_max3_f32 v24, v24, v26, v27
	v_mov_b32_e32 v26, v25
	v_mov_b32_e32 v27, v25
	s_nop 1
	v_permlane32_swap_b32_e32 v26, v27
	v_max3_f32 v25, v25, v26, v27
	v_mov_b32_e32 v26, v24
	v_mov_b32_e32 v27, v24
	s_nop 1
	v_permlane16_swap_b32_e32 v26, v27
	v_max_f32_e32 v24, v24, v26
	v_max3_f32 v177, v183, v24, v27
	v_sub_f32_e32 v48, v66, v177
	v_exp_f32_e32 v48, v48
	v_sub_f32_e32 v24, v183, v177
	v_exp_f32_e32 v72, v24
	v_sub_f32_e32 v24, v64, v177
	v_cndmask_b32_e64 v49, v48, 0, s[22:23]
	v_sub_f32_e32 v48, v67, v177
	v_exp_f32_e32 v48, v48
	v_exp_f32_e32 v24, v24
	v_sub_f32_e32 v27, v65, v177
	v_exp_f32_e32 v27, v27
	v_cndmask_b32_e64 v50, v48, 0, s[24:25]
	v_sub_f32_e32 v48, v68, v177
	v_exp_f32_e32 v48, v48
	v_mov_b32_e32 v26, v25
	v_mov_b32_e32 v73, v25
	s_nop 1
	v_permlane16_swap_b32_e32 v26, v73
	v_cndmask_b32_e64 v51, v48, 0, s[26:27]
	v_sub_f32_e32 v48, v69, v177
	v_exp_f32_e32 v48, v48
	v_max_f32_e32 v25, v25, v26
	v_cndmask_b32_e64 v64, v48, 0, s[28:29]
	v_sub_f32_e32 v48, v70, v177
	v_exp_f32_e32 v48, v48
	v_add_f32_e32 v26, 0, v24
	v_add_f32_e32 v26, v27, v26
	v_cndmask_b32_e64 v65, v48, 0, s[30:31]
	v_sub_f32_e32 v48, v71, v177
	v_exp_f32_e32 v48, v48
	v_add_f32_e32 v26, v49, v26
	v_add_f32_e32 v26, v50, v26
	v_add_f32_e32 v26, v51, v26
	v_max3_f32 v179, v185, v25, v73
	v_add_f32_e32 v26, v64, v26
	v_cndmask_b32_e64 v66, v48, 0, s[34:35]
	v_cvt_pk_bf16_f32 v48, v24, v27
	v_sub_f32_e32 v24, v185, v179
	v_add_f32_e32 v26, v65, v26
	v_cvt_pk_bf16_f32 v49, v49, v50
	v_cvt_pk_bf16_f32 v50, v51, v64
	v_exp_f32_e32 v64, v24
	v_sub_f32_e32 v24, v40, v179
	v_add_f32_e32 v178, v66, v26
	v_exp_f32_e32 v24, v24
	v_sub_f32_e32 v26, v41, v179
	v_exp_f32_e32 v26, v26
	v_sub_f32_e32 v27, v42, v179
	v_exp_f32_e32 v27, v27
	v_sub_f32_e32 v40, v43, v179
	v_exp_f32_e32 v40, v40
	v_sub_f32_e32 v16, v16, v179
	v_exp_f32_e32 v16, v16
	v_sub_f32_e32 v17, v17, v179
	v_add_f32_e32 v25, 0, v24
	v_exp_f32_e32 v17, v17
	v_add_f32_e32 v25, v26, v25
	v_add_f32_e32 v25, v27, v25
	v_add_f32_e32 v25, v40, v25
	v_cndmask_b32_e64 v41, v16, 0, s[46:47]
	v_add_f32_e32 v16, v41, v25
	v_cndmask_b32_e64 v25, v17, 0, s[48:49]
	v_sub_f32_e32 v17, v18, v179
	v_exp_f32_e32 v17, v17
	v_add_f32_e32 v16, v25, v16
	v_cvt_pk_bf16_f32 v51, v65, v66
	v_cvt_pk_bf16_f32 v18, v41, v25
	v_cndmask_b32_e64 v42, v17, 0, s[50:51]
	v_sub_f32_e32 v17, v19, v179
	v_exp_f32_e32 v17, v17
	v_add_f32_e32 v16, v42, v16
	v_fmac_f32_e32 v178, v184, v72
	v_cndmask_b32_e64 v19, v17, 0, s[52:53]
	v_add_f32_e32 v180, v19, v16
	v_cvt_pk_bf16_f32 v16, v24, v26
	v_cvt_pk_bf16_f32 v17, v27, v40
	v_cvt_pk_bf16_f32 v19, v42, v19
	v_pk_mul_f32 v[26:27], v[122:123], v[72:73] op_sel_hi:[1,0]
	v_pk_mul_f32 v[24:25], v[120:121], v[72:73] op_sel_hi:[1,0]
	v_pk_mul_f32 v[42:43], v[126:127], v[64:65] op_sel_hi:[1,0]
	v_pk_mul_f32 v[40:41], v[124:125], v[64:65] op_sel_hi:[1,0]
	s_waitcnt lgkmcnt(10)
	v_mfma_f32_16x16x32_bf16 v[24:27], v[100:103], v[48:51], v[24:27]
	v_fmac_f32_e32 v180, v186, v64
	v_mfma_f32_16x16x32_bf16 v[100:103], v[100:103], v[16:19], v[40:43]
	s_nop 2
	v_mul_f32_e64 v42, v98, v72
	v_mul_f32_e64 v43, v99, v72
	v_pk_mul_f32 v[40:41], v[96:97], v[72:73] op_sel_hi:[1,0]
	s_waitcnt lgkmcnt(8)
	s_nop 0
	v_mfma_f32_16x16x32_bf16 v[104:107], v[108:111], v[48:51], v[40:43]
	s_nop 2
	v_mul_f32_e64 v42, v130, v64
	v_mul_f32_e64 v43, v131, v64
	v_pk_mul_f32 v[40:41], v[128:129], v[64:65] op_sel_hi:[1,0]
	s_nop 1
	v_mfma_f32_16x16x32_bf16 v[108:111], v[108:111], v[16:19], v[40:43]
	s_nop 2
	v_mul_f32_e64 v42, v134, v72
	v_mul_f32_e64 v43, v135, v72
	v_pk_mul_f32 v[40:41], v[132:133], v[72:73] op_sel_hi:[1,0]
	s_waitcnt lgkmcnt(6)
	s_nop 0
	v_mfma_f32_16x16x32_bf16 v[112:115], v[116:119], v[48:51], v[40:43]
	s_nop 2
	v_mul_f32_e64 v42, v138, v64
	v_mul_f32_e64 v43, v139, v64
	v_pk_mul_f32 v[40:41], v[136:137], v[64:65] op_sel_hi:[1,0]
	s_nop 1
	v_mfma_f32_16x16x32_bf16 v[116:119], v[116:119], v[16:19], v[40:43]
	s_nop 2
	v_mul_f32_e64 v42, v142, v72
	v_mul_f32_e64 v43, v143, v72
	v_pk_mul_f32 v[40:41], v[140:141], v[72:73] op_sel_hi:[1,0]
	s_waitcnt lgkmcnt(4)
	s_nop 0
	v_mfma_f32_16x16x32_bf16 v[120:123], v[148:151], v[48:51], v[40:43]
	s_nop 2
	v_mul_f32_e64 v42, v146, v64
	v_mul_f32_e64 v43, v147, v64
	v_pk_mul_f32 v[40:41], v[144:145], v[64:65] op_sel_hi:[1,0]
	s_nop 1
	v_mfma_f32_16x16x32_bf16 v[124:127], v[148:151], v[16:19], v[40:43]
	v_lshlrev_b32_e32 v16, 2, v196
	v_add_u32_e32 v16, s76, v16
	v_med3_i32 v16, v16, 0, s75
	v_lshl_add_u32 v16, v16, 9, v152
	global_load_dwordx4 v[68:71], v16, s[98:99]
	v_lshlrev_b32_e32 v16, 2, v168
	v_add_u32_e32 v16, s76, v16
	v_med3_i32 v16, v16, 0, s75
	v_lshl_add_u32 v16, v16, 9, v152
	global_load_dwordx4 v[72:75], v16, s[98:99]
	v_lshlrev_b32_e32 v16, 2, v193
	v_add_u32_e32 v16, s76, v16
	v_med3_i32 v16, v16, 0, s75
	v_lshl_add_u32 v16, v16, 9, v152
	global_load_dwordx4 v[76:79], v16, s[98:99]
	v_lshlrev_b32_e32 v16, 2, v194
	v_add_u32_e32 v16, s76, v16
	v_med3_i32 v16, v16, 0, s75
	v_lshl_add_u32 v16, v16, 9, v152
	global_load_dwordx4 v[96:99], v16, s[98:99]
	v_or_b32_e32 v16, 0x180, v209
	v_add_u32_e32 v16, s76, v16
	v_med3_i32 v16, v16, 0, s75
	v_lshl_add_u32 v16, v16, 9, v158
	global_load_dwordx4 v[64:67], v16, s[100:101]
	global_load_dwordx4 v[48:51], v16, s[100:101] offset:64
	v_or_b32_e32 v16, 0x1c0, v209
	v_add_u32_e32 v16, s76, v16
	v_med3_i32 v16, v16, 0, s75
	v_lshl_add_u32 v16, v16, 9, v158
	global_load_dwordx4 v[40:43], v16, s[100:101]
	s_nop 0
	global_load_dwordx4 v[16:19], v16, s[100:101] offset:64
	ds_read_b64_tr_b16 v[142:143], v169 offset:6912
	ds_read_b64_tr_b16 v[140:141], v169 offset:4608
	ds_read_b64_tr_b16 v[136:137], v169 offset:4640
	ds_read_b64_tr_b16 v[138:139], v169 offset:6944
	ds_read_b64_tr_b16 v[132:133], v169 offset:4672
	ds_read_b64_tr_b16 v[134:135], v169 offset:6976
	ds_read_b64_tr_b16 v[128:129], v169 offset:4704
	ds_read_b64_tr_b16 v[130:131], v169 offset:7008
	s_waitcnt vmcnt(15)
	ds_write_b128 v241, v[80:83]
	s_waitcnt vmcnt(14)
	ds_write_b128 v242, v[84:87]
	s_waitcnt vmcnt(13)
	ds_write_b128 v243, v[88:91]
	s_waitcnt vmcnt(12)
	ds_write_b128 v244, v[92:95]
	v_mfma_f32_16x16x32_bf16 v[80:83], v[60:63], v[4:7], 0
	v_mfma_f32_16x16x32_bf16 v[84:87], v[36:39], v[4:7], 0
	v_mfma_f32_16x16x32_bf16 v[36:39], v[36:39], v[12:15], 0
	v_mfma_f32_16x16x32_bf16 v[80:83], v[56:59], v[8:11], v[80:83]
	v_mfma_f32_16x16x32_bf16 v[84:87], v[32:35], v[8:11], v[84:87]
	v_mfma_f32_16x16x32_bf16 v[32:35], v[32:35], v[0:3], v[36:39]
	s_nop 4
	v_sub_u32_e32 v36, v197, v176
	v_mfma_f32_16x16x32_bf16 v[60:63], v[60:63], v[12:15], 0
	v_add_u32_e32 v39, 1, v36
	v_cmp_gt_u32_e64 s[0:1], v39, v175
	v_cmp_gt_u32_e32 vcc, v36, v175
	s_nop 0
	v_cndmask_b32_e64 v81, v81, v246, s[0:1]
	s_nop 0
	v_cndmask_b32_e32 v80, v80, v246, vcc
	v_max_f32_e32 v38, 0xf149f2ca, v80
	v_mfma_f32_16x16x32_bf16 v[56:59], v[56:59], v[0:3], v[60:63]
	v_max_f32_e32 v38, v38, v81
	v_add_u32_e32 v39, 2, v36
	v_cmp_gt_u32_e64 s[22:23], v39, v175
	v_add_u32_e32 v60, 3, v36
	v_cmp_gt_u32_e64 s[24:25], v60, v175
	v_cndmask_b32_e64 v82, v82, v246, s[22:23]
	v_sub_u32_e32 v37, v197, v181
	v_cndmask_b32_e64 v83, v83, v246, s[24:25]
	v_max3_f32 v38, v38, v82, v83
	v_add_u32_e32 v39, 16, v36
	v_add_u32_e32 v60, 17, v36
	v_cmp_gt_u32_e64 s[26:27], v39, v175
	v_cmp_gt_u32_e64 s[28:29], v60, v175
	v_cmp_gt_u32_e64 s[38:39], v37, v252
	v_cndmask_b32_e64 v84, v84, v246, s[26:27]
	v_cndmask_b32_e64 v85, v85, v246, s[28:29]
	v_max3_f32 v38, v38, v84, v85
	v_add_u32_e32 v39, 18, v36
	v_add_u32_e32 v36, 19, v36
	v_cmp_gt_u32_e64 s[30:31], v39, v175
	v_cmp_gt_u32_e64 s[34:35], v36, v175
	v_add_u32_e32 v60, 3, v37
	v_cndmask_b32_e64 v86, v86, v246, s[30:31]
	v_cndmask_b32_e64 v87, v87, v246, s[34:35]
	v_max3_f32 v36, v38, v86, v87
	v_add_u32_e32 v39, 1, v37
	v_cmp_gt_u32_e64 s[40:41], v39, v252
	v_cndmask_b32_e64 v56, v56, v246, s[38:39]
	v_max_f32_e32 v38, 0xf149f2ca, v56
	v_cndmask_b32_e64 v57, v57, v246, s[40:41]
	v_max_f32_e32 v38, v38, v57
	v_add_u32_e32 v39, 2, v37
	v_cmp_gt_u32_e64 s[42:43], v39, v252
	v_cmp_gt_u32_e64 s[44:45], v60, v252
	s_nop 0
	v_cndmask_b32_e64 v58, v58, v246, s[42:43]
	v_cndmask_b32_e64 v59, v59, v246, s[44:45]
	v_max3_f32 v38, v38, v58, v59
	v_add_u32_e32 v39, 16, v37
	v_add_u32_e32 v60, 17, v37
	v_cmp_gt_u32_e64 s[46:47], v39, v252
	v_cmp_gt_u32_e64 s[48:49], v60, v252
	s_nop 0
	v_cndmask_b32_e64 v32, v32, v246, s[46:47]
	v_cndmask_b32_e64 v33, v33, v246, s[48:49]
	v_max3_f32 v38, v38, v32, v33
	v_add_u32_e32 v39, 18, v37
	v_add_u32_e32 v37, 19, v37
	v_cmp_gt_u32_e64 s[50:51], v39, v252
	v_cmp_gt_u32_e64 s[52:53], v37, v252
	s_nop 0
	v_cndmask_b32_e64 v34, v34, v246, s[50:51]
	v_cndmask_b32_e64 v35, v35, v246, s[52:53]
	v_max3_f32 v37, v38, v34, v35
	v_mov_b32_e32 v38, v36
	v_mov_b32_e32 v39, v36
	s_nop 1
	v_permlane32_swap_b32_e32 v38, v39
	v_max3_f32 v36, v36, v38, v39
	v_mov_b32_e32 v38, v37
	v_mov_b32_e32 v39, v37
	s_nop 1
	v_permlane32_swap_b32_e32 v38, v39
	v_max3_f32 v37, v37, v38, v39
	v_mov_b32_e32 v38, v36
	v_mov_b32_e32 v39, v36
	s_nop 1
	v_permlane16_swap_b32_e32 v38, v39
	v_max_f32_e32 v36, v36, v38
	v_mov_b32_e32 v38, v37
	v_mov_b32_e32 v61, v37
	v_max3_f32 v144, v177, v36, v39
	s_nop 0
	v_permlane16_swap_b32_e32 v38, v61
	v_sub_f32_e32 v36, v177, v144
	v_exp_f32_e32 v60, v36
	v_sub_f32_e32 v36, v80, v144
	v_max_f32_e32 v62, v37, v38
	v_exp_f32_e32 v36, v36
	v_sub_f32_e32 v38, v81, v144
	v_exp_f32_e32 v38, v38
	v_sub_f32_e32 v39, v82, v144
	v_exp_f32_e32 v39, v39
	v_sub_f32_e32 v63, v83, v144
	v_max3_f32 v146, v179, v62, v61
	v_exp_f32_e32 v63, v63
	v_sub_f32_e32 v80, v84, v144
	v_sub_f32_e32 v56, v56, v146
	v_exp_f32_e32 v80, v80
	v_sub_f32_e32 v81, v85, v144
	v_exp_f32_e32 v56, v56
	v_sub_f32_e32 v57, v57, v146
	v_add_f32_e32 v37, 0, v36
	v_exp_f32_e32 v81, v81
	v_sub_f32_e32 v82, v86, v144
	v_exp_f32_e32 v57, v57
	v_sub_f32_e32 v58, v58, v146
	v_add_f32_e32 v37, v38, v37
	v_exp_f32_e32 v82, v82
	v_sub_f32_e32 v83, v87, v144
	v_exp_f32_e32 v58, v58
	v_sub_f32_e32 v59, v59, v146
	v_add_f32_e32 v37, v39, v37
	v_exp_f32_e32 v83, v83
	v_exp_f32_e32 v59, v59
	v_sub_f32_e32 v32, v32, v146
	v_add_f32_e32 v37, v63, v37
	v_sub_f32_e32 v61, v179, v146
	v_exp_f32_e32 v32, v32
	v_sub_f32_e32 v33, v33, v146
	v_add_f32_e32 v37, v80, v37
	v_exp_f32_e32 v62, v61
	v_add_f32_e32 v61, 0, v56
	v_exp_f32_e32 v33, v33
	v_add_f32_e32 v37, v81, v37
	v_add_f32_e32 v61, v57, v61
	v_add_f32_e32 v37, v82, v37
	v_add_f32_e32 v61, v58, v61
	v_add_f32_e32 v145, v83, v37
	v_cvt_pk_bf16_f32 v37, v39, v63
	v_add_f32_e32 v61, v59, v61
	v_cndmask_b32_e64 v63, v32, 0, s[46:47]
	v_add_f32_e32 v32, v63, v61
	v_cndmask_b32_e64 v61, v33, 0, s[48:49]
	v_sub_f32_e32 v33, v34, v146
	v_exp_f32_e32 v33, v33
	v_cvt_pk_bf16_f32 v36, v36, v38
	v_cvt_pk_bf16_f32 v38, v80, v81
	v_add_f32_e32 v32, v61, v32
	v_cndmask_b32_e64 v80, v33, 0, s[50:51]
	v_sub_f32_e32 v33, v35, v146
	v_exp_f32_e32 v33, v33
	v_cvt_pk_bf16_f32 v39, v82, v83
	v_add_f32_e32 v32, v80, v32
	v_pk_mul_f32 v[26:27], v[26:27], v[60:61] op_sel_hi:[1,0]
	v_cndmask_b32_e64 v35, v33, 0, s[52:53]
	v_pk_mul_f32 v[24:25], v[24:25], v[60:61] op_sel_hi:[1,0]
	v_add_f32_e32 v147, v35, v32
	v_cvt_pk_bf16_f32 v32, v56, v57
	v_cvt_pk_bf16_f32 v33, v58, v59
	v_cvt_pk_bf16_f32 v34, v63, v61
	v_cvt_pk_bf16_f32 v35, v80, v35
	s_waitcnt lgkmcnt(10)
	v_mfma_f32_16x16x32_bf16 v[92:95], v[140:143], v[36:39], v[24:27]
	v_fmac_f32_e32 v145, v178, v60
	v_fmac_f32_e32 v147, v180, v62
	s_nop 0
	v_pk_mul_f32 v[26:27], v[102:103], v[62:63] op_sel_hi:[1,0]
	v_pk_mul_f32 v[24:25], v[100:101], v[62:63] op_sel_hi:[1,0]
	s_nop 1
	v_mfma_f32_16x16x32_bf16 v[100:103], v[140:143], v[32:35], v[24:27]
	s_nop 2
	v_mul_f32_e64 v26, v106, v60
	v_mul_f32_e64 v27, v107, v60
	v_pk_mul_f32 v[24:25], v[104:105], v[60:61] op_sel_hi:[1,0]
	s_waitcnt lgkmcnt(8)
	s_nop 0
	v_mfma_f32_16x16x32_bf16 v[104:107], v[136:139], v[36:39], v[24:27]
	s_nop 2
	v_mul_f32_e64 v26, v110, v62
	v_mul_f32_e64 v27, v111, v62
	v_pk_mul_f32 v[24:25], v[108:109], v[62:63] op_sel_hi:[1,0]
	s_nop 1
	v_mfma_f32_16x16x32_bf16 v[108:111], v[136:139], v[32:35], v[24:27]
	s_nop 2
	v_mul_f32_e64 v26, v114, v60
	v_mul_f32_e64 v27, v115, v60
	v_pk_mul_f32 v[24:25], v[112:113], v[60:61] op_sel_hi:[1,0]
	s_waitcnt lgkmcnt(6)
	s_nop 0
	v_mfma_f32_16x16x32_bf16 v[112:115], v[132:135], v[36:39], v[24:27]
	s_nop 2
	v_mul_f32_e64 v26, v118, v62
	v_mul_f32_e64 v27, v119, v62
	v_pk_mul_f32 v[24:25], v[116:117], v[62:63] op_sel_hi:[1,0]
	s_nop 1
	v_mfma_f32_16x16x32_bf16 v[116:119], v[132:135], v[32:35], v[24:27]
	s_nop 2
	v_mul_f32_e64 v26, v122, v60
	v_mul_f32_e64 v27, v123, v60
	v_pk_mul_f32 v[24:25], v[120:121], v[60:61] op_sel_hi:[1,0]
	s_waitcnt lgkmcnt(4)
	s_nop 0
	v_mfma_f32_16x16x32_bf16 v[120:123], v[128:131], v[36:39], v[24:27]
	s_nop 2
	v_mul_f32_e64 v26, v126, v62
	v_mul_f32_e64 v27, v127, v62
	v_pk_mul_f32 v[24:25], v[124:125], v[62:63] op_sel_hi:[1,0]
	s_nop 1
	v_mfma_f32_16x16x32_bf16 v[124:127], v[128:131], v[32:35], v[24:27]
	s_nop 2
	v_add_u32_e32 v24, s76, v214
	v_med3_i32 v24, v24, 0, s75
	v_lshl_add_u32 v24, v24, 9, v152
	global_load_dwordx4 v[60:63], v24, s[98:99]
	v_add_u32_e32 v24, s76, v216
	v_med3_i32 v24, v24, 0, s75
	v_lshl_add_u32 v24, v24, 9, v152
	global_load_dwordx4 v[80:83], v24, s[98:99]
	v_add_u32_e32 v24, s76, v218
	v_med3_i32 v24, v24, 0, s75
	v_lshl_add_u32 v24, v24, 9, v152
	global_load_dwordx4 v[84:87], v24, s[98:99]
	v_add_u32_e32 v24, s76, v220
	v_med3_i32 v24, v24, 0, s75
	v_lshl_add_u32 v24, v24, 9, v152
	global_load_dwordx4 v[88:91], v24, s[98:99]
	v_add_u32_e32 v24, s76, v221
	v_med3_i32 v24, v24, 0, s75
	v_lshl_add_u32 v24, v24, 9, v158
	global_load_dwordx4 v[56:59], v24, s[100:101]
	global_load_dwordx4 v[36:39], v24, s[100:101] offset:64
	v_or_b32_e32 v24, 0x100, v221
	v_add_u32_e32 v24, s76, v24
	v_med3_i32 v24, v24, 0, s75
	v_lshl_add_u32 v24, v24, 9, v158
	global_load_dwordx4 v[32:35], v24, s[100:101]
	s_nop 0
	global_load_dwordx4 v[24:27], v24, s[100:101] offset:64
	ds_read_b64_tr_b16 v[142:143], v169 offset:2304
	ds_read_b64_tr_b16 v[140:141], v169
	ds_read_b64_tr_b16 v[136:137], v169 offset:32
	ds_read_b64_tr_b16 v[138:139], v169 offset:2336
	ds_read_b64_tr_b16 v[132:133], v169 offset:64
	ds_read_b64_tr_b16 v[134:135], v169 offset:2368
	ds_read_b64_tr_b16 v[128:129], v169 offset:96
	ds_read_b64_tr_b16 v[130:131], v169 offset:2400
	s_waitcnt vmcnt(15)
	ds_write_b128 v241, v[68:71] offset:4608
	s_waitcnt vmcnt(14)
	ds_write_b128 v242, v[72:75] offset:4608
	s_waitcnt vmcnt(13)
	ds_write_b128 v243, v[76:79] offset:4608
	s_waitcnt vmcnt(12)
	ds_write_b128 v244, v[96:99] offset:4608
	v_mfma_f32_16x16x32_bf16 v[68:71], v[52:55], v[4:7], 0
	v_mfma_f32_16x16x32_bf16 v[72:75], v[28:31], v[4:7], 0
	v_mfma_f32_16x16x32_bf16 v[28:31], v[28:31], v[12:15], 0
	v_mfma_f32_16x16x32_bf16 v[68:71], v[44:47], v[8:11], v[68:71]
	v_mfma_f32_16x16x32_bf16 v[72:75], v[20:23], v[8:11], v[72:75]
	v_mfma_f32_16x16x32_bf16 v[20:23], v[20:23], v[0:3], v[28:31]
	s_nop 4
	v_sub_u32_e32 v28, v198, v176
	v_mfma_f32_16x16x32_bf16 v[52:55], v[52:55], v[12:15], 0
	v_add_u32_e32 v31, 1, v28
	v_cmp_gt_u32_e64 s[0:1], v31, v175
	v_cmp_gt_u32_e32 vcc, v28, v175
	s_nop 0
	v_cndmask_b32_e64 v69, v69, v246, s[0:1]
	s_nop 0
	v_cndmask_b32_e32 v68, v68, v246, vcc
	v_max_f32_e32 v30, 0xf149f2ca, v68
	v_mfma_f32_16x16x32_bf16 v[44:47], v[44:47], v[0:3], v[52:55]
	v_max_f32_e32 v30, v30, v69
	v_add_u32_e32 v31, 2, v28
	v_cmp_gt_u32_e64 s[22:23], v31, v175
	v_add_u32_e32 v52, 3, v28
	v_cmp_gt_u32_e64 s[24:25], v52, v175
	v_cndmask_b32_e64 v70, v70, v246, s[22:23]
	v_sub_u32_e32 v29, v198, v181
	v_cndmask_b32_e64 v71, v71, v246, s[24:25]
	v_max3_f32 v30, v30, v70, v71
	v_add_u32_e32 v31, 16, v28
	v_add_u32_e32 v52, 17, v28
	v_cmp_gt_u32_e64 s[26:27], v31, v175
	v_cmp_gt_u32_e64 s[28:29], v52, v175
	v_cmp_gt_u32_e64 s[38:39], v29, v252
	v_cndmask_b32_e64 v72, v72, v246, s[26:27]
	v_cndmask_b32_e64 v73, v73, v246, s[28:29]
	v_max3_f32 v30, v30, v72, v73
	v_add_u32_e32 v31, 18, v28
	v_add_u32_e32 v28, 19, v28
	v_cmp_gt_u32_e64 s[30:31], v31, v175
	v_cmp_gt_u32_e64 s[34:35], v28, v175
	v_add_u32_e32 v52, 3, v29
	v_cndmask_b32_e64 v74, v74, v246, s[30:31]
	v_cndmask_b32_e64 v75, v75, v246, s[34:35]
	v_max3_f32 v28, v30, v74, v75
	v_add_u32_e32 v31, 1, v29
	v_cmp_gt_u32_e64 s[40:41], v31, v252
	v_cndmask_b32_e64 v44, v44, v246, s[38:39]
	v_max_f32_e32 v30, 0xf149f2ca, v44
	v_cndmask_b32_e64 v45, v45, v246, s[40:41]
	v_max_f32_e32 v30, v30, v45
	v_add_u32_e32 v31, 2, v29
	v_cmp_gt_u32_e64 s[42:43], v31, v252
	v_cmp_gt_u32_e64 s[44:45], v52, v252
	s_nop 0
	v_cndmask_b32_e64 v46, v46, v246, s[42:43]
	v_cndmask_b32_e64 v47, v47, v246, s[44:45]
	v_max3_f32 v30, v30, v46, v47
	v_add_u32_e32 v31, 16, v29
	v_add_u32_e32 v52, 17, v29
	v_cmp_gt_u32_e64 s[46:47], v31, v252
	v_cmp_gt_u32_e64 s[48:49], v52, v252
	s_nop 0
	v_cndmask_b32_e64 v20, v20, v246, s[46:47]
	v_cndmask_b32_e64 v21, v21, v246, s[48:49]
	v_max3_f32 v30, v30, v20, v21
	v_add_u32_e32 v31, 18, v29
	v_add_u32_e32 v29, 19, v29
	v_cmp_gt_u32_e64 s[50:51], v31, v252
	v_cmp_gt_u32_e64 s[52:53], v29, v252
	s_nop 0
	v_cndmask_b32_e64 v22, v22, v246, s[50:51]
	v_cndmask_b32_e64 v23, v23, v246, s[52:53]
	v_max3_f32 v29, v30, v22, v23
	v_mov_b32_e32 v30, v28
	v_mov_b32_e32 v31, v28
	s_nop 1
	v_permlane32_swap_b32_e32 v30, v31
	v_max3_f32 v28, v28, v30, v31
	v_mov_b32_e32 v30, v29
	v_mov_b32_e32 v31, v29
	s_nop 1
	v_permlane32_swap_b32_e32 v30, v31
	v_max3_f32 v29, v29, v30, v31
	v_mov_b32_e32 v30, v28
	v_mov_b32_e32 v31, v28
	s_nop 1
	v_permlane16_swap_b32_e32 v30, v31
	v_max_f32_e32 v28, v28, v30
	v_mov_b32_e32 v30, v29
	v_mov_b32_e32 v53, v29
	v_max3_f32 v148, v144, v28, v31
	s_nop 0
	v_permlane16_swap_b32_e32 v30, v53
	v_sub_f32_e32 v28, v144, v148
	v_exp_f32_e32 v52, v28
	v_sub_f32_e32 v28, v68, v148
	v_max_f32_e32 v54, v29, v30
	v_exp_f32_e32 v28, v28
	v_sub_f32_e32 v30, v69, v148
	v_exp_f32_e32 v30, v30
	v_sub_f32_e32 v31, v70, v148
	v_exp_f32_e32 v31, v31
	v_sub_f32_e32 v55, v71, v148
	v_max3_f32 v149, v146, v54, v53
	v_exp_f32_e32 v55, v55
	v_sub_f32_e32 v68, v72, v148
	v_sub_f32_e32 v44, v44, v149
	v_exp_f32_e32 v68, v68
	v_sub_f32_e32 v69, v73, v148
	v_exp_f32_e32 v44, v44
	v_sub_f32_e32 v45, v45, v149
	v_add_f32_e32 v29, 0, v28
	v_exp_f32_e32 v69, v69
	v_sub_f32_e32 v70, v74, v148
	v_exp_f32_e32 v45, v45
	v_sub_f32_e32 v46, v46, v149
	v_add_f32_e32 v29, v30, v29
	v_exp_f32_e32 v70, v70
	v_sub_f32_e32 v71, v75, v148
	v_exp_f32_e32 v46, v46
	v_sub_f32_e32 v47, v47, v149
	v_add_f32_e32 v29, v31, v29
	v_exp_f32_e32 v71, v71
	v_exp_f32_e32 v47, v47
	v_sub_f32_e32 v20, v20, v149
	v_add_f32_e32 v29, v55, v29
	v_sub_f32_e32 v53, v146, v149
	v_exp_f32_e32 v20, v20
	v_sub_f32_e32 v21, v21, v149
	v_add_f32_e32 v29, v68, v29
	v_exp_f32_e32 v54, v53
	v_add_f32_e32 v53, 0, v44
	v_exp_f32_e32 v21, v21
	v_add_f32_e32 v29, v69, v29
	v_add_f32_e32 v53, v45, v53
	v_add_f32_e32 v29, v70, v29
	v_add_f32_e32 v53, v46, v53
	v_add_f32_e32 v144, v71, v29
	v_cvt_pk_bf16_f32 v29, v31, v55
	v_add_f32_e32 v53, v47, v53
	v_cndmask_b32_e64 v55, v20, 0, s[46:47]
	v_add_f32_e32 v20, v55, v53
	v_cndmask_b32_e64 v53, v21, 0, s[48:49]
	v_sub_f32_e32 v21, v22, v149
	v_exp_f32_e32 v21, v21
	v_cvt_pk_bf16_f32 v28, v28, v30
	v_cvt_pk_bf16_f32 v30, v68, v69
	v_add_f32_e32 v20, v53, v20
	v_cndmask_b32_e64 v68, v21, 0, s[50:51]
	v_sub_f32_e32 v21, v23, v149
	v_exp_f32_e32 v21, v21
	v_add_f32_e32 v20, v68, v20
	v_fmac_f32_e32 v144, v145, v52
	v_cvt_pk_bf16_f32 v31, v70, v71
	v_cndmask_b32_e64 v23, v21, 0, s[52:53]
	v_add_f32_e32 v145, v23, v20
	v_cvt_pk_bf16_f32 v20, v44, v45
	v_cvt_pk_bf16_f32 v21, v46, v47
	v_pk_mul_f32 v[46:47], v[94:95], v[52:53] op_sel_hi:[1,0]
	v_pk_mul_f32 v[44:45], v[92:93], v[52:53] op_sel_hi:[1,0]
	v_cvt_pk_bf16_f32 v22, v55, v53
	v_cvt_pk_bf16_f32 v23, v68, v23
	s_waitcnt lgkmcnt(10)
	v_mfma_f32_16x16x32_bf16 v[96:99], v[140:143], v[28:31], v[44:47]
	v_fmac_f32_e32 v145, v147, v54
	s_nop 1
	v_pk_mul_f32 v[46:47], v[102:103], v[54:55] op_sel_hi:[1,0]
	v_pk_mul_f32 v[44:45], v[100:101], v[54:55] op_sel_hi:[1,0]
	s_nop 1
	v_mfma_f32_16x16x32_bf16 v[100:103], v[140:143], v[20:23], v[44:47]
	s_nop 2
	v_mul_f32_e64 v46, v106, v52
	v_mul_f32_e64 v47, v107, v52
	v_pk_mul_f32 v[44:45], v[104:105], v[52:53] op_sel_hi:[1,0]
	s_waitcnt lgkmcnt(8)
	s_nop 0
	v_mfma_f32_16x16x32_bf16 v[104:107], v[136:139], v[28:31], v[44:47]
	s_nop 2
	v_mul_f32_e64 v46, v110, v54
	v_mul_f32_e64 v47, v111, v54
	v_pk_mul_f32 v[44:45], v[108:109], v[54:55] op_sel_hi:[1,0]
	s_nop 1
	v_mfma_f32_16x16x32_bf16 v[108:111], v[136:139], v[20:23], v[44:47]
	s_nop 2
	v_mul_f32_e64 v46, v114, v52
	v_mul_f32_e64 v47, v115, v52
	v_pk_mul_f32 v[44:45], v[112:113], v[52:53] op_sel_hi:[1,0]
	s_waitcnt lgkmcnt(6)
	s_nop 0
	v_mfma_f32_16x16x32_bf16 v[112:115], v[132:135], v[28:31], v[44:47]
	s_nop 2
	v_mul_f32_e64 v46, v118, v54
	v_mul_f32_e64 v47, v119, v54
	v_pk_mul_f32 v[44:45], v[116:117], v[54:55] op_sel_hi:[1,0]
	s_nop 1
	v_mfma_f32_16x16x32_bf16 v[116:119], v[132:135], v[20:23], v[44:47]
	s_nop 2
	v_mul_f32_e64 v46, v122, v52
	v_mul_f32_e64 v47, v123, v52
	v_pk_mul_f32 v[44:45], v[120:121], v[52:53] op_sel_hi:[1,0]
	s_waitcnt lgkmcnt(4)
	s_nop 0
	v_mfma_f32_16x16x32_bf16 v[120:123], v[128:131], v[28:31], v[44:47]
	v_mul_f32_e64 v30, v126, v54
	v_mul_f32_e64 v31, v127, v54
	v_pk_mul_f32 v[28:29], v[124:125], v[54:55] op_sel_hi:[1,0]
	s_nop 1
	v_mfma_f32_16x16x32_bf16 v[124:127], v[128:131], v[20:23], v[28:31]
	v_add_u32_e32 v20, s76, v222
	v_med3_i32 v20, v20, 0, s75
	v_lshl_add_u32 v20, v20, 9, v152
	global_load_dwordx4 v[68:71], v20, s[98:99]
	v_add_u32_e32 v20, s76, v223
	v_med3_i32 v20, v20, 0, s75
	v_lshl_add_u32 v20, v20, 9, v152
	global_load_dwordx4 v[72:75], v20, s[98:99]
	v_add_u32_e32 v20, s76, v224
	v_med3_i32 v20, v20, 0, s75
	v_lshl_add_u32 v20, v20, 9, v152
	global_load_dwordx4 v[76:79], v20, s[98:99]
	v_add_u32_e32 v20, s76, v225
	v_med3_i32 v20, v20, 0, s75
	v_lshl_add_u32 v20, v20, 9, v152
	global_load_dwordx4 v[92:95], v20, s[98:99]
	v_add_u32_e32 v20, s76, v226
	v_med3_i32 v20, v20, 0, s75
	v_lshl_add_u32 v20, v20, 9, v158
	global_load_dwordx4 v[52:55], v20, s[100:101]
	global_load_dwordx4 v[44:47], v20, s[100:101] offset:64
	v_add_u32_e32 v20, s76, v227
	v_med3_i32 v20, v20, 0, s75
	v_lshl_add_u32 v20, v20, 9, v158
	global_load_dwordx4 v[28:31], v20, s[100:101]
	s_nop 0
	global_load_dwordx4 v[20:23], v20, s[100:101] offset:64
	ds_read_b64_tr_b16 v[142:143], v169 offset:6912
	ds_read_b64_tr_b16 v[140:141], v169 offset:4608
	ds_read_b64_tr_b16 v[136:137], v169 offset:4640
	ds_read_b64_tr_b16 v[138:139], v169 offset:6944
	ds_read_b64_tr_b16 v[132:133], v169 offset:4672
	ds_read_b64_tr_b16 v[134:135], v169 offset:6976
	ds_read_b64_tr_b16 v[128:129], v169 offset:4704
	ds_read_b64_tr_b16 v[130:131], v169 offset:7008
	s_waitcnt vmcnt(15)
	ds_write_b128 v241, v[60:63]
	s_waitcnt vmcnt(14)
	ds_write_b128 v242, v[80:83]
	s_waitcnt vmcnt(13)
	ds_write_b128 v243, v[84:87]
	s_waitcnt vmcnt(12)
	ds_write_b128 v244, v[88:91]
	v_mfma_f32_16x16x32_bf16 v[60:63], v[64:67], v[4:7], 0
	v_mfma_f32_16x16x32_bf16 v[80:83], v[40:43], v[4:7], 0
	v_mfma_f32_16x16x32_bf16 v[40:43], v[40:43], v[12:15], 0
	v_mfma_f32_16x16x32_bf16 v[60:63], v[48:51], v[8:11], v[60:63]
	v_mfma_f32_16x16x32_bf16 v[80:83], v[16:19], v[8:11], v[80:83]
	v_mfma_f32_16x16x32_bf16 v[16:19], v[16:19], v[0:3], v[40:43]
	s_nop 4
	v_sub_u32_e32 v40, v199, v176
	v_mfma_f32_16x16x32_bf16 v[64:67], v[64:67], v[12:15], 0
	v_add_u32_e32 v43, 1, v40
	v_cmp_gt_u32_e64 s[0:1], v43, v175
	v_cmp_gt_u32_e32 vcc, v40, v175
	s_nop 0
	v_cndmask_b32_e64 v61, v61, v246, s[0:1]
	s_nop 0
	v_cndmask_b32_e32 v60, v60, v246, vcc
	v_max_f32_e32 v42, 0xf149f2ca, v60
	v_mfma_f32_16x16x32_bf16 v[48:51], v[48:51], v[0:3], v[64:67]
	v_max_f32_e32 v42, v42, v61
	v_add_u32_e32 v43, 2, v40
	v_cmp_gt_u32_e64 s[22:23], v43, v175
	v_add_u32_e32 v64, 3, v40
	v_cmp_gt_u32_e64 s[24:25], v64, v175
	v_cndmask_b32_e64 v62, v62, v246, s[22:23]
	v_sub_u32_e32 v41, v199, v181
	v_cndmask_b32_e64 v63, v63, v246, s[24:25]
	v_max3_f32 v42, v42, v62, v63
	v_add_u32_e32 v43, 16, v40
	v_add_u32_e32 v64, 17, v40
	v_cmp_gt_u32_e64 s[26:27], v43, v175
	v_cmp_gt_u32_e64 s[28:29], v64, v175
	v_cmp_gt_u32_e64 s[38:39], v41, v252
	v_cndmask_b32_e64 v80, v80, v246, s[26:27]
	v_cndmask_b32_e64 v81, v81, v246, s[28:29]
	v_max3_f32 v42, v42, v80, v81
	v_add_u32_e32 v43, 18, v40
	v_add_u32_e32 v40, 19, v40
	v_cmp_gt_u32_e64 s[30:31], v43, v175
	v_cmp_gt_u32_e64 s[34:35], v40, v175
	v_add_u32_e32 v64, 3, v41
	v_cndmask_b32_e64 v82, v82, v246, s[30:31]
	v_cndmask_b32_e64 v83, v83, v246, s[34:35]
	v_max3_f32 v40, v42, v82, v83
	v_add_u32_e32 v43, 1, v41
	v_cmp_gt_u32_e64 s[40:41], v43, v252
	v_cndmask_b32_e64 v48, v48, v246, s[38:39]
	v_max_f32_e32 v42, 0xf149f2ca, v48
	v_cndmask_b32_e64 v49, v49, v246, s[40:41]
	v_max_f32_e32 v42, v42, v49
	v_add_u32_e32 v43, 2, v41
	v_cmp_gt_u32_e64 s[42:43], v43, v252
	v_cmp_gt_u32_e64 s[44:45], v64, v252
	s_nop 0
	v_cndmask_b32_e64 v50, v50, v246, s[42:43]
	v_cndmask_b32_e64 v51, v51, v246, s[44:45]
	v_max3_f32 v42, v42, v50, v51
	v_add_u32_e32 v43, 16, v41
	v_add_u32_e32 v64, 17, v41
	v_cmp_gt_u32_e64 s[46:47], v43, v252
	v_cmp_gt_u32_e64 s[48:49], v64, v252
	s_nop 0
	v_cndmask_b32_e64 v16, v16, v246, s[46:47]
	v_cndmask_b32_e64 v17, v17, v246, s[48:49]
	v_max3_f32 v42, v42, v16, v17
	v_add_u32_e32 v43, 18, v41
	v_add_u32_e32 v41, 19, v41
	v_cmp_gt_u32_e64 s[50:51], v43, v252
	v_cmp_gt_u32_e64 s[52:53], v41, v252
	s_nop 0
	v_cndmask_b32_e64 v18, v18, v246, s[50:51]
	v_cndmask_b32_e64 v19, v19, v246, s[52:53]
	v_max3_f32 v41, v42, v18, v19
	v_mov_b32_e32 v42, v40
	v_mov_b32_e32 v43, v40
	s_nop 1
	v_permlane32_swap_b32_e32 v42, v43
	v_max3_f32 v40, v40, v42, v43
	v_mov_b32_e32 v42, v41
	v_mov_b32_e32 v43, v41
	s_nop 1
	v_permlane32_swap_b32_e32 v42, v43
	v_max3_f32 v41, v41, v42, v43
	v_mov_b32_e32 v42, v40
	v_mov_b32_e32 v43, v40
	s_nop 1
	v_permlane16_swap_b32_e32 v42, v43
	v_max_f32_e32 v40, v40, v42
	v_max3_f32 v147, v148, v40, v43
	v_sub_f32_e32 v40, v148, v147
	v_exp_f32_e32 v84, v40
	v_sub_f32_e32 v40, v60, v147
	v_exp_f32_e32 v40, v40
	v_mov_b32_e32 v42, v41
	v_mov_b32_e32 v64, v41
	s_nop 1
	v_permlane16_swap_b32_e32 v42, v64
	v_cndmask_b32_e64 v85, v40, 0, vcc
	v_sub_f32_e32 v40, v61, v147
	v_exp_f32_e32 v40, v40
	v_max_f32_e32 v65, v41, v42
	v_max3_f32 v146, v149, v65, v64
	v_cndmask_b32_e64 v61, v40, 0, s[0:1]
	v_sub_f32_e32 v40, v62, v147
	v_exp_f32_e32 v40, v40
	v_sub_f32_e32 v48, v48, v146
	v_sub_f32_e32 v16, v16, v146
	v_exp_f32_e32 v48, v48
	v_cndmask_b32_e64 v62, v40, 0, s[22:23]
	v_sub_f32_e32 v40, v63, v147
	v_exp_f32_e32 v40, v40
	v_exp_f32_e32 v16, v16
	v_cndmask_b32_e64 v86, v48, 0, s[38:39]
	v_sub_f32_e32 v48, v49, v146
	v_cndmask_b32_e64 v63, v40, 0, s[24:25]
	v_sub_f32_e32 v40, v80, v147
	v_exp_f32_e32 v40, v40
	v_cndmask_b32_e64 v90, v16, 0, s[46:47]
	v_sub_f32_e32 v16, v17, v146
	v_exp_f32_e32 v48, v48
	v_cndmask_b32_e64 v80, v40, 0, s[26:27]
	v_sub_f32_e32 v40, v81, v147
	v_exp_f32_e32 v40, v40
	v_exp_f32_e32 v16, v16
	v_cndmask_b32_e64 v87, v48, 0, s[40:41]
	v_sub_f32_e32 v48, v50, v146
	v_cndmask_b32_e64 v81, v40, 0, s[28:29]
	v_sub_f32_e32 v40, v82, v147
	v_exp_f32_e32 v40, v40
	v_cndmask_b32_e64 v91, v16, 0, s[48:49]
	v_sub_f32_e32 v16, v18, v146
	v_exp_f32_e32 v48, v48
	v_exp_f32_e32 v16, v16
	v_cndmask_b32_e64 v82, v40, 0, s[30:31]
	v_sub_f32_e32 v40, v83, v147
	v_exp_f32_e32 v40, v40
	v_cndmask_b32_e64 v88, v48, 0, s[42:43]
	v_sub_f32_e32 v48, v51, v146
	v_cndmask_b32_e64 v148, v16, 0, s[50:51]
	v_sub_f32_e32 v16, v19, v146
	v_sub_f32_e32 v60, v149, v146
	v_exp_f32_e32 v48, v48
	v_exp_f32_e32 v16, v16
	v_exp_f32_e32 v60, v60
	v_cndmask_b32_e64 v83, v40, 0, s[34:35]
	v_cvt_pk_bf16_f32 v40, v85, v61
	v_cvt_pk_bf16_f32 v41, v62, v63
	v_cvt_pk_bf16_f32 v42, v80, v81
	v_cvt_pk_bf16_f32 v43, v82, v83
	v_cndmask_b32_e64 v89, v48, 0, s[44:45]
	v_cndmask_b32_e64 v149, v16, 0, s[52:53]
	v_pk_mul_f32 v[50:51], v[98:99], v[84:85] op_sel_hi:[1,0]
	v_pk_mul_f32 v[48:49], v[96:97], v[84:85] op_sel_hi:[1,0]
	v_cvt_pk_bf16_f32 v16, v86, v87
	v_cvt_pk_bf16_f32 v17, v88, v89
	v_cvt_pk_bf16_f32 v18, v90, v91
	v_cvt_pk_bf16_f32 v19, v148, v149
	s_waitcnt lgkmcnt(10)
	v_mfma_f32_16x16x32_bf16 v[64:67], v[140:143], v[40:43], v[48:51]
	s_cselect_b64 s[38:39], -1, 0
	s_add_i32 s0, s76, 0xfffffc00
	s_min_i32 s1, s0, 0
	v_pk_mul_f32 v[50:51], v[102:103], v[60:61] op_sel_hi:[1,0]
	v_pk_mul_f32 v[48:49], v[100:101], v[60:61] op_sel_hi:[1,0]
	s_sub_i32 s1, 15, s1
	s_ashr_i32 s1, s1, 4
	v_mfma_f32_16x16x32_bf16 v[100:103], v[140:143], v[16:19], v[48:51]
	s_sub_i32 s0, s75, s0
	s_ashr_i32 s0, s0, 4
	s_or_b32 s40, s76, 8
	v_pk_mul_f32 v[50:51], v[106:107], v[84:85] op_sel_hi:[1,0]
	v_pk_mul_f32 v[48:49], v[104:105], v[84:85] op_sel_hi:[1,0]
	s_lshl_b32 s56, s56, 7
	s_add_i32 s71, s71, s78
	s_waitcnt lgkmcnt(8)
	v_mfma_f32_16x16x32_bf16 v[104:107], v[136:139], v[40:43], v[48:51]
	s_nop 2
	v_mul_f32_e64 v50, v110, v60
	v_mul_f32_e64 v51, v111, v60
	v_pk_mul_f32 v[48:49], v[108:109], v[60:61] op_sel_hi:[1,0]
	s_nop 1
	v_mfma_f32_16x16x32_bf16 v[108:111], v[136:139], v[16:19], v[48:51]
	s_nop 2
	v_mul_f32_e64 v50, v114, v84
	v_mul_f32_e64 v51, v115, v84
	v_pk_mul_f32 v[48:49], v[112:113], v[84:85] op_sel_hi:[1,0]
	s_waitcnt lgkmcnt(6)
	s_nop 0
	v_mfma_f32_16x16x32_bf16 v[112:115], v[132:135], v[40:43], v[48:51]
	s_nop 2
	v_mul_f32_e64 v50, v118, v60
	v_mul_f32_e64 v51, v119, v60
	v_pk_mul_f32 v[48:49], v[116:117], v[60:61] op_sel_hi:[1,0]
	s_nop 1
	v_mfma_f32_16x16x32_bf16 v[116:119], v[132:135], v[16:19], v[48:51]
	s_nop 2
	v_mul_f32_e64 v50, v122, v84
	v_mul_f32_e64 v51, v123, v84
	v_pk_mul_f32 v[48:49], v[120:121], v[84:85] op_sel_hi:[1,0]
	s_waitcnt lgkmcnt(4)
	s_nop 0
	v_mfma_f32_16x16x32_bf16 v[120:123], v[128:131], v[40:43], v[48:51]
	v_mul_f32_e64 v42, v126, v60
	v_mul_f32_e64 v43, v127, v60
	v_pk_mul_f32 v[40:41], v[124:125], v[60:61] op_sel_hi:[1,0]
	s_nop 1
	v_mfma_f32_16x16x32_bf16 v[124:127], v[128:131], v[16:19], v[40:43]
	v_add_f32_e32 v16, 0, v86
	v_add_f32_e32 v16, v87, v16
	v_add_f32_e32 v16, v88, v16
	v_add_f32_e32 v16, v89, v16
	v_add_f32_e32 v16, v90, v16
	v_add_f32_e32 v16, v91, v16
	v_add_f32_e32 v16, v148, v16
	v_add_f32_e32 v151, v149, v16
	v_add_f32_e32 v16, 0, v85
	v_add_f32_e32 v16, v61, v16
	v_add_f32_e32 v16, v62, v16
	v_add_f32_e32 v16, v63, v16
	v_add_f32_e32 v16, v80, v16
	v_add_f32_e32 v16, v81, v16
	v_add_f32_e32 v16, v82, v16
	v_fmac_f32_e32 v151, v145, v60
	v_add_f32_e32 v145, v83, v16
	v_add_u32_e32 v16, s76, v213
	v_fmac_f32_e32 v145, v144, v84
	v_ashrrev_i32_e32 v148, 4, v250
	v_med3_i32 v16, v16, 0, s75
	v_lshl_add_u32 v16, v16, 9, v152
	global_load_dwordx4 v[80:83], v16, s[98:99]
	v_add_u32_e32 v16, s76, v215
	v_max_i32_e32 v150, s1, v148
	s_nop 0
	v_med3_i32 v16, v16, 0, s75
	v_lshl_add_u32 v16, v16, 9, v152
	global_load_dwordx4 v[84:87], v16, s[98:99]
	v_add_u32_e32 v16, s76, v217
	v_med3_i32 v16, v16, 0, s75
	v_lshl_add_u32 v16, v16, 9, v152
	global_load_dwordx4 v[88:91], v16, s[98:99]
	v_add_u32_e32 v16, s76, v219
	v_med3_i32 v16, v16, 0, s75
	v_lshl_add_u32 v16, v16, 9, v152
	global_load_dwordx4 v[96:99], v16, s[98:99]
	v_min_i32_e32 v16, s75, v251
	v_cndmask_b32_e64 v16, v16, 0, s[38:39]
	v_lshl_add_u32 v16, v16, 9, v158
	global_load_dwordx4 v[48:51], v16, s[100:101]
	global_load_dwordx4 v[60:63], v16, s[100:101] offset:64
	v_add_u32_e32 v16, s76, v228
	v_med3_i32 v16, v16, 0, s75
	v_lshl_add_u32 v16, v16, 9, v158
	global_load_dwordx4 v[40:43], v16, s[100:101]
	s_nop 0
	global_load_dwordx4 v[16:19], v16, s[100:101] offset:64
	ds_read_b64_tr_b16 v[142:143], v169 offset:2304
	ds_read_b64_tr_b16 v[140:141], v169
	ds_read_b64_tr_b16 v[136:137], v169 offset:32
	ds_read_b64_tr_b16 v[138:139], v169 offset:2336
	ds_read_b64_tr_b16 v[132:133], v169 offset:64
	ds_read_b64_tr_b16 v[134:135], v169 offset:2368
	ds_read_b64_tr_b16 v[128:129], v169 offset:96
	ds_read_b64_tr_b16 v[130:131], v169 offset:2400
	s_waitcnt vmcnt(15)
	ds_write_b128 v241, v[68:71] offset:4608
	s_waitcnt vmcnt(14)
	ds_write_b128 v242, v[72:75] offset:4608
	s_waitcnt vmcnt(13)
	ds_write_b128 v243, v[76:79] offset:4608
	s_waitcnt vmcnt(12)
	ds_write_b128 v244, v[92:95] offset:4608
	v_mfma_f32_16x16x32_bf16 v[72:75], v[32:35], v[4:7], 0
	v_mfma_f32_16x16x32_bf16 v[68:71], v[56:59], v[4:7], 0
	v_mfma_f32_16x16x32_bf16 v[72:75], v[24:27], v[8:11], v[72:75]
	v_mfma_f32_16x16x32_bf16 v[68:71], v[36:39], v[8:11], v[68:71]
	s_nop 5
	v_add_u32_e32 v25, 0x800, v250
	v_ashrrev_i32_e32 v25, 4, v25
	v_min3_i32 v25, v25, s0, v248
	v_sub_u32_e32 v26, v154, v150
	v_sub_u32_e32 v149, v25, v150
	v_add_u32_e32 v27, 1, v26
	v_cmp_gt_u32_e64 s[0:1], v27, v149
	v_cmp_gt_u32_e32 vcc, v26, v149
	s_nop 0
	v_cndmask_b32_e64 v69, v69, v246, s[0:1]
	s_nop 0
	v_cndmask_b32_e32 v68, v68, v246, vcc
	v_max_f32_e32 v25, 0xf149f2ca, v68
	v_max_f32_e32 v25, v25, v69
	v_add_u32_e32 v27, 2, v26
	v_add_u32_e32 v32, 3, v26
	v_cmp_gt_u32_e64 s[22:23], v27, v149
	v_cmp_gt_u32_e64 s[24:25], v32, v149
	s_nop 0
	v_cndmask_b32_e64 v70, v70, v246, s[22:23]
	s_nop 0
	v_cndmask_b32_e64 v71, v71, v246, s[24:25]
	v_max3_f32 v25, v25, v70, v71
	v_add_u32_e32 v27, 16, v26
	v_add_u32_e32 v32, 17, v26
	v_cmp_gt_u32_e64 s[26:27], v27, v149
	v_cmp_gt_u32_e64 s[28:29], v32, v149
	s_nop 0
	v_cndmask_b32_e64 v72, v72, v246, s[26:27]
	v_cndmask_b32_e64 v73, v73, v246, s[28:29]
	v_max3_f32 v25, v25, v72, v73
	v_add_u32_e32 v27, 18, v26
	v_add_u32_e32 v26, 19, v26
	v_cmp_gt_u32_e64 s[30:31], v27, v149
	v_cmp_gt_u32_e64 s[34:35], v26, v149
	s_nop 0
	v_cndmask_b32_e64 v74, v74, v246, s[30:31]
	v_cndmask_b32_e64 v75, v75, v246, s[34:35]
	v_max3_f32 v25, v25, v74, v75
	v_mov_b32_e32 v27, v25
	v_mov_b32_e32 v32, v25
	s_nop 1
	v_permlane32_swap_b32_e32 v27, v32
	v_max3_f32 v25, v25, v27, v32
	s_nop 1
	v_mov_b32_e32 v27, v25
	v_mov_b32_e32 v32, v25
	s_nop 1
	v_permlane16_swap_b32_e32 v27, v32
	v_max_f32_e32 v25, v25, v27
	v_max3_f32 v144, v147, v25, v32
	v_sub_f32_e32 v25, v147, v144
	v_exp_f32_e32 v56, v25
	v_sub_f32_e32 v25, v68, v144
	v_exp_f32_e32 v25, v25
	v_sub_f32_e32 v32, v69, v144
	v_exp_f32_e32 v32, v32
	v_sub_f32_e32 v33, v70, v144
	v_exp_f32_e32 v33, v33
	v_sub_f32_e32 v34, v71, v144
	v_exp_f32_e32 v34, v34
	v_sub_f32_e32 v35, v72, v144
	v_exp_f32_e32 v35, v35
	v_sub_f32_e32 v38, v73, v144
	v_add_f32_e32 v27, 0, v25
	v_exp_f32_e32 v38, v38
	v_sub_f32_e32 v39, v74, v144
	v_add_f32_e32 v27, v32, v27
	v_exp_f32_e32 v39, v39
	v_sub_f32_e32 v57, v75, v144
	v_add_f32_e32 v27, v33, v27
	v_exp_f32_e32 v57, v57
	v_add_f32_e32 v27, v34, v27
	v_add_f32_e32 v27, v35, v27
	v_add_f32_e32 v27, v38, v27
	v_add_f32_e32 v27, v39, v27
	v_add_f32_e32 v147, v57, v27
	v_fmac_f32_e32 v147, v145, v56
	v_mov_b32_e32 v145, v146
	v_cvt_pk_bf16_f32 v32, v25, v32
	v_mov_b32_e32 v58, 1.0
	v_cvt_pk_bf16_f32 v33, v33, v34
	v_mov_b32_e32 v25, 0
	v_cvt_pk_bf16_f32 v34, v35, v38
	v_cvt_pk_bf16_f32 v35, v39, v57
	v_add_f32_e32 v26, 0, v25
	v_mov_b32_e32 v27, 0
	v_pk_mul_f32 v[38:39], v[66:67], v[56:57] op_sel_hi:[1,0]
	v_pk_mul_f32 v[36:37], v[64:65], v[56:57] op_sel_hi:[1,0]
	v_add_f32_e32 v146, v27, v26
	v_cvt_pk_bf16_f32 v24, v25, 0
	v_cvt_pk_bf16_f32 v26, v27, 0
	v_mov_b32_e32 v25, v153
	v_mov_b32_e32 v27, v153
	s_waitcnt lgkmcnt(10)
	v_mfma_f32_16x16x32_bf16 v[76:79], v[140:143], v[32:35], v[36:39]
	v_fmac_f32_e32 v146, v151, v58
	s_nop 1
	v_pk_mul_f32 v[38:39], v[102:103], v[58:59] op_sel_hi:[1,0]
	v_pk_mul_f32 v[36:37], v[100:101], v[58:59] op_sel_hi:[1,0]
	s_nop 1
	v_mfma_f32_16x16x32_bf16 v[100:103], v[140:143], v[24:27], v[36:39]
	s_nop 2
	v_mul_f32_e64 v38, v106, v56
	v_mul_f32_e64 v39, v107, v56
	v_pk_mul_f32 v[36:37], v[104:105], v[56:57] op_sel_hi:[1,0]
	s_waitcnt lgkmcnt(8)
	s_nop 0
	v_mfma_f32_16x16x32_bf16 v[104:107], v[136:139], v[32:35], v[36:39]
	s_nop 2
	v_mul_f32_e64 v38, v110, v58
	v_mul_f32_e64 v39, v111, v58
	v_pk_mul_f32 v[36:37], v[108:109], v[58:59] op_sel_hi:[1,0]
	s_nop 1
	v_mfma_f32_16x16x32_bf16 v[108:111], v[136:139], v[24:27], v[36:39]
	s_nop 2
	v_mul_f32_e64 v38, v114, v56
	v_mul_f32_e64 v39, v115, v56
	v_pk_mul_f32 v[36:37], v[112:113], v[56:57] op_sel_hi:[1,0]
	s_waitcnt lgkmcnt(6)
	s_nop 0
	v_mfma_f32_16x16x32_bf16 v[112:115], v[132:135], v[32:35], v[36:39]
	s_nop 2
	v_mul_f32_e64 v38, v118, v58
	v_mul_f32_e64 v39, v119, v58
	v_pk_mul_f32 v[36:37], v[116:117], v[58:59] op_sel_hi:[1,0]
	s_nop 1
	v_mfma_f32_16x16x32_bf16 v[116:119], v[132:135], v[24:27], v[36:39]
	s_nop 2
	v_mul_f32_e64 v38, v122, v56
	v_mul_f32_e64 v39, v123, v56
	v_pk_mul_f32 v[36:37], v[120:121], v[56:57] op_sel_hi:[1,0]
	v_add_u32_e32 v56, s76, v232
	s_waitcnt lgkmcnt(4)
	v_mfma_f32_16x16x32_bf16 v[120:123], v[128:131], v[32:35], v[36:39]
	v_mul_f32_e64 v34, v126, v58
	v_mul_f32_e64 v35, v127, v58
	v_pk_mul_f32 v[32:33], v[124:125], v[58:59] op_sel_hi:[1,0]
	v_add_u32_e32 v36, s76, v231
	s_nop 0
	v_mfma_f32_16x16x32_bf16 v[124:127], v[128:131], v[24:27], v[32:35]
	v_add_u32_e32 v24, s76, v229
	s_nop 1
	v_add_u32_e32 v32, s76, v230
	v_med3_i32 v24, v24, 0, s75
	v_med3_i32 v32, v32, 0, s75
	v_med3_i32 v36, v36, 0, s75
	v_med3_i32 v56, v56, 0, s75
	v_lshl_add_u32 v36, v36, 9, v152
	v_lshl_add_u32 v56, v56, 9, v152
	global_load_dwordx4 v[36:39], v36, s[98:99]
	global_load_dwordx4 v[92:95], v56, s[98:99]
	v_add_u32_e32 v56, s76, v233
	v_med3_i32 v56, v56, 0, s75
	v_lshl_add_u32 v24, v24, 9, v152
	v_lshl_add_u32 v32, v32, 9, v152
	v_lshl_add_u32 v56, v56, 9, v158
	global_load_dwordx4 v[24:27], v24, s[98:99]
	s_nop 0
	global_load_dwordx4 v[32:35], v32, s[98:99]
	s_nop 0
	global_load_dwordx4 v[72:75], v56, s[100:101]
	global_load_dwordx4 v[68:71], v56, s[100:101] offset:64
	v_add_u32_e32 v56, s76, v234
	v_med3_i32 v56, v56, 0, s75
	v_lshl_add_u32 v56, v56, 9, v158
	global_load_dwordx4 v[64:67], v56, s[100:101]
	s_nop 0
	global_load_dwordx4 v[56:59], v56, s[100:101] offset:64
	ds_read_b64_tr_b16 v[142:143], v169 offset:6912
	ds_read_b64_tr_b16 v[140:141], v169 offset:4608
	ds_read_b64_tr_b16 v[136:137], v169 offset:4640
	ds_read_b64_tr_b16 v[138:139], v169 offset:6944
	ds_read_b64_tr_b16 v[132:133], v169 offset:4672
	ds_read_b64_tr_b16 v[134:135], v169 offset:6976
	ds_read_b64_tr_b16 v[128:129], v169 offset:4704
	ds_read_b64_tr_b16 v[130:131], v169 offset:7008
	s_waitcnt vmcnt(15)
	ds_write_b128 v241, v[80:83]
	s_waitcnt vmcnt(14)
	ds_write_b128 v242, v[84:87]
	s_waitcnt vmcnt(13)
	ds_write_b128 v243, v[88:91]
	s_waitcnt vmcnt(12)
	ds_write_b128 v244, v[96:99]
	v_mfma_f32_16x16x32_bf16 v[80:83], v[52:55], v[4:7], 0
	v_mfma_f32_16x16x32_bf16 v[84:87], v[28:31], v[4:7], 0
	v_mfma_f32_16x16x32_bf16 v[80:83], v[44:47], v[8:11], v[80:83]
	v_mfma_f32_16x16x32_bf16 v[84:87], v[20:23], v[8:11], v[84:87]
	s_nop 5
	v_sub_u32_e32 v21, v187, v150
	v_add_u32_e32 v23, 1, v21
	v_cmp_gt_u32_e64 s[0:1], v23, v149
	v_cmp_gt_u32_e32 vcc, v21, v149
	s_nop 0
	v_cndmask_b32_e64 v81, v81, v246, s[0:1]
	s_nop 0
	v_cndmask_b32_e32 v80, v80, v246, vcc
	v_max_f32_e32 v22, 0xf149f2ca, v80
	v_max_f32_e32 v22, v22, v81
	v_add_u32_e32 v23, 2, v21
	v_add_u32_e32 v28, 3, v21
	v_cmp_gt_u32_e64 s[22:23], v23, v149
	v_cmp_gt_u32_e64 s[24:25], v28, v149
	s_nop 0
	v_cndmask_b32_e64 v82, v82, v246, s[22:23]
	v_cndmask_b32_e64 v83, v83, v246, s[24:25]
	v_max3_f32 v22, v22, v82, v83
	v_add_u32_e32 v23, 16, v21
	v_add_u32_e32 v28, 17, v21
	v_cmp_gt_u32_e64 s[26:27], v23, v149
	v_cmp_gt_u32_e64 s[28:29], v28, v149
	s_nop 0
	v_cndmask_b32_e64 v84, v84, v246, s[26:27]
	v_cndmask_b32_e64 v85, v85, v246, s[28:29]
	v_max3_f32 v22, v22, v84, v85
	v_add_u32_e32 v23, 18, v21
	v_add_u32_e32 v21, 19, v21
	v_cmp_gt_u32_e64 s[30:31], v23, v149
	v_cmp_gt_u32_e64 s[34:35], v21, v149
	s_nop 0
	v_cndmask_b32_e64 v86, v86, v246, s[30:31]
	v_cndmask_b32_e64 v87, v87, v246, s[34:35]
	v_max3_f32 v21, v22, v86, v87
	v_mov_b32_e32 v23, v21
	v_mov_b32_e32 v28, v21
	s_nop 1
	v_permlane32_swap_b32_e32 v23, v28
	v_max3_f32 v21, v21, v23, v28
	s_nop 1
	v_mov_b32_e32 v23, v21
	v_mov_b32_e32 v28, v21
	s_nop 1
	v_permlane16_swap_b32_e32 v23, v28
	v_max_f32_e32 v21, v21, v23
	v_max3_f32 v175, v144, v21, v28
	v_sub_f32_e32 v21, v144, v175
	v_exp_f32_e32 v144, v21
	v_sub_f32_e32 v21, v80, v175
	v_sub_f32_e32 v28, v81, v175
	v_exp_f32_e32 v21, v21
	v_exp_f32_e32 v28, v28
	v_sub_f32_e32 v30, v82, v175
	v_exp_f32_e32 v30, v30
	v_sub_f32_e32 v31, v83, v175
	v_exp_f32_e32 v31, v31
	v_sub_f32_e32 v45, v84, v175
	v_exp_f32_e32 v45, v45
	v_sub_f32_e32 v46, v85, v175
	v_mov_b32_e32 v176, v145
	v_add_f32_e32 v23, 0, v21
	v_exp_f32_e32 v46, v46
	v_sub_f32_e32 v47, v86, v175
	v_cvt_pk_bf16_f32 v80, v21, v28
	v_add_f32_e32 v23, v28, v23
	v_exp_f32_e32 v47, v47
	v_sub_f32_e32 v52, v87, v175
	v_mov_b32_e32 v84, 1.0
	v_add_f32_e32 v23, v30, v23
	v_exp_f32_e32 v52, v52
	v_add_f32_e32 v23, v31, v23
	v_add_f32_e32 v23, v45, v23
	v_add_f32_e32 v23, v46, v23
	v_add_f32_e32 v23, v47, v23
	v_mov_b32_e32 v21, 0
	v_add_f32_e32 v151, v52, v23
	v_add_f32_e32 v22, 0, v21
	v_mov_b32_e32 v23, 0
	v_fmac_f32_e32 v151, v147, v144
	v_cvt_pk_bf16_f32 v81, v30, v31
	v_add_f32_e32 v147, v23, v22
	v_cvt_pk_bf16_f32 v20, v21, 0
	v_cvt_pk_bf16_f32 v22, v23, 0
	v_mov_b32_e32 v21, v153
	v_mov_b32_e32 v23, v153
	v_pk_mul_f32 v[30:31], v[78:79], v[144:145] op_sel_hi:[1,0]
	v_pk_mul_f32 v[28:29], v[76:77], v[144:145] op_sel_hi:[1,0]
	v_pk_mul_f32 v[78:79], v[110:111], v[84:85] op_sel_hi:[1,0]
	v_pk_mul_f32 v[76:77], v[108:109], v[84:85] op_sel_hi:[1,0]
	v_cvt_pk_bf16_f32 v82, v45, v46
	v_cvt_pk_bf16_f32 v83, v47, v52
	s_waitcnt lgkmcnt(8)
	v_mfma_f32_16x16x32_bf16 v[88:91], v[136:139], v[20:23], v[76:79]
	v_mul_f32_e64 v46, v102, v84
	v_mul_f32_e64 v47, v103, v84
	v_pk_mul_f32 v[44:45], v[100:101], v[84:85] op_sel_hi:[1,0]
	v_pk_mul_f32 v[54:55], v[106:107], v[144:145] op_sel_hi:[1,0]
	v_pk_mul_f32 v[78:79], v[114:115], v[144:145] op_sel_hi:[1,0]
	v_pk_mul_f32 v[76:77], v[112:113], v[144:145] op_sel_hi:[1,0]
	v_pk_mul_f32 v[52:53], v[104:105], v[144:145] op_sel_hi:[1,0]
	v_mfma_f32_16x16x32_bf16 v[44:47], v[140:143], v[20:23], v[44:47]
	v_fmac_f32_e32 v147, v146, v84
	s_waitcnt lgkmcnt(6)
	v_mfma_f32_16x16x32_bf16 v[96:99], v[132:135], v[80:83], v[76:79]
	s_nop 2
	v_mul_f32_e64 v78, v118, v84
	v_mul_f32_e64 v79, v119, v84
	v_pk_mul_f32 v[76:77], v[116:117], v[84:85] op_sel_hi:[1,0]
	v_mfma_f32_16x16x32_bf16 v[28:31], v[140:143], v[80:83], v[28:31]
	s_nop 0
	v_mfma_f32_16x16x32_bf16 v[100:103], v[132:135], v[20:23], v[76:79]
	s_nop 2
	v_mul_f32_e64 v78, v122, v144
	v_mul_f32_e64 v79, v123, v144
	v_pk_mul_f32 v[76:77], v[120:121], v[144:145] op_sel_hi:[1,0]
	v_mfma_f32_16x16x32_bf16 v[52:55], v[136:139], v[80:83], v[52:55]
	s_waitcnt lgkmcnt(4)
	v_mfma_f32_16x16x32_bf16 v[104:107], v[128:131], v[80:83], v[76:79]
	s_nop 2
	v_mul_f32_e64 v78, v126, v84
	v_mul_f32_e64 v79, v127, v84
	v_pk_mul_f32 v[76:77], v[124:125], v[84:85] op_sel_hi:[1,0]
	s_nop 1
	v_mfma_f32_16x16x32_bf16 v[108:111], v[128:131], v[20:23], v[76:79]
	v_add_u32_e32 v20, s76, v235
	v_med3_i32 v20, v20, 0, s75
	v_lshl_add_u32 v20, v20, 9, v152
	global_load_dwordx4 v[112:115], v20, s[98:99]
	v_add_u32_e32 v20, s76, v236
	v_med3_i32 v20, v20, 0, s75
	v_lshl_add_u32 v20, v20, 9, v152
	global_load_dwordx4 v[116:119], v20, s[98:99]
	v_add_u32_e32 v20, s76, v237
	v_med3_i32 v20, v20, 0, s75
	v_lshl_add_u32 v20, v20, 9, v152
	global_load_dwordx4 v[120:123], v20, s[98:99]
	v_add_u32_e32 v20, s76, v238
	v_med3_i32 v20, v20, 0, s75
	v_lshl_add_u32 v20, v20, 9, v152
	global_load_dwordx4 v[124:127], v20, s[98:99]
	v_add_u32_e32 v20, s76, v239
	v_med3_i32 v20, v20, 0, s75
	v_lshl_add_u32 v20, v20, 9, v158
	global_load_dwordx4 v[84:87], v20, s[100:101]
	global_load_dwordx4 v[80:83], v20, s[100:101] offset:64
	v_add_u32_e32 v20, s76, v240
	s_addk_i32 s76, 0xfc08
	s_nop 0
	v_med3_i32 v20, v20, 0, s75
	v_lshl_add_u32 v20, v20, 9, v158
	global_load_dwordx4 v[76:79], v20, s[100:101]
	s_nop 0
	global_load_dwordx4 v[20:23], v20, s[100:101] offset:64
	ds_read_b64_tr_b16 v[142:143], v169 offset:2304
	ds_read_b64_tr_b16 v[140:141], v169
	ds_read_b64_tr_b16 v[136:137], v169 offset:32
	ds_read_b64_tr_b16 v[138:139], v169 offset:2336
	ds_read_b64_tr_b16 v[132:133], v169 offset:64
	ds_read_b64_tr_b16 v[134:135], v169 offset:2368
	ds_read_b64_tr_b16 v[128:129], v169 offset:96
	ds_read_b64_tr_b16 v[130:131], v169 offset:2400
	s_waitcnt vmcnt(13)
	ds_write_b128 v241, v[24:27] offset:4608
	s_waitcnt vmcnt(12)
	ds_write_b128 v242, v[32:35] offset:4608
	ds_write_b128 v243, v[36:39] offset:4608
	ds_write_b128 v244, v[92:95] offset:4608
	v_mfma_f32_16x16x32_bf16 v[24:27], v[48:51], v[4:7], 0
	v_mfma_f32_16x16x32_bf16 v[32:35], v[40:43], v[4:7], 0
	v_mfma_f32_16x16x32_bf16 v[24:27], v[60:63], v[8:11], v[24:27]
	v_mfma_f32_16x16x32_bf16 v[32:35], v[16:19], v[8:11], v[32:35]
	s_nop 7
	v_sub_u32_e32 v17, v192, v150
	v_add_u32_e32 v19, 1, v17
	v_cmp_gt_u32_e64 s[0:1], v19, v149
	v_cmp_gt_u32_e32 vcc, v17, v149
	s_nop 0
	v_cndmask_b32_e64 v25, v25, v246, s[0:1]
	s_nop 0
	v_cndmask_b32_e32 v24, v24, v246, vcc
	v_max_f32_e32 v18, 0xf149f2ca, v24
	v_max_f32_e32 v18, v18, v25
	v_add_u32_e32 v19, 2, v17
	v_add_u32_e32 v37, 3, v17
	v_cmp_gt_u32_e64 s[22:23], v19, v149
	v_cmp_gt_u32_e64 s[24:25], v37, v149
	s_nop 0
	v_cndmask_b32_e64 v26, v26, v246, s[22:23]
	v_cndmask_b32_e64 v27, v27, v246, s[24:25]
	v_max3_f32 v18, v18, v26, v27
	v_add_u32_e32 v19, 16, v17
	v_add_u32_e32 v37, 17, v17
	v_cmp_gt_u32_e64 s[26:27], v19, v149
	v_cmp_gt_u32_e64 s[28:29], v37, v149
	s_nop 0
	v_cndmask_b32_e64 v32, v32, v246, s[26:27]
	v_cndmask_b32_e64 v33, v33, v246, s[28:29]
	v_max3_f32 v18, v18, v32, v33
	v_add_u32_e32 v19, 18, v17
	v_add_u32_e32 v17, 19, v17
	v_cmp_gt_u32_e64 s[30:31], v19, v149
	v_cmp_gt_u32_e64 s[34:35], v17, v149
	s_nop 0
	v_cndmask_b32_e64 v34, v34, v246, s[30:31]
	v_cndmask_b32_e64 v35, v35, v246, s[34:35]
	v_max3_f32 v17, v18, v34, v35
	v_mov_b32_e32 v19, v17
	v_mov_b32_e32 v37, v17
	s_nop 1
	v_permlane32_swap_b32_e32 v19, v37
	v_max3_f32 v17, v17, v19, v37
	s_nop 1
	v_mov_b32_e32 v19, v17
	v_mov_b32_e32 v37, v17
	s_nop 1
	v_permlane16_swap_b32_e32 v19, v37
	v_max_f32_e32 v17, v17, v19
	v_max3_f32 v145, v175, v17, v37
	v_sub_f32_e32 v17, v175, v145
	v_exp_f32_e32 v38, v17
	v_sub_f32_e32 v17, v24, v145
	v_exp_f32_e32 v17, v17
	s_nop 1
	v_cndmask_b32_e64 v37, v17, 0, vcc
	v_sub_f32_e32 v17, v25, v145
	v_exp_f32_e32 v17, v17
	v_mov_b32_e32 v144, v176
	v_cndmask_b32_e64 v60, v17, 0, s[0:1]
	v_sub_f32_e32 v17, v26, v145
	v_exp_f32_e32 v17, v17
	v_cvt_pk_bf16_f32 v24, v37, v60
	v_cndmask_b32_e64 v61, v17, 0, s[22:23]
	v_sub_f32_e32 v17, v27, v145
	v_exp_f32_e32 v17, v17
	v_mov_b32_e32 v39, 0
	v_pk_mul_f32 v[30:31], v[30:31], v[38:39] op_sel_hi:[1,0]
	v_pk_mul_f32 v[28:29], v[28:29], v[38:39] op_sel_hi:[1,0]
	v_cndmask_b32_e64 v62, v17, 0, s[24:25]
	v_sub_f32_e32 v17, v32, v145
	v_exp_f32_e32 v17, v17
	v_cvt_pk_bf16_f32 v25, v61, v62
	v_cvt_pk_bf16_f32 v18, v39, 0
	v_mov_b32_e32 v19, v153
	v_cndmask_b32_e64 v63, v17, 0, s[26:27]
	v_sub_f32_e32 v17, v33, v145
	v_exp_f32_e32 v17, v17
	s_nop 0
	v_cndmask_b32_e64 v33, v17, 0, s[28:29]
	v_sub_f32_e32 v17, v34, v145
	v_exp_f32_e32 v17, v17
	v_cvt_pk_bf16_f32 v26, v63, v33
	v_cndmask_b32_e64 v34, v17, 0, s[30:31]
	v_sub_f32_e32 v17, v35, v145
	v_exp_f32_e32 v17, v17
	s_nop 0
	v_cndmask_b32_e64 v35, v17, 0, s[34:35]
	v_mov_b32_e32 v32, 1.0
	v_cvt_pk_bf16_f32 v27, v34, v35
	v_mov_b32_e32 v36, 0
	v_cvt_pk_bf16_f32 v16, v36, 0
	v_mov_b32_e32 v17, v153
	s_waitcnt lgkmcnt(10)
	v_mfma_f32_16x16x32_bf16 v[40:43], v[140:143], v[24:27], v[28:31]
	s_nop 2
	v_mul_f32_e64 v30, v46, v32
	v_mul_f32_e64 v31, v47, v32
	v_pk_mul_f32 v[28:29], v[44:45], v[32:33] op_sel_hi:[1,0]
	s_nop 1
	v_mfma_f32_16x16x32_bf16 v[44:47], v[140:143], v[16:19], v[28:31]
	s_nop 2
	v_mul_f32_e64 v30, v54, v38
	v_mul_f32_e64 v31, v55, v38
	v_pk_mul_f32 v[28:29], v[52:53], v[38:39] op_sel_hi:[1,0]
	s_waitcnt lgkmcnt(8)
	s_nop 0
	v_mfma_f32_16x16x32_bf16 v[48:51], v[136:139], v[24:27], v[28:31]
	s_nop 2
	v_mul_f32_e64 v30, v90, v32
	v_mul_f32_e64 v31, v91, v32
	v_pk_mul_f32 v[28:29], v[88:89], v[32:33] op_sel_hi:[1,0]
	s_nop 1
	v_mfma_f32_16x16x32_bf16 v[52:55], v[136:139], v[16:19], v[28:31]
	s_nop 2
	v_mul_f32_e64 v30, v98, v38
	v_mul_f32_e64 v31, v99, v38
	v_pk_mul_f32 v[28:29], v[96:97], v[38:39] op_sel_hi:[1,0]
	s_waitcnt lgkmcnt(6)
	s_nop 0
	v_mfma_f32_16x16x32_bf16 v[88:91], v[132:135], v[24:27], v[28:31]
	s_nop 2
	v_mul_f32_e64 v30, v102, v32
	v_mul_f32_e64 v31, v103, v32
	v_pk_mul_f32 v[28:29], v[100:101], v[32:33] op_sel_hi:[1,0]
	s_nop 1
	v_mfma_f32_16x16x32_bf16 v[100:103], v[132:135], v[16:19], v[28:31]
	s_nop 2
	v_mul_f32_e64 v30, v106, v38
	v_mul_f32_e64 v31, v107, v38
	v_pk_mul_f32 v[28:29], v[104:105], v[38:39] op_sel_hi:[1,0]
	s_waitcnt lgkmcnt(4)
	s_nop 0
	v_mfma_f32_16x16x32_bf16 v[104:107], v[128:131], v[24:27], v[28:31]
	v_mul_f32_e64 v26, v110, v32
	v_mul_f32_e64 v27, v111, v32
	v_pk_mul_f32 v[24:25], v[108:109], v[32:33] op_sel_hi:[1,0]
	s_nop 1
	v_mfma_f32_16x16x32_bf16 v[108:111], v[128:131], v[16:19], v[24:27]
	v_add_f32_e32 v16, 0, v36
	v_add_f32_e32 v146, v39, v16
	v_add_f32_e32 v16, 0, v37
	v_add_f32_e32 v16, v60, v16
	v_add_f32_e32 v16, v61, v16
	v_add_f32_e32 v16, v62, v16
	v_add_f32_e32 v16, v63, v16
	v_add_f32_e32 v16, v33, v16
	v_add_f32_e32 v16, v34, v16
	v_fmac_f32_e32 v146, v147, v32
	v_add_f32_e32 v147, v35, v16
	v_add_u32_e32 v16, s40, v214
	v_add_u32_e32 v24, s40, v216
	v_med3_i32 v16, v16, 0, s75
	v_med3_i32 v24, v24, 0, s75
	v_lshl_add_u32 v16, v16, 9, v152
	v_lshl_add_u32 v24, v24, 9, v152
	global_load_dwordx4 v[16:19], v16, s[98:99]
	v_or_b32_e32 v32, 0xfffffd00, v167
	global_load_dwordx4 v[60:63], v24, s[98:99]
	v_add_u32_e32 v24, s40, v218
	v_add_u32_e32 v32, s40, v32
	v_med3_i32 v24, v24, 0, s75
	v_lshl_add_u32 v24, v24, 9, v152
	global_load_dwordx4 v[92:95], v24, s[98:99]
	v_add_u32_e32 v24, s40, v220
	v_fmac_f32_e32 v147, v151, v38
	s_nop 0
	v_med3_i32 v24, v24, 0, s75
	v_lshl_add_u32 v24, v24, 9, v152
	global_load_dwordx4 v[96:99], v24, s[98:99]
	v_add_u32_e32 v24, s40, v221
	v_med3_i32 v24, v24, 0, s75
	v_med3_i32 v32, v32, 0, s75
	v_lshl_add_u32 v28, v24, 9, v158
	v_lshl_add_u32 v36, v32, 9, v158
	global_load_dwordx4 v[24:27], v28, s[100:101]
	s_nop 0
	global_load_dwordx4 v[28:31], v28, s[100:101] offset:64
	s_nop 0
	global_load_dwordx4 v[32:35], v36, s[100:101]
	s_nop 0
	global_load_dwordx4 v[36:39], v36, s[100:101] offset:64
	ds_read_b64_tr_b16 v[142:143], v169 offset:6912
	ds_read_b64_tr_b16 v[140:141], v169 offset:4608
	ds_read_b64_tr_b16 v[132:133], v169 offset:4640
	ds_read_b64_tr_b16 v[134:135], v169 offset:6944
	ds_read_b64_tr_b16 v[128:129], v169 offset:4672
	ds_read_b64_tr_b16 v[130:131], v169 offset:6976
	ds_read_b64_tr_b16 v[136:137], v169 offset:4704
	ds_read_b64_tr_b16 v[138:139], v169 offset:7008
	s_waitcnt vmcnt(15)
	ds_write_b128 v241, v[112:115]
	s_waitcnt vmcnt(14)
	ds_write_b128 v242, v[116:119]
	s_waitcnt vmcnt(13)
	ds_write_b128 v243, v[120:123]
	s_waitcnt vmcnt(12)
	ds_write_b128 v244, v[124:127]
	v_mfma_f32_16x16x32_bf16 v[112:115], v[72:75], v[4:7], 0
	v_mfma_f32_16x16x32_bf16 v[116:119], v[64:67], v[4:7], 0
	v_mfma_f32_16x16x32_bf16 v[112:115], v[68:71], v[8:11], v[112:115]
	v_mfma_f32_16x16x32_bf16 v[116:119], v[56:59], v[8:11], v[116:119]
	s_nop 5
	v_sub_u32_e32 v57, v197, v150
	v_add_u32_e32 v59, 1, v57
	v_cmp_gt_u32_e64 s[0:1], v59, v149
	v_cmp_gt_u32_e32 vcc, v57, v149
	s_nop 0
	v_cndmask_b32_e64 v113, v113, v246, s[0:1]
	s_nop 0
	v_cndmask_b32_e32 v112, v112, v246, vcc
	v_max_f32_e32 v58, 0xf149f2ca, v112
	v_max_f32_e32 v58, v58, v113
	v_add_u32_e32 v59, 2, v57
	v_add_u32_e32 v64, 3, v57
	v_cmp_gt_u32_e64 s[22:23], v59, v149
	v_cmp_gt_u32_e64 s[24:25], v64, v149
	s_nop 0
	v_cndmask_b32_e64 v114, v114, v246, s[22:23]
	v_cndmask_b32_e64 v115, v115, v246, s[24:25]
	v_max3_f32 v58, v58, v114, v115
	v_add_u32_e32 v59, 16, v57
	v_add_u32_e32 v64, 17, v57
	v_cmp_gt_u32_e64 s[26:27], v59, v149
	v_cmp_gt_u32_e64 s[28:29], v64, v149
	s_nop 0
	v_cndmask_b32_e64 v116, v116, v246, s[26:27]
	v_cndmask_b32_e64 v117, v117, v246, s[28:29]
	v_max3_f32 v58, v58, v116, v117
	v_add_u32_e32 v59, 18, v57
	v_add_u32_e32 v57, 19, v57
	v_cmp_gt_u32_e64 s[30:31], v59, v149
	v_cmp_gt_u32_e64 s[34:35], v57, v149
	s_nop 0
	v_cndmask_b32_e64 v118, v118, v246, s[30:31]
	v_cndmask_b32_e64 v119, v119, v246, s[34:35]
	v_max3_f32 v57, v58, v118, v119
	v_mov_b32_e32 v59, v57
	v_mov_b32_e32 v64, v57
	s_nop 1
	v_permlane32_swap_b32_e32 v59, v64
	v_max3_f32 v57, v57, v59, v64
	s_nop 1
	v_mov_b32_e32 v59, v57
	v_mov_b32_e32 v64, v57
	s_nop 1
	v_permlane16_swap_b32_e32 v59, v64
	v_max_f32_e32 v57, v57, v59
	v_max3_f32 v175, v145, v57, v64
	v_sub_f32_e32 v57, v145, v175
	v_exp_f32_e32 v72, v57
	v_sub_f32_e32 v57, v112, v175
	v_exp_f32_e32 v57, v57
	v_sub_f32_e32 v64, v113, v175
	v_exp_f32_e32 v64, v64
	s_nop 0
	v_sub_f32_e32 v65, v114, v175
	v_exp_f32_e32 v65, v65
	v_sub_f32_e32 v66, v115, v175
	v_add_f32_e32 v59, 0, v57
	v_exp_f32_e32 v66, v66
	v_sub_f32_e32 v67, v116, v175
	v_mov_b32_e32 v177, v144
	v_add_f32_e32 v59, v64, v59
	v_exp_f32_e32 v67, v67
	v_sub_f32_e32 v70, v117, v175
	v_cvt_pk_bf16_f32 v64, v57, v64
	v_exp_f32_e32 v70, v70
	v_sub_f32_e32 v71, v118, v175
	v_sub_f32_e32 v73, v119, v175
	v_mov_b32_e32 v74, 1.0
	v_exp_f32_e32 v71, v71
	v_exp_f32_e32 v73, v73
	v_add_f32_e32 v59, v65, v59
	v_add_f32_e32 v59, v66, v59
	v_add_f32_e32 v59, v67, v59
	v_add_f32_e32 v59, v70, v59
	v_mov_b32_e32 v57, 0
	v_add_f32_e32 v59, v71, v59
	v_cvt_pk_bf16_f32 v65, v65, v66
	v_cvt_pk_bf16_f32 v66, v67, v70
	v_cvt_pk_bf16_f32 v67, v71, v73
	v_add_f32_e32 v58, 0, v57
	v_mov_b32_e32 v56, 0
	v_pk_mul_f32 v[42:43], v[42:43], v[72:73] op_sel_hi:[1,0]
	v_pk_mul_f32 v[40:41], v[40:41], v[72:73] op_sel_hi:[1,0]
	v_add_f32_e32 v176, v73, v59
	v_add_f32_e32 v178, v56, v58
	v_cvt_pk_bf16_f32 v68, v57, 0
	v_cvt_pk_bf16_f32 v70, v56, 0
	v_mov_b32_e32 v69, v153
	v_mov_b32_e32 v71, v153
	s_waitcnt lgkmcnt(10)
	v_mfma_f32_16x16x32_bf16 v[56:59], v[140:143], v[64:67], v[40:43]
	v_fmac_f32_e32 v176, v147, v72
	v_fmac_f32_e32 v178, v146, v74
	s_nop 0
	v_pk_mul_f32 v[42:43], v[46:47], v[74:75] op_sel_hi:[1,0]
	v_pk_mul_f32 v[40:41], v[44:45], v[74:75] op_sel_hi:[1,0]
	s_nop 1
	v_mfma_f32_16x16x32_bf16 v[112:115], v[140:143], v[68:71], v[40:43]
	s_nop 2
	v_mul_f32_e64 v42, v50, v72
	v_mul_f32_e64 v43, v51, v72
	v_pk_mul_f32 v[40:41], v[48:49], v[72:73] op_sel_hi:[1,0]
	v_add_u32_e32 v48, s40, v227
	v_min_i32_e32 v49, s75, v48
	s_waitcnt lgkmcnt(8)
	v_mfma_f32_16x16x32_bf16 v[116:119], v[132:135], v[64:67], v[40:43]
	s_nop 2
	v_mul_f32_e64 v42, v54, v74
	v_mul_f32_e64 v43, v55, v74
	v_pk_mul_f32 v[40:41], v[52:53], v[74:75] op_sel_hi:[1,0]
	s_nop 1
	v_mfma_f32_16x16x32_bf16 v[120:123], v[132:135], v[68:71], v[40:43]
	s_nop 2
	v_mul_f32_e64 v42, v90, v72
	v_mul_f32_e64 v43, v91, v72
	v_pk_mul_f32 v[40:41], v[88:89], v[72:73] op_sel_hi:[1,0]
	s_waitcnt lgkmcnt(6)
	s_nop 0
	v_mfma_f32_16x16x32_bf16 v[124:127], v[128:131], v[64:67], v[40:43]
	s_nop 2
	v_mul_f32_e64 v42, v102, v74
	v_mul_f32_e64 v43, v103, v74
	v_pk_mul_f32 v[40:41], v[100:101], v[74:75] op_sel_hi:[1,0]
	s_nop 1
	v_mfma_f32_16x16x32_bf16 v[128:131], v[128:131], v[68:71], v[40:43]
	s_nop 2
	v_mul_f32_e64 v42, v106, v72
	v_mul_f32_e64 v43, v107, v72
	v_pk_mul_f32 v[40:41], v[104:105], v[72:73] op_sel_hi:[1,0]
	s_waitcnt lgkmcnt(4)
	s_nop 0
	v_mfma_f32_16x16x32_bf16 v[132:135], v[136:139], v[64:67], v[40:43]
	s_nop 2
	v_mul_f32_e64 v42, v110, v74
	v_mul_f32_e64 v43, v111, v74
	v_pk_mul_f32 v[40:41], v[108:109], v[74:75] op_sel_hi:[1,0]
	s_nop 1
	v_mfma_f32_16x16x32_bf16 v[136:139], v[136:139], v[68:71], v[40:43]
	s_nop 2
	v_add_u32_e32 v40, s40, v222
	v_med3_i32 v40, v40, 0, s75
	v_lshl_add_u32 v40, v40, 9, v152
	global_load_dwordx4 v[64:67], v40, s[98:99]
	v_add_u32_e32 v40, s40, v223
	v_med3_i32 v40, v40, 0, s75
	v_lshl_add_u32 v40, v40, 9, v152
	global_load_dwordx4 v[68:71], v40, s[98:99]
	v_add_u32_e32 v40, s40, v224
	v_med3_i32 v40, v40, 0, s75
	v_lshl_add_u32 v40, v40, 9, v152
	global_load_dwordx4 v[72:75], v40, s[98:99]
	v_add_u32_e32 v40, s40, v225
	v_med3_i32 v40, v40, 0, s75
	v_lshl_add_u32 v40, v40, 9, v152
	global_load_dwordx4 v[88:91], v40, s[98:99]
	v_add_u32_e32 v40, s40, v226
	v_med3_i32 v40, v40, 0, s75
	v_cmp_lt_i32_e32 vcc, -1, v48
	s_nop 1
	v_cndmask_b32_e32 v48, 0, v49, vcc
	v_lshl_add_u32 v44, v40, 9, v158
	v_lshl_add_u32 v52, v48, 9, v158
	global_load_dwordx4 v[40:43], v44, s[100:101]
	s_nop 0
	global_load_dwordx4 v[44:47], v44, s[100:101] offset:64
	s_nop 0
	global_load_dwordx4 v[48:51], v52, s[100:101]
	s_nop 0
	global_load_dwordx4 v[52:55], v52, s[100:101] offset:64
	ds_read_b64_tr_b16 v[102:103], v169 offset:2304
	ds_read_b64_tr_b16 v[100:101], v169
	ds_read_b64_tr_b16 v[108:109], v169 offset:32
	ds_read_b64_tr_b16 v[110:111], v169 offset:2336
	ds_read_b64_tr_b16 v[144:145], v169 offset:64
	ds_read_b64_tr_b16 v[146:147], v169 offset:2368
	ds_read_b64_tr_b16 v[140:141], v169 offset:96
	ds_read_b64_tr_b16 v[142:143], v169 offset:2400
	s_waitcnt vmcnt(15)
	ds_write_b128 v241, v[16:19] offset:4608
	s_waitcnt vmcnt(14)
	ds_write_b128 v242, v[60:63] offset:4608
	s_waitcnt vmcnt(13)
	ds_write_b128 v243, v[92:95] offset:4608
	s_waitcnt vmcnt(12)
	ds_write_b128 v244, v[96:99] offset:4608
	v_mfma_f32_16x16x32_bf16 v[16:19], v[84:87], v[4:7], 0
	v_mfma_f32_16x16x32_bf16 v[60:63], v[76:79], v[4:7], 0
	v_mfma_f32_16x16x32_bf16 v[16:19], v[80:83], v[8:11], v[16:19]
	v_mfma_f32_16x16x32_bf16 v[60:63], v[20:23], v[8:11], v[60:63]
	s_nop 5
	v_sub_u32_e32 v21, v198, v150
	v_add_u32_e32 v23, 1, v21
	v_cmp_gt_u32_e64 s[0:1], v23, v149
	v_cmp_gt_u32_e32 vcc, v21, v149
	s_nop 0
	v_cndmask_b32_e64 v17, v17, v246, s[0:1]
	s_nop 0
	v_cndmask_b32_e32 v16, v16, v246, vcc
	v_max_f32_e32 v22, 0xf149f2ca, v16
	v_max_f32_e32 v22, v22, v17
	v_add_u32_e32 v23, 2, v21
	v_add_u32_e32 v76, 3, v21
	v_cmp_gt_u32_e64 s[22:23], v23, v149
	v_cmp_gt_u32_e64 s[24:25], v76, v149
	s_nop 0
	v_cndmask_b32_e64 v18, v18, v246, s[22:23]
	v_cndmask_b32_e64 v19, v19, v246, s[24:25]
	v_max3_f32 v22, v22, v18, v19
	v_add_u32_e32 v23, 16, v21
	v_add_u32_e32 v76, 17, v21
	v_cmp_gt_u32_e64 s[26:27], v23, v149
	v_cmp_gt_u32_e64 s[28:29], v76, v149
	s_nop 0
	v_cndmask_b32_e64 v60, v60, v246, s[26:27]
	v_cndmask_b32_e64 v61, v61, v246, s[28:29]
	v_max3_f32 v22, v22, v60, v61
	v_add_u32_e32 v23, 18, v21
	v_add_u32_e32 v21, 19, v21
	v_cmp_gt_u32_e64 s[30:31], v23, v149
	v_cmp_gt_u32_e64 s[34:35], v21, v149
	s_nop 0
	v_cndmask_b32_e64 v62, v62, v246, s[30:31]
	v_cndmask_b32_e64 v63, v63, v246, s[34:35]
	v_max3_f32 v21, v22, v62, v63
	v_mov_b32_e32 v23, v21
	v_mov_b32_e32 v76, v21
	s_nop 1
	v_permlane32_swap_b32_e32 v23, v76
	v_max3_f32 v21, v21, v23, v76
	s_nop 1
	v_mov_b32_e32 v23, v21
	v_mov_b32_e32 v76, v21
	s_nop 1
	v_permlane16_swap_b32_e32 v23, v76
	v_max_f32_e32 v21, v21, v23
	v_max3_f32 v151, v175, v21, v76
	v_sub_f32_e32 v16, v16, v151
	v_exp_f32_e32 v16, v16
	v_sub_f32_e32 v17, v17, v151
	v_exp_f32_e32 v17, v17
	v_sub_f32_e32 v18, v18, v151
	v_exp_f32_e32 v18, v18
	v_sub_f32_e32 v19, v19, v151
	v_exp_f32_e32 v19, v19
	v_sub_f32_e32 v23, v60, v151
	v_sub_f32_e32 v21, v175, v151
	v_exp_f32_e32 v23, v23
	v_sub_f32_e32 v60, v61, v151
	v_exp_f32_e32 v76, v21
	v_add_f32_e32 v21, 0, v16
	v_exp_f32_e32 v60, v60
	v_sub_f32_e32 v61, v62, v151
	v_add_f32_e32 v21, v17, v21
	v_exp_f32_e32 v61, v61
	v_sub_f32_e32 v62, v63, v151
	v_add_f32_e32 v21, v18, v21
	v_exp_f32_e32 v62, v62
	v_add_f32_e32 v21, v19, v21
	v_add_f32_e32 v21, v23, v21
	v_add_f32_e32 v21, v60, v21
	v_add_f32_e32 v21, v61, v21
	v_mov_b32_e32 v175, v177
	v_add_f32_e32 v149, v62, v21
	v_cvt_pk_bf16_f32 v16, v16, v17
	v_cvt_pk_bf16_f32 v17, v18, v19
	v_cvt_pk_bf16_f32 v18, v23, v60
	v_mov_b32_e32 v60, 1.0
	v_cvt_pk_bf16_f32 v19, v61, v62
	v_mov_b32_e32 v21, 0
	v_add_f32_e32 v22, 0, v21
	v_mov_b32_e32 v23, 0
	v_pk_mul_f32 v[58:59], v[58:59], v[76:77] op_sel_hi:[1,0]
	v_pk_mul_f32 v[56:57], v[56:57], v[76:77] op_sel_hi:[1,0]
	v_add_f32_e32 v150, v23, v22
	v_cvt_pk_bf16_f32 v20, v21, 0
	v_cvt_pk_bf16_f32 v22, v23, 0
	v_mov_b32_e32 v21, v153
	v_mov_b32_e32 v23, v153
	s_waitcnt lgkmcnt(10)
	v_mfma_f32_16x16x32_bf16 v[96:99], v[100:103], v[16:19], v[56:59]
	v_fmac_f32_e32 v149, v176, v76
	v_fmac_f32_e32 v150, v178, v60
	s_min_i32 s0, s76, 0
	v_pk_mul_f32 v[58:59], v[114:115], v[60:61] op_sel_hi:[1,0]
	v_pk_mul_f32 v[56:57], v[112:113], v[60:61] op_sel_hi:[1,0]
	s_sub_i32 s0, 15, s0
	s_sub_i32 s1, s75, s76
	v_mfma_f32_16x16x32_bf16 v[100:103], v[100:103], v[20:23], v[56:59]
	s_ashr_i32 s0, s0, 4
	s_ashr_i32 s1, s1, 4
	s_cmpk_lt_i32 s71, 0x3000
	v_pk_mul_f32 v[58:59], v[118:119], v[76:77] op_sel_hi:[1,0]
	v_pk_mul_f32 v[56:57], v[116:117], v[76:77] op_sel_hi:[1,0]
	s_waitcnt lgkmcnt(8)
	s_nop 0
	v_mfma_f32_16x16x32_bf16 v[104:107], v[108:111], v[16:19], v[56:59]
	s_nop 2
	v_mul_f32_e64 v58, v122, v60
	v_mul_f32_e64 v59, v123, v60
	v_pk_mul_f32 v[56:57], v[120:121], v[60:61] op_sel_hi:[1,0]
	s_nop 1
	v_mfma_f32_16x16x32_bf16 v[108:111], v[108:111], v[20:23], v[56:59]
	s_nop 2
	v_mul_f32_e64 v58, v126, v76
	v_mul_f32_e64 v59, v127, v76
	v_pk_mul_f32 v[56:57], v[124:125], v[76:77] op_sel_hi:[1,0]
	s_waitcnt lgkmcnt(6)
	s_nop 0
	v_mfma_f32_16x16x32_bf16 v[112:115], v[144:147], v[16:19], v[56:59]
	s_nop 2
	v_mul_f32_e64 v58, v130, v60
	v_mul_f32_e64 v59, v131, v60
	v_pk_mul_f32 v[56:57], v[128:129], v[60:61] op_sel_hi:[1,0]
	s_nop 1
	v_mfma_f32_16x16x32_bf16 v[116:119], v[144:147], v[20:23], v[56:59]
	v_max_i32_e32 v145, s0, v148
	s_nop 1
	v_pk_mul_f32 v[58:59], v[134:135], v[76:77] op_sel_hi:[1,0]
	v_pk_mul_f32 v[56:57], v[132:133], v[76:77] op_sel_hi:[1,0]
	s_waitcnt lgkmcnt(4)
	s_nop 0
	v_mfma_f32_16x16x32_bf16 v[120:123], v[140:143], v[16:19], v[56:59]
	v_mul_f32_e64 v18, v138, v60
	v_mul_f32_e64 v19, v139, v60
	v_pk_mul_f32 v[16:17], v[136:137], v[60:61] op_sel_hi:[1,0]
	v_add_u32_e32 v56, s40, v228
	s_nop 0
	v_mfma_f32_16x16x32_bf16 v[124:127], v[140:143], v[20:23], v[16:19]
	s_nop 1
	s_nop 0
	v_add_u32_e32 v16, s40, v213
	v_med3_i32 v16, v16, 0, s75
	v_lshl_add_u32 v16, v16, 9, v152
	global_load_dwordx4 v[76:79], v16, s[98:99]
	v_add_u32_e32 v16, s40, v215
	v_med3_i32 v16, v16, 0, s75
	v_lshl_add_u32 v16, v16, 9, v152
	global_load_dwordx4 v[80:83], v16, s[98:99]
	v_add_u32_e32 v16, s40, v217
	v_med3_i32 v16, v16, 0, s75
	v_lshl_add_u32 v16, v16, 9, v152
	global_load_dwordx4 v[84:87], v16, s[98:99]
	v_add_u32_e32 v16, s40, v219
	v_med3_i32 v16, v16, 0, s75
	v_lshl_add_u32 v16, v16, 9, v152
	global_load_dwordx4 v[92:95], v16, s[98:99]
	v_or_b32_e32 v16, s40, v167
	v_min_i32_e32 v16, s75, v16
	v_cndmask_b32_e64 v16, v16, 0, s[38:39]
	v_med3_i32 v56, v56, 0, s75
	v_lshl_add_u32 v20, v16, 9, v158
	v_lshl_add_u32 v60, v56, 9, v158
	global_load_dwordx4 v[16:19], v20, s[100:101]
	s_nop 0
	global_load_dwordx4 v[20:23], v20, s[100:101] offset:64
	s_nop 0
	global_load_dwordx4 v[56:59], v60, s[100:101]
	s_nop 0
	global_load_dwordx4 v[60:63], v60, s[100:101] offset:64
	ds_read_b64_tr_b16 v[132:133], v169 offset:6912
	ds_read_b64_tr_b16 v[130:131], v169 offset:4608
	ds_read_b64_tr_b16 v[134:135], v169 offset:4640
	ds_read_b64_tr_b16 v[136:137], v169 offset:6944
	ds_read_b64_tr_b16 v[138:139], v169 offset:4672
	ds_read_b64_tr_b16 v[140:141], v169 offset:6976
	ds_read_b64_tr_b16 v[176:177], v169 offset:4704
	ds_read_b64_tr_b16 v[178:179], v169 offset:7008
	s_waitcnt vmcnt(15)
	ds_write_b128 v241, v[64:67]
	s_waitcnt vmcnt(14)
	ds_write_b128 v242, v[68:71]
	s_waitcnt vmcnt(13)
	ds_write_b128 v243, v[72:75]
	s_waitcnt vmcnt(12)
	ds_write_b128 v244, v[88:91]
	v_mfma_f32_16x16x32_bf16 v[24:27], v[24:27], v[12:15], 0
	v_mfma_f32_16x16x32_bf16 v[24:27], v[28:31], v[0:3], v[24:27]
	v_mfma_f32_16x16x32_bf16 v[28:31], v[32:35], v[12:15], 0
	v_add_u32_e32 v32, 0x7f8, v249
	v_ashrrev_i32_e32 v32, 4, v32
	v_min3_i32 v32, v32, s1, v248
	v_sub_u32_e32 v144, v32, v145
	v_sub_u32_e32 v33, v154, v145
	s_nop 2
	v_add_u32_e32 v35, 1, v33
	v_cmp_gt_u32_e64 s[0:1], v35, v144
	v_cmp_gt_u32_e32 vcc, v33, v144
	s_nop 0
	v_cndmask_b32_e64 v25, v25, v246, s[0:1]
	s_nop 0
	v_cndmask_b32_e32 v24, v24, v246, vcc
	v_max_f32_e32 v34, 0xf149f2ca, v24
	v_mfma_f32_16x16x32_bf16 v[28:31], v[36:39], v[0:3], v[28:31]
	v_max_f32_e32 v34, v34, v25
	v_add_u32_e32 v35, 2, v33
	v_add_u32_e32 v36, 3, v33
	v_cmp_gt_u32_e64 s[22:23], v35, v144
	v_cmp_gt_u32_e64 s[24:25], v36, v144
	s_nop 0
	v_cndmask_b32_e64 v26, v26, v246, s[22:23]
	v_cndmask_b32_e64 v27, v27, v246, s[24:25]
	v_max3_f32 v34, v34, v26, v27
	v_add_u32_e32 v35, 16, v33
	v_add_u32_e32 v36, 17, v33
	v_cmp_gt_u32_e64 s[26:27], v35, v144
	v_cmp_gt_u32_e64 s[28:29], v36, v144
	s_nop 0
	v_cndmask_b32_e64 v28, v28, v246, s[26:27]
	v_cndmask_b32_e64 v29, v29, v246, s[28:29]
	v_max3_f32 v34, v34, v28, v29
	v_add_u32_e32 v35, 18, v33
	v_add_u32_e32 v33, 19, v33
	v_cmp_gt_u32_e64 s[30:31], v35, v144
	v_cmp_gt_u32_e64 s[34:35], v33, v144
	s_nop 0
	v_cndmask_b32_e64 v30, v30, v246, s[30:31]
	v_cndmask_b32_e64 v31, v31, v246, s[34:35]
	v_max3_f32 v33, v34, v30, v31
	s_nop 1
	v_mov_b32_e32 v34, v33
	v_mov_b32_e32 v35, v33
	s_nop 1
	v_permlane32_swap_b32_e32 v34, v35
	v_max3_f32 v33, v33, v34, v35
	s_nop 1
	v_mov_b32_e32 v34, v33
	v_mov_b32_e32 v37, v33
	s_nop 1
	v_permlane16_swap_b32_e32 v34, v37
	v_max_f32_e32 v38, v33, v34
	v_max3_f32 v128, v175, v38, v37
	v_sub_f32_e32 v24, v24, v128
	v_exp_f32_e32 v24, v24
	v_sub_f32_e32 v37, v175, v128
	v_exp_f32_e32 v38, v37
	v_mov_b32_e32 v129, v151
	v_cndmask_b32_e64 v37, v24, 0, vcc
	v_sub_f32_e32 v24, v25, v128
	v_exp_f32_e32 v24, v24
	v_mov_b32_e32 v36, 1.0
	v_cndmask_b32_e64 v65, v24, 0, s[0:1]
	v_sub_f32_e32 v24, v26, v128
	v_exp_f32_e32 v24, v24
	v_mov_b32_e32 v33, v153
	v_mov_b32_e32 v35, v153
	v_mov_b32_e32 v39, 0
	v_cndmask_b32_e64 v66, v24, 0, s[22:23]
	v_sub_f32_e32 v24, v27, v128
	v_exp_f32_e32 v24, v24
	s_nop 0
	v_cndmask_b32_e64 v67, v24, 0, s[24:25]
	v_sub_f32_e32 v24, v28, v128
	v_exp_f32_e32 v24, v24
	v_mov_b32_e32 v64, 0
	v_cvt_pk_bf16_f32 v32, v39, 0
	v_cvt_pk_bf16_f32 v34, v64, 0
	v_cndmask_b32_e64 v68, v24, 0, s[26:27]
	v_sub_f32_e32 v24, v29, v128
	v_exp_f32_e32 v24, v24
	v_pk_mul_f32 v[28:29], v[96:97], v[36:37] op_sel_hi:[1,0]
	v_cvt_pk_bf16_f32 v25, v66, v67
	v_cndmask_b32_e64 v69, v24, 0, s[28:29]
	v_sub_f32_e32 v24, v30, v128
	v_exp_f32_e32 v24, v24
	v_cvt_pk_bf16_f32 v26, v68, v69
	v_cndmask_b32_e64 v70, v24, 0, s[30:31]
	v_sub_f32_e32 v24, v31, v128
	v_exp_f32_e32 v24, v24
	v_pk_mul_f32 v[30:31], v[98:99], v[36:37] op_sel_hi:[1,0]
	v_cndmask_b32_e64 v71, v24, 0, s[34:35]
	v_cvt_pk_bf16_f32 v24, v37, v65
	v_cvt_pk_bf16_f32 v27, v70, v71
	s_waitcnt lgkmcnt(10)
	v_mfma_f32_16x16x32_bf16 v[96:99], v[130:133], v[32:35], v[28:31]
	s_nop 2
	v_mul_f32_e64 v30, v102, v38
	v_mul_f32_e64 v31, v103, v38
	v_pk_mul_f32 v[28:29], v[100:101], v[38:39] op_sel_hi:[1,0]
	s_nop 1
	v_mfma_f32_16x16x32_bf16 v[100:103], v[130:133], v[24:27], v[28:31]
	s_nop 2
	v_mul_f32_e64 v30, v106, v36
	v_mul_f32_e64 v31, v107, v36
	v_pk_mul_f32 v[28:29], v[104:105], v[36:37] op_sel_hi:[1,0]
	s_waitcnt lgkmcnt(8)
	s_nop 0
	v_mfma_f32_16x16x32_bf16 v[104:107], v[134:137], v[32:35], v[28:31]
	s_nop 2
	v_mul_f32_e64 v30, v110, v38
	v_mul_f32_e64 v31, v111, v38
	v_pk_mul_f32 v[28:29], v[108:109], v[38:39] op_sel_hi:[1,0]
	s_nop 1
	v_mfma_f32_16x16x32_bf16 v[108:111], v[134:137], v[24:27], v[28:31]
	s_nop 2
	v_mul_f32_e64 v30, v114, v36
	v_mul_f32_e64 v31, v115, v36
	v_pk_mul_f32 v[28:29], v[112:113], v[36:37] op_sel_hi:[1,0]
	s_waitcnt lgkmcnt(6)
	s_nop 0
	v_mfma_f32_16x16x32_bf16 v[112:115], v[138:141], v[32:35], v[28:31]
	s_nop 2
	v_mul_f32_e64 v30, v118, v38
	v_mul_f32_e64 v31, v119, v38
	v_pk_mul_f32 v[28:29], v[116:117], v[38:39] op_sel_hi:[1,0]
	s_nop 1
	v_mfma_f32_16x16x32_bf16 v[116:119], v[138:141], v[24:27], v[28:31]
	s_nop 2
	v_mul_f32_e64 v30, v122, v36
	v_mul_f32_e64 v31, v123, v36
	v_pk_mul_f32 v[28:29], v[120:121], v[36:37] op_sel_hi:[1,0]
	s_waitcnt lgkmcnt(4)
	s_nop 0
	v_mfma_f32_16x16x32_bf16 v[120:123], v[176:179], v[32:35], v[28:31]
	v_add_u32_e32 v32, s40, v234
	s_nop 0
	s_nop 0
	v_pk_mul_f32 v[30:31], v[126:127], v[38:39] op_sel_hi:[1,0]
	v_pk_mul_f32 v[28:29], v[124:125], v[38:39] op_sel_hi:[1,0]
	s_nop 1
	v_mfma_f32_16x16x32_bf16 v[124:127], v[176:179], v[24:27], v[28:31]
	v_add_f32_e32 v24, 0, v37
	v_add_f32_e32 v24, v65, v24
	v_add_f32_e32 v24, v66, v24
	v_add_f32_e32 v24, v67, v24
	v_add_f32_e32 v24, v68, v24
	v_add_f32_e32 v24, v69, v24
	v_add_f32_e32 v24, v70, v24
	v_add_f32_e32 v130, v71, v24
	v_add_f32_e32 v24, 0, v39
	v_add_f32_e32 v131, v64, v24
	v_add_u32_e32 v24, s40, v229
	v_fmac_f32_e32 v131, v149, v36
	v_fmac_f32_e32 v130, v150, v38
	v_med3_i32 v24, v24, 0, s75
	v_lshl_add_u32 v24, v24, 9, v152
	global_load_dwordx4 v[64:67], v24, s[98:99]
	v_add_u32_e32 v24, s40, v230
	v_med3_i32 v24, v24, 0, s75
	v_lshl_add_u32 v24, v24, 9, v152
	global_load_dwordx4 v[68:71], v24, s[98:99]
	v_add_u32_e32 v24, s40, v231
	v_med3_i32 v24, v24, 0, s75
	v_lshl_add_u32 v24, v24, 9, v152
	global_load_dwordx4 v[72:75], v24, s[98:99]
	v_add_u32_e32 v24, s40, v232
	v_med3_i32 v24, v24, 0, s75
	v_lshl_add_u32 v24, v24, 9, v152
	global_load_dwordx4 v[88:91], v24, s[98:99]
	v_add_u32_e32 v24, s40, v233
	v_med3_i32 v24, v24, 0, s75
	v_med3_i32 v32, v32, 0, s75
	v_lshl_add_u32 v28, v24, 9, v158
	v_lshl_add_u32 v36, v32, 9, v158
	global_load_dwordx4 v[24:27], v28, s[100:101]
	s_nop 0
	global_load_dwordx4 v[28:31], v28, s[100:101] offset:64
	s_nop 0
	global_load_dwordx4 v[32:35], v36, s[100:101]
	s_nop 0
	global_load_dwordx4 v[36:39], v36, s[100:101] offset:64
	ds_read_b64_tr_b16 v[134:135], v169 offset:2304
	ds_read_b64_tr_b16 v[132:133], v169
	ds_read_b64_tr_b16 v[136:137], v169 offset:32
	ds_read_b64_tr_b16 v[138:139], v169 offset:2336
	ds_read_b64_tr_b16 v[140:141], v169 offset:64
	ds_read_b64_tr_b16 v[142:143], v169 offset:2368
	ds_read_b64_tr_b16 v[176:177], v169 offset:96
	ds_read_b64_tr_b16 v[178:179], v169 offset:2400
	s_waitcnt vmcnt(15)
	ds_write_b128 v241, v[76:79] offset:4608
	s_waitcnt vmcnt(14)
	ds_write_b128 v242, v[80:83] offset:4608
	s_waitcnt vmcnt(13)
	ds_write_b128 v243, v[84:87] offset:4608
	s_waitcnt vmcnt(12)
	ds_write_b128 v244, v[92:95] offset:4608
	v_mfma_f32_16x16x32_bf16 v[40:43], v[40:43], v[12:15], 0
	s_nop 5
	v_mov_b32_e32 v77, v153
	v_mfma_f32_16x16x32_bf16 v[40:43], v[44:47], v[0:3], v[40:43]
	v_mfma_f32_16x16x32_bf16 v[44:47], v[48:51], v[12:15], 0
	v_sub_u32_e32 v48, v187, v145
	s_nop 1
	v_add_u32_e32 v51, 1, v48
	v_cmp_gt_u32_e64 s[0:1], v51, v144
	v_cmp_gt_u32_e32 vcc, v48, v144
	s_nop 0
	v_cndmask_b32_e64 v41, v41, v246, s[0:1]
	s_nop 0
	v_cndmask_b32_e32 v40, v40, v246, vcc
	v_max_f32_e32 v50, 0xf149f2ca, v40
	v_mfma_f32_16x16x32_bf16 v[44:47], v[52:55], v[0:3], v[44:47]
	v_max_f32_e32 v50, v50, v41
	v_add_u32_e32 v51, 2, v48
	v_add_u32_e32 v52, 3, v48
	v_cmp_gt_u32_e64 s[22:23], v51, v144
	v_cmp_gt_u32_e64 s[24:25], v52, v144
	v_mov_b32_e32 v79, v153
	v_cndmask_b32_e64 v42, v42, v246, s[22:23]
	v_cndmask_b32_e64 v43, v43, v246, s[24:25]
	v_max3_f32 v50, v50, v42, v43
	v_add_u32_e32 v51, 16, v48
	v_add_u32_e32 v52, 17, v48
	v_cmp_gt_u32_e64 s[26:27], v51, v144
	v_cmp_gt_u32_e64 s[28:29], v52, v144
	s_nop 0
	v_cndmask_b32_e64 v44, v44, v246, s[26:27]
	v_cndmask_b32_e64 v45, v45, v246, s[28:29]
	v_max3_f32 v50, v50, v44, v45
	v_add_u32_e32 v51, 18, v48
	v_add_u32_e32 v48, 19, v48
	v_cmp_gt_u32_e64 s[30:31], v51, v144
	v_cmp_gt_u32_e64 s[34:35], v48, v144
	s_nop 0
	v_cndmask_b32_e64 v46, v46, v246, s[30:31]
	v_cndmask_b32_e64 v47, v47, v246, s[34:35]
	v_max3_f32 v48, v50, v46, v47
	s_nop 1
	v_mov_b32_e32 v50, v48
	v_mov_b32_e32 v51, v48
	s_nop 1
	v_permlane32_swap_b32_e32 v50, v51
	v_max3_f32 v48, v48, v50, v51
	s_nop 1
	v_mov_b32_e32 v50, v48
	v_mov_b32_e32 v52, v48
	s_nop 1
	v_permlane16_swap_b32_e32 v50, v52
	v_max_f32_e32 v48, v48, v50
	v_max3_f32 v148, v128, v48, v52
	v_sub_f32_e32 v40, v40, v148
	v_exp_f32_e32 v40, v40
	v_sub_f32_e32 v41, v41, v148
	v_exp_f32_e32 v41, v41
	v_sub_f32_e32 v42, v42, v148
	v_exp_f32_e32 v42, v42
	v_sub_f32_e32 v43, v43, v148
	v_exp_f32_e32 v43, v43
	v_sub_f32_e32 v44, v44, v148
	v_mov_b32_e32 v146, v129
	v_sub_f32_e32 v48, v128, v148
	v_exp_f32_e32 v44, v44
	v_sub_f32_e32 v45, v45, v148
	v_exp_f32_e32 v86, v48
	v_add_f32_e32 v48, 0, v40
	v_exp_f32_e32 v45, v45
	v_sub_f32_e32 v46, v46, v148
	v_sub_f32_e32 v47, v47, v148
	v_mov_b32_e32 v84, 1.0
	v_add_f32_e32 v48, v41, v48
	v_exp_f32_e32 v46, v46
	v_exp_f32_e32 v47, v47
	v_add_f32_e32 v48, v42, v48
	v_add_f32_e32 v48, v43, v48
	v_add_f32_e32 v48, v44, v48
	v_add_f32_e32 v48, v45, v48
	v_mov_b32_e32 v49, 0
	v_mov_b32_e32 v51, 0
	v_add_f32_e32 v48, v46, v48
	v_cvt_pk_bf16_f32 v40, v40, v41
	v_cvt_pk_bf16_f32 v41, v42, v43
	v_cvt_pk_bf16_f32 v42, v44, v45
	v_cvt_pk_bf16_f32 v43, v46, v47
	v_pk_mul_f32 v[82:83], v[110:111], v[86:87] op_sel_hi:[1,0]
	v_pk_mul_f32 v[80:81], v[108:109], v[86:87] op_sel_hi:[1,0]
	v_add_f32_e32 v50, 0, v49
	v_cvt_pk_bf16_f32 v76, v49, 0
	v_cvt_pk_bf16_f32 v78, v51, 0
	v_add_f32_e32 v149, v47, v48
	v_pk_mul_f32 v[46:47], v[98:99], v[84:85] op_sel_hi:[1,0]
	v_pk_mul_f32 v[44:45], v[96:97], v[84:85] op_sel_hi:[1,0]
	s_waitcnt lgkmcnt(8)
	v_mfma_f32_16x16x32_bf16 v[96:99], v[136:139], v[40:43], v[80:83]
	v_add_f32_e32 v147, v51, v50
	v_pk_mul_f32 v[50:51], v[102:103], v[86:87] op_sel_hi:[1,0]
	v_pk_mul_f32 v[48:49], v[100:101], v[86:87] op_sel_hi:[1,0]
	v_pk_mul_f32 v[82:83], v[114:115], v[84:85] op_sel_hi:[1,0]
	v_pk_mul_f32 v[80:81], v[112:113], v[84:85] op_sel_hi:[1,0]
	v_pk_mul_f32 v[54:55], v[106:107], v[84:85] op_sel_hi:[1,0]
	v_pk_mul_f32 v[52:53], v[104:105], v[84:85] op_sel_hi:[1,0]
	s_waitcnt lgkmcnt(6)
	v_mfma_f32_16x16x32_bf16 v[100:103], v[140:143], v[76:79], v[80:83]
	v_fmac_f32_e32 v147, v131, v84
	v_fmac_f32_e32 v149, v130, v86
	s_nop 0
	v_pk_mul_f32 v[82:83], v[118:119], v[86:87] op_sel_hi:[1,0]
	v_pk_mul_f32 v[80:81], v[116:117], v[86:87] op_sel_hi:[1,0]
	v_mfma_f32_16x16x32_bf16 v[44:47], v[132:135], v[76:79], v[44:47]
	s_nop 0
	v_mfma_f32_16x16x32_bf16 v[104:107], v[140:143], v[40:43], v[80:83]
	s_nop 2
	v_mul_f32_e64 v82, v122, v84
	v_mul_f32_e64 v83, v123, v84
	v_pk_mul_f32 v[80:81], v[120:121], v[84:85] op_sel_hi:[1,0]
	v_mfma_f32_16x16x32_bf16 v[52:55], v[136:139], v[76:79], v[52:55]
	v_add_u32_e32 v84, s40, v240
	s_waitcnt lgkmcnt(4)
	v_mfma_f32_16x16x32_bf16 v[108:111], v[176:179], v[76:79], v[80:83]
	v_mul_f32_e64 v78, v126, v86
	v_mul_f32_e64 v79, v127, v86
	v_pk_mul_f32 v[76:77], v[124:125], v[86:87] op_sel_hi:[1,0]
	v_mfma_f32_16x16x32_bf16 v[48:51], v[132:135], v[40:43], v[48:51]
	s_nop 0
	v_mfma_f32_16x16x32_bf16 v[112:115], v[176:179], v[40:43], v[76:79]
	v_add_u32_e32 v40, s40, v235
	s_nop 1
	v_add_u32_e32 v76, s40, v236
	v_med3_i32 v40, v40, 0, s75
	v_med3_i32 v76, v76, 0, s75
	v_lshl_add_u32 v40, v40, 9, v152
	v_lshl_add_u32 v76, v76, 9, v152
	global_load_dwordx4 v[40:43], v40, s[98:99]
	s_nop 0
	global_load_dwordx4 v[116:119], v76, s[98:99]
	v_add_u32_e32 v76, s40, v237
	v_med3_i32 v76, v76, 0, s75
	v_lshl_add_u32 v76, v76, 9, v152
	global_load_dwordx4 v[120:123], v76, s[98:99]
	v_add_u32_e32 v76, s40, v238
	v_med3_i32 v76, v76, 0, s75
	v_lshl_add_u32 v76, v76, 9, v152
	global_load_dwordx4 v[124:127], v76, s[98:99]
	v_add_u32_e32 v76, s40, v239
	v_med3_i32 v76, v76, 0, s75
	v_med3_i32 v84, v84, 0, s75
	v_lshl_add_u32 v80, v76, 9, v158
	v_lshl_add_u32 v84, v84, 9, v158
	global_load_dwordx4 v[76:79], v80, s[100:101]
	s_nop 0
	global_load_dwordx4 v[80:83], v80, s[100:101] offset:64
	s_nop 0
	global_load_dwordx4 v[92:95], v84, s[100:101]
	s_nop 0
	global_load_dwordx4 v[84:87], v84, s[100:101] offset:64
	ds_read_b64_tr_b16 v[142:143], v169 offset:6912
	ds_read_b64_tr_b16 v[140:141], v169 offset:4608
	ds_read_b64_tr_b16 v[136:137], v169 offset:4640
	ds_read_b64_tr_b16 v[138:139], v169 offset:6944
	ds_read_b64_tr_b16 v[132:133], v169 offset:4672
	ds_read_b64_tr_b16 v[134:135], v169 offset:6976
	ds_read_b64_tr_b16 v[128:129], v169 offset:4704
	ds_read_b64_tr_b16 v[130:131], v169 offset:7008
	s_waitcnt vmcnt(15)
	ds_write_b128 v241, v[64:67]
	s_waitcnt vmcnt(14)
	ds_write_b128 v242, v[68:71]
	s_waitcnt vmcnt(13)
	ds_write_b128 v243, v[72:75]
	s_waitcnt vmcnt(12)
	ds_write_b128 v244, v[88:91]
	v_mfma_f32_16x16x32_bf16 v[16:19], v[16:19], v[12:15], 0
	v_mfma_f32_16x16x32_bf16 v[16:19], v[20:23], v[0:3], v[16:19]
	v_mfma_f32_16x16x32_bf16 v[20:23], v[56:59], v[12:15], 0
	s_nop 2
	v_sub_u32_e32 v56, v192, v145
	v_add_u32_e32 v59, 1, v56
	v_cmp_gt_u32_e64 s[0:1], v59, v144
	v_cmp_gt_u32_e32 vcc, v56, v144
	s_nop 0
	v_cndmask_b32_e64 v17, v17, v246, s[0:1]
	s_nop 0
	v_cndmask_b32_e32 v16, v16, v246, vcc
	v_max_f32_e32 v58, 0xf149f2ca, v16
	v_mfma_f32_16x16x32_bf16 v[20:23], v[60:63], v[0:3], v[20:23]
	v_max_f32_e32 v58, v58, v17
	v_add_u32_e32 v59, 2, v56
	v_add_u32_e32 v60, 3, v56
	v_cmp_gt_u32_e64 s[22:23], v59, v144
	v_cmp_gt_u32_e64 s[24:25], v60, v144
	v_mov_b32_e32 v61, v153
	v_cndmask_b32_e64 v18, v18, v246, s[22:23]
	v_cndmask_b32_e64 v19, v19, v246, s[24:25]
	v_max3_f32 v58, v58, v18, v19
	v_add_u32_e32 v59, 16, v56
	v_add_u32_e32 v60, 17, v56
	v_cmp_gt_u32_e64 s[26:27], v59, v144
	v_cmp_gt_u32_e64 s[28:29], v60, v144
	v_mov_b32_e32 v63, v153
	v_cndmask_b32_e64 v20, v20, v246, s[26:27]
	v_cndmask_b32_e64 v60, v21, v246, s[28:29]
	v_max3_f32 v58, v58, v20, v60
	v_add_u32_e32 v59, 18, v56
	v_add_u32_e32 v56, 19, v56
	v_cmp_gt_u32_e64 s[30:31], v59, v144
	v_cmp_gt_u32_e64 s[34:35], v56, v144
	s_nop 0
	v_cndmask_b32_e64 v22, v22, v246, s[30:31]
	v_cndmask_b32_e64 v23, v23, v246, s[34:35]
	v_max3_f32 v56, v58, v22, v23
	s_nop 1
	v_mov_b32_e32 v58, v56
	v_mov_b32_e32 v59, v56
	s_nop 1
	v_permlane32_swap_b32_e32 v58, v59
	v_max3_f32 v56, v56, v58, v59
	s_nop 1
	v_mov_b32_e32 v58, v56
	v_mov_b32_e32 v65, v56
	s_nop 1
	v_permlane16_swap_b32_e32 v58, v65
	v_max_f32_e32 v56, v56, v58
	v_max3_f32 v151, v148, v56, v65
	v_sub_f32_e32 v16, v16, v151
	v_exp_f32_e32 v16, v16
	v_sub_f32_e32 v17, v17, v151
	v_mov_b32_e32 v150, v146
	v_exp_f32_e32 v17, v17
	v_sub_f32_e32 v18, v18, v151
	v_exp_f32_e32 v18, v18
	v_sub_f32_e32 v19, v19, v151
	v_mov_b32_e32 v68, 1.0
	v_exp_f32_e32 v19, v19
	v_sub_f32_e32 v20, v20, v151
	v_sub_f32_e32 v56, v148, v151
	v_exp_f32_e32 v20, v20
	v_sub_f32_e32 v21, v21, v151
	v_exp_f32_e32 v72, v56
	v_add_f32_e32 v56, 0, v16
	v_exp_f32_e32 v21, v21
	v_sub_f32_e32 v22, v22, v151
	v_add_f32_e32 v56, v17, v56
	v_exp_f32_e32 v22, v22
	v_sub_f32_e32 v23, v23, v151
	v_add_f32_e32 v56, v18, v56
	v_exp_f32_e32 v23, v23
	v_mov_b32_e32 v57, 0
	v_add_f32_e32 v56, v19, v56
	v_add_f32_e32 v58, 0, v57
	v_mov_b32_e32 v59, 0
	v_add_f32_e32 v56, v20, v56
	v_cndmask_b32_e64 v21, v21, 0, s[28:29]
	v_add_f32_e32 v146, v59, v58
	v_add_f32_e32 v56, v21, v56
	v_fmac_f32_e32 v146, v147, v68
	v_cvt_pk_bf16_f32 v60, v57, 0
	v_cvt_pk_bf16_f32 v62, v59, 0
	v_add_f32_e32 v56, v22, v56
	v_cvt_pk_bf16_f32 v64, v16, v17
	v_cvt_pk_bf16_f32 v65, v18, v19
	v_pk_mul_f32 v[18:19], v[46:47], v[68:69] op_sel_hi:[1,0]
	v_pk_mul_f32 v[16:17], v[44:45], v[68:69] op_sel_hi:[1,0]
	v_pk_mul_f32 v[46:47], v[54:55], v[68:69] op_sel_hi:[1,0]
	v_pk_mul_f32 v[44:45], v[52:53], v[68:69] op_sel_hi:[1,0]
	v_pk_mul_f32 v[54:55], v[102:103], v[68:69] op_sel_hi:[1,0]
	v_pk_mul_f32 v[52:53], v[100:101], v[68:69] op_sel_hi:[1,0]
	v_pk_mul_f32 v[70:71], v[110:111], v[68:69] op_sel_hi:[1,0]
	v_pk_mul_f32 v[68:69], v[108:109], v[68:69] op_sel_hi:[1,0]
	v_add_f32_e32 v147, v23, v56
	v_cvt_pk_bf16_f32 v66, v20, v21
	v_cvt_pk_bf16_f32 v67, v22, v23
	s_waitcnt lgkmcnt(10)
	v_mfma_f32_16x16x32_bf16 v[16:19], v[140:143], v[60:63], v[16:19]
	v_mul_f32_e64 v22, v50, v72
	v_mul_f32_e64 v23, v51, v72
	v_pk_mul_f32 v[20:21], v[48:49], v[72:73] op_sel_hi:[1,0]
	v_pk_mul_f32 v[50:51], v[98:99], v[72:73] op_sel_hi:[1,0]
	s_waitcnt lgkmcnt(8)
	v_mfma_f32_16x16x32_bf16 v[44:47], v[136:139], v[60:63], v[44:47]
	v_mul_f32_e64 v48, v96, v72
	v_mul_f32_e64 v49, v97, v72
	v_pk_mul_f32 v[58:59], v[106:107], v[72:73] op_sel_hi:[1,0]
	v_pk_mul_f32 v[56:57], v[104:105], v[72:73] op_sel_hi:[1,0]
	s_waitcnt lgkmcnt(6)
	v_mfma_f32_16x16x32_bf16 v[52:55], v[132:135], v[60:63], v[52:55]
	v_fmac_f32_e32 v147, v149, v72
	s_waitcnt lgkmcnt(4)
	v_mfma_f32_16x16x32_bf16 v[60:63], v[128:131], v[60:63], v[68:71]
	s_nop 2
	v_mul_f32_e64 v70, v114, v72
	v_mul_f32_e64 v71, v115, v72
	v_pk_mul_f32 v[68:69], v[112:113], v[72:73] op_sel_hi:[1,0]
	v_mfma_f32_16x16x32_bf16 v[20:23], v[140:143], v[64:67], v[20:23]
	v_mfma_f32_16x16x32_bf16 v[48:51], v[136:139], v[64:67], v[48:51]
	v_mfma_f32_16x16x32_bf16 v[56:59], v[132:135], v[64:67], v[56:59]
	v_mfma_f32_16x16x32_bf16 v[64:67], v[128:131], v[64:67], v[68:71]
	ds_read_b64_tr_b16 v[98:99], v169 offset:2304
	ds_read_b64_tr_b16 v[96:97], v169
	ds_read_b64_tr_b16 v[88:89], v169 offset:32
	ds_read_b64_tr_b16 v[90:91], v169 offset:2336
	ds_read_b64_tr_b16 v[72:73], v169 offset:64
	ds_read_b64_tr_b16 v[74:75], v169 offset:2368
	ds_read_b64_tr_b16 v[68:69], v169 offset:96
	ds_read_b64_tr_b16 v[70:71], v169 offset:2400
	s_waitcnt vmcnt(7)
	ds_write_b128 v241, v[40:43] offset:4608
	s_waitcnt vmcnt(6)
	ds_write_b128 v242, v[116:119] offset:4608
	s_waitcnt vmcnt(5)
	ds_write_b128 v243, v[120:123] offset:4608
	s_waitcnt vmcnt(4)
	ds_write_b128 v244, v[124:127] offset:4608
	v_mfma_f32_16x16x32_bf16 v[24:27], v[24:27], v[12:15], 0
	v_mfma_f32_16x16x32_bf16 v[24:27], v[28:31], v[0:3], v[24:27]
	s_nop 5
	v_mov_b32_e32 v41, v153
	v_mov_b32_e32 v43, v153
	v_mfma_f32_16x16x32_bf16 v[28:31], v[32:35], v[12:15], 0
	v_sub_u32_e32 v32, v197, v145
	v_add_u32_e32 v35, 1, v32
	v_cmp_gt_u32_e64 s[0:1], v35, v144
	v_cmp_gt_u32_e32 vcc, v32, v144
	s_nop 0
	v_cndmask_b32_e64 v25, v25, v246, s[0:1]
	s_nop 0
	v_cndmask_b32_e32 v24, v24, v246, vcc
	v_max_f32_e32 v34, 0xf149f2ca, v24
	v_mfma_f32_16x16x32_bf16 v[28:31], v[36:39], v[0:3], v[28:31]
	v_max_f32_e32 v34, v34, v25
	v_add_u32_e32 v35, 2, v32
	v_add_u32_e32 v36, 3, v32
	v_cmp_gt_u32_e64 s[22:23], v35, v144
	v_cmp_gt_u32_e64 s[24:25], v36, v144
	s_nop 0
	v_cndmask_b32_e64 v26, v26, v246, s[22:23]
	v_cndmask_b32_e64 v27, v27, v246, s[24:25]
	v_max3_f32 v34, v34, v26, v27
	v_add_u32_e32 v35, 16, v32
	v_add_u32_e32 v36, 17, v32
	v_cmp_gt_u32_e64 s[26:27], v35, v144
	v_cmp_gt_u32_e64 s[28:29], v36, v144
	s_nop 0
	v_cndmask_b32_e64 v28, v28, v246, s[26:27]
	v_cndmask_b32_e64 v29, v29, v246, s[28:29]
	v_max3_f32 v34, v34, v28, v29
	v_add_u32_e32 v35, 18, v32
	v_add_u32_e32 v32, 19, v32
	v_cmp_gt_u32_e64 s[30:31], v35, v144
	v_cmp_gt_u32_e64 s[34:35], v32, v144
	s_nop 0
	v_cndmask_b32_e64 v30, v30, v246, s[30:31]
	v_cndmask_b32_e64 v31, v31, v246, s[34:35]
	v_max3_f32 v32, v34, v30, v31
	s_nop 1
	v_mov_b32_e32 v34, v32
	v_mov_b32_e32 v35, v32
	s_nop 1
	v_permlane32_swap_b32_e32 v34, v35
	v_max3_f32 v32, v32, v34, v35
	s_nop 1
	v_mov_b32_e32 v101, v150
	v_mov_b32_e32 v106, 1.0
	v_mov_b32_e32 v34, v32
	v_mov_b32_e32 v36, v32
	s_nop 0
	s_nop 0
	v_permlane16_swap_b32_e32 v34, v36
	v_max_f32_e32 v32, v32, v34
	v_mov_b32_e32 v107, 0
	v_max3_f32 v100, v151, v32, v36
	v_sub_f32_e32 v24, v24, v100
	v_exp_f32_e32 v24, v24
	v_sub_f32_e32 v32, v151, v100
	v_exp_f32_e32 v108, v32
	v_cndmask_b32_e64 v110, v24, 0, vcc
	v_sub_f32_e32 v24, v25, v100
	v_exp_f32_e32 v24, v24
	v_mov_b32_e32 v109, 0
	v_cvt_pk_bf16_f32 v40, v107, 0
	v_cvt_pk_bf16_f32 v42, v109, 0
	v_cndmask_b32_e64 v111, v24, 0, s[0:1]
	v_sub_f32_e32 v24, v26, v100
	v_exp_f32_e32 v24, v24
	v_pk_mul_f32 v[18:19], v[18:19], v[106:107] op_sel_hi:[1,0]
	v_pk_mul_f32 v[16:17], v[16:17], v[106:107] op_sel_hi:[1,0]
	v_pk_mul_f32 v[34:35], v[54:55], v[106:107] op_sel_hi:[1,0]
	v_cndmask_b32_e64 v112, v24, 0, s[22:23]
	v_sub_f32_e32 v24, v27, v100
	v_exp_f32_e32 v24, v24
	v_pk_mul_f32 v[26:27], v[46:47], v[106:107] op_sel_hi:[1,0]
	v_pk_mul_f32 v[32:33], v[52:53], v[106:107] op_sel_hi:[1,0]
	v_pk_mul_f32 v[46:47], v[62:63], v[106:107] op_sel_hi:[1,0]
	v_cndmask_b32_e64 v113, v24, 0, s[24:25]
	v_sub_f32_e32 v24, v28, v100
	v_exp_f32_e32 v24, v24
	s_waitcnt lgkmcnt(10)
	v_mfma_f32_16x16x32_bf16 v[16:19], v[96:99], v[40:43], v[16:19]
	v_cvt_pk_bf16_f32 v102, v110, v111
	v_cvt_pk_bf16_f32 v103, v112, v113
	v_cndmask_b32_e64 v114, v24, 0, s[26:27]
	v_sub_f32_e32 v24, v29, v100
	v_exp_f32_e32 v24, v24
	s_waitcnt lgkmcnt(6)
	v_mfma_f32_16x16x32_bf16 v[32:35], v[72:75], v[40:43], v[32:35]
	v_mul_f32_e64 v28, v48, v108
	v_mul_f32_e64 v29, v49, v108
	v_add_f32_e32 v48, 0, v110
	v_cndmask_b32_e64 v115, v24, 0, s[28:29]
	v_sub_f32_e32 v24, v30, v100
	v_exp_f32_e32 v24, v24
	v_add_f32_e32 v48, v111, v48
	v_add_f32_e32 v48, v112, v48
	v_add_f32_e32 v48, v113, v48
	v_cndmask_b32_e64 v116, v24, 0, s[30:31]
	v_sub_f32_e32 v24, v31, v100
	v_exp_f32_e32 v24, v24
	v_add_f32_e32 v48, v114, v48
	v_add_f32_e32 v48, v115, v48
	v_cvt_pk_bf16_f32 v104, v114, v115
	v_cndmask_b32_e64 v117, v24, 0, s[34:35]
	v_pk_mul_f32 v[24:25], v[44:45], v[106:107] op_sel_hi:[1,0]
	v_pk_mul_f32 v[44:45], v[60:61], v[106:107] op_sel_hi:[1,0]
	v_cvt_pk_bf16_f32 v105, v116, v117
	v_mfma_f32_16x16x32_bf16 v[24:27], v[88:91], v[40:43], v[24:27]
	v_add_f32_e32 v48, v116, v48
	v_pk_mul_f32 v[38:39], v[58:59], v[108:109] op_sel_hi:[1,0]
	v_pk_mul_f32 v[36:37], v[56:57], v[108:109] op_sel_hi:[1,0]
	s_waitcnt lgkmcnt(4)
	v_mfma_f32_16x16x32_bf16 v[40:43], v[68:71], v[40:43], v[44:47]
	v_mul_f32_e64 v30, v50, v108
	v_mul_f32_e64 v31, v51, v108
	v_pk_mul_f32 v[22:23], v[22:23], v[108:109] op_sel_hi:[1,0]
	v_pk_mul_f32 v[20:21], v[20:21], v[108:109] op_sel_hi:[1,0]
	v_pk_mul_f32 v[46:47], v[66:67], v[108:109] op_sel_hi:[1,0]
	v_pk_mul_f32 v[44:45], v[64:65], v[108:109] op_sel_hi:[1,0]
	s_waitcnt vmcnt(3)
	s_waitcnt vmcnt(1)
	s_waitcnt vmcnt(0)
	v_mfma_f32_16x16x32_bf16 v[4:7], v[76:79], v[12:15], 0
	v_mfma_f32_16x16x32_bf16 v[10:13], v[92:95], v[12:15], 0
	s_nop 5
	v_sub_u32_e32 v9, v198, v145
	v_cmp_gt_u32_e64 s[34:35], v9, v144
	v_mov_b32_e32 v15, v153
	v_mfma_f32_16x16x32_bf16 v[4:7], v[80:83], v[0:3], v[4:7]
	v_mfma_f32_16x16x32_bf16 v[0:3], v[84:87], v[0:3], v[10:13]
	s_nop 2
	v_add_u32_e32 v12, 1, v9
	v_cmp_gt_u32_e64 s[30:31], v12, v144
	s_nop 1
	v_cndmask_b32_e64 v4, v4, v246, s[34:35]
	v_max_f32_e32 v11, 0xf149f2ca, v4
	v_cndmask_b32_e64 v5, v5, v246, s[30:31]
	v_max_f32_e32 v11, v11, v5
	v_add_u32_e32 v12, 2, v9
	v_add_u32_e32 v13, 3, v9
	v_cmp_gt_u32_e64 s[28:29], v12, v144
	v_cmp_gt_u32_e64 s[26:27], v13, v144
	v_mfma_f32_16x16x32_bf16 v[44:47], v[68:71], v[102:105], v[44:47]
	v_cndmask_b32_e64 v6, v6, v246, s[28:29]
	v_cndmask_b32_e64 v7, v7, v246, s[26:27]
	v_max3_f32 v11, v11, v6, v7
	v_add_u32_e32 v12, 16, v9
	v_add_u32_e32 v13, 17, v9
	v_cmp_gt_u32_e64 s[24:25], v12, v144
	v_cmp_gt_u32_e64 s[22:23], v13, v144
	v_add_f32_e32 v68, v117, v48
	v_cndmask_b32_e64 v0, v0, v246, s[24:25]
	v_cndmask_b32_e64 v13, v1, v246, s[22:23]
	v_max3_f32 v11, v11, v0, v13
	v_add_u32_e32 v12, 18, v9
	v_add_u32_e32 v9, 19, v9
	v_cmp_gt_u32_e64 s[0:1], v12, v144
	v_cmp_gt_u32_e32 vcc, v9, v144
	v_add_f32_e32 v48, 0, v107
	v_cndmask_b32_e64 v2, v2, v246, s[0:1]
	v_cndmask_b32_e64 v3, v3, v246, vcc
	v_max3_f32 v9, v11, v2, v3
	s_nop 1
	v_mov_b32_e32 v11, v9
	v_mov_b32_e32 v12, v9
	s_nop 1
	v_permlane32_swap_b32_e32 v11, v12
	v_max3_f32 v9, v9, v11, v12
	s_nop 1
	v_mov_b32_e32 v11, v9
	v_mov_b32_e32 v67, v9
	s_nop 1
	v_permlane16_swap_b32_e32 v11, v67
	v_max_f32_e32 v9, v9, v11
	v_mov_b32_e32 v66, 1.0
	v_add_f32_e32 v69, v109, v48
	v_mov_b32_e32 v11, 0
	v_add_f32_e32 v12, 0, v11
	v_mov_b32_e32 v8, 0
	v_fmac_f32_e32 v69, v146, v106
	v_add_f32_e32 v65, v8, v12
	v_cvt_pk_bf16_f32 v14, v8, 0
	v_max3_f32 v8, v100, v9, v67
	v_fmac_f32_e32 v65, v69, v66
	v_sub_f32_e32 v4, v4, v8
	v_cvt_pk_bf16_f32 v12, v11, 0
	v_exp_f32_e32 v4, v4
	v_sub_f32_e32 v5, v5, v8
	v_pk_mul_f32 v[10:11], v[34:35], v[66:67] op_sel_hi:[1,0]
	ds_bpermute_b32 v34, v170, v65
	v_exp_f32_e32 v5, v5
	v_sub_f32_e32 v6, v6, v8
	v_exp_f32_e32 v6, v6
	v_sub_f32_e32 v7, v7, v8
	v_exp_f32_e32 v7, v7
	v_sub_f32_e32 v0, v0, v8
	v_sub_f32_e32 v9, v100, v8
	v_exp_f32_e32 v0, v0
	v_sub_f32_e32 v1, v1, v8
	v_mfma_f32_16x16x32_bf16 v[36:39], v[72:75], v[102:105], v[36:39]
	v_exp_f32_e32 v72, v9
	v_add_f32_e32 v9, 0, v4
	v_exp_f32_e32 v1, v1
	v_sub_f32_e32 v2, v2, v8
	s_waitcnt lgkmcnt(0)
	v_add_f32_e32 v34, v65, v34
	v_add_f32_e32 v9, v5, v9
	v_exp_f32_e32 v2, v2
	v_sub_f32_e32 v3, v3, v8
	ds_bpermute_b32 v35, v171, v34
	v_add_f32_e32 v9, v6, v9
	v_exp_f32_e32 v3, v3
	v_add_f32_e32 v9, v7, v9
	v_add_f32_e32 v9, v0, v9
	v_cndmask_b32_e64 v1, v1, 0, s[22:23]
	ds_read_b64_tr_b16 v[62:63], v169 offset:6912
	ds_read_b64_tr_b16 v[60:61], v169 offset:4608
	ds_read_b64_tr_b16 v[56:57], v169 offset:4640
	ds_read_b64_tr_b16 v[58:59], v169 offset:6944
	ds_read_b64_tr_b16 v[52:53], v169 offset:4672
	ds_read_b64_tr_b16 v[54:55], v169 offset:6976
	ds_read_b64_tr_b16 v[48:49], v169 offset:4704
	ds_read_b64_tr_b16 v[50:51], v169 offset:7008
	v_add_f32_e32 v9, v1, v9
	v_add_f32_e32 v9, v2, v9
	s_waitcnt lgkmcnt(8)
	v_add_f32_e32 v34, v34, v35
	v_fmac_f32_e32 v68, v147, v108
	v_mov_b32_e32 v13, v153
	v_add_f32_e32 v64, v3, v9
	v_pk_mul_f32 v[8:9], v[32:33], v[66:67] op_sel_hi:[1,0]
	v_div_scale_f32 v35, s[0:1], v34, v34, 1.0
	v_fmac_f32_e32 v64, v68, v72
	v_cvt_pk_bf16_f32 v68, v4, v5
	v_cvt_pk_bf16_f32 v69, v6, v7
	v_pk_mul_f32 v[6:7], v[26:27], v[66:67] op_sel_hi:[1,0]
	v_pk_mul_f32 v[4:5], v[24:25], v[66:67] op_sel_hi:[1,0]
	s_waitcnt lgkmcnt(2)
	v_mfma_f32_16x16x32_bf16 v[24:27], v[52:55], v[12:15], v[8:11]
	v_cvt_pk_bf16_f32 v70, v0, v1
	v_cvt_pk_bf16_f32 v71, v2, v3
	v_pk_mul_f32 v[2:3], v[18:19], v[66:67] op_sel_hi:[1,0]
	v_pk_mul_f32 v[8:9], v[36:37], v[72:73] op_sel_hi:[1,0]
	v_rcp_f32_e32 v36, v35
	v_mfma_f32_16x16x32_bf16 v[20:23], v[96:99], v[102:105], v[20:23]
	v_mul_f32_e64 v10, v38, v72
	v_mul_f32_e64 v11, v39, v72
	v_pk_mul_f32 v[0:1], v[16:17], v[66:67] op_sel_hi:[1,0]
	v_fma_f32 v37, -v35, v36, 1.0
	v_fmac_f32_e32 v36, v37, v36
	v_div_scale_f32 v37, vcc, 1.0, v34, 1.0
	v_mul_f32_e32 v38, v37, v36
	v_fma_f32 v39, -v35, v38, v37
	v_mfma_f32_16x16x32_bf16 v[16:19], v[60:63], v[12:15], v[0:3]
	v_fmac_f32_e32 v38, v39, v36
	v_fma_f32 v35, -v35, v38, v37
	v_div_fmas_f32 v35, v35, v36, v38
	v_mfma_f32_16x16x32_bf16 v[28:31], v[88:91], v[102:105], v[28:31]
	v_mul_f32_e64 v2, v22, v72
	v_mul_f32_e64 v3, v23, v72
	v_pk_mul_f32 v[0:1], v[20:21], v[72:73] op_sel_hi:[1,0]
	v_div_fixup_f32 v34, v35, v34, 1.0
	v_mfma_f32_16x16x32_bf16 v[20:23], v[56:59], v[12:15], v[4:7]
	v_lshl_add_u64 v[32:33], v[156:157], 0, s[56:57]
	v_lshlrev_b64 v[36:37], 11, v[162:163]
	v_pk_mul_f32 v[16:17], v[16:17], v[34:35] op_sel_hi:[1,0]
	v_pk_mul_f32 v[18:19], v[18:19], v[34:35] op_sel_hi:[1,0]
	v_pk_mul_f32 v[6:7], v[30:31], v[72:73] op_sel_hi:[1,0]
	v_pk_mul_f32 v[4:5], v[28:29], v[72:73] op_sel_hi:[1,0]
	v_pk_mul_f32 v[30:31], v[42:43], v[66:67] op_sel_hi:[1,0]
	v_pk_mul_f32 v[28:29], v[40:41], v[66:67] op_sel_hi:[1,0]
	v_lshl_add_u64 v[36:37], v[32:33], 0, v[36:37]
	v_cvt_pk_bf16_f32 v16, v16, v17
	v_cvt_pk_bf16_f32 v17, v18, v19
	s_waitcnt lgkmcnt(0)
	v_mfma_f32_16x16x32_bf16 v[28:31], v[48:51], v[12:15], v[28:31]
	global_store_dwordx2 v[36:37], v[16:17], off
	v_pk_mul_f32 v[16:17], v[20:21], v[34:35] op_sel_hi:[1,0]
	v_pk_mul_f32 v[18:19], v[22:23], v[34:35] op_sel_hi:[1,0]
	v_cvt_pk_bf16_f32 v16, v16, v17
	v_cvt_pk_bf16_f32 v17, v18, v19
	global_store_dwordx2 v[36:37], v[16:17], off offset:32
	v_pk_mul_f32 v[16:17], v[24:25], v[34:35] op_sel_hi:[1,0]
	v_pk_mul_f32 v[18:19], v[26:27], v[34:35] op_sel_hi:[1,0]
	v_cvt_pk_bf16_f32 v16, v16, v17
	v_cvt_pk_bf16_f32 v17, v18, v19
	global_store_dwordx2 v[36:37], v[16:17], off offset:64
	v_pk_mul_f32 v[16:17], v[28:29], v[34:35] op_sel_hi:[1,0]
	v_pk_mul_f32 v[18:19], v[30:31], v[34:35] op_sel_hi:[1,0]
	v_cvt_pk_bf16_f32 v16, v16, v17
	v_cvt_pk_bf16_f32 v17, v18, v19
	global_store_dwordx2 v[36:37], v[16:17], off offset:96
	ds_bpermute_b32 v16, v170, v64
	v_mfma_f32_16x16x32_bf16 v[0:3], v[60:63], v[68:71], v[0:3]
	v_mul_f32_e64 v14, v46, v72
	v_mul_f32_e64 v15, v47, v72
	v_pk_mul_f32 v[12:13], v[44:45], v[72:73] op_sel_hi:[1,0]
	s_waitcnt lgkmcnt(0)
	v_add_f32_e32 v16, v64, v16
	ds_bpermute_b32 v17, v171, v16
	v_mfma_f32_16x16x32_bf16 v[4:7], v[56:59], v[68:71], v[4:7]
	s_waitcnt lgkmcnt(0)
	v_add_f32_e32 v16, v16, v17
	v_div_scale_f32 v17, s[0:1], v16, v16, 1.0
	v_rcp_f32_e32 v18, v17
	v_mfma_f32_16x16x32_bf16 v[8:11], v[52:55], v[68:71], v[8:11]
	v_fma_f32 v19, -v17, v18, 1.0
	v_fmac_f32_e32 v18, v19, v18
	v_div_scale_f32 v19, vcc, 1.0, v16, 1.0
	v_mul_f32_e32 v20, v19, v18
	v_fma_f32 v21, -v17, v20, v19
	v_fmac_f32_e32 v20, v21, v18
	v_fma_f32 v17, -v17, v20, v19
	v_div_fmas_f32 v17, v17, v18, v20
	v_div_fixup_f32 v16, v17, v16, 1.0
	v_lshlrev_b64 v[18:19], 11, v[160:161]
	v_pk_mul_f32 v[0:1], v[0:1], v[16:17] op_sel_hi:[1,0]
	v_pk_mul_f32 v[2:3], v[2:3], v[16:17] op_sel_hi:[1,0]
	v_lshl_add_u64 v[18:19], v[32:33], 0, v[18:19]
	v_cvt_pk_bf16_f32 v0, v0, v1
	v_cvt_pk_bf16_f32 v1, v2, v3
	v_mfma_f32_16x16x32_bf16 v[12:15], v[48:51], v[68:71], v[12:15]
	global_store_dwordx2 v[18:19], v[0:1], off
	v_pk_mul_f32 v[0:1], v[4:5], v[16:17] op_sel_hi:[1,0]
	v_pk_mul_f32 v[2:3], v[6:7], v[16:17] op_sel_hi:[1,0]
	v_cvt_pk_bf16_f32 v0, v0, v1
	v_cvt_pk_bf16_f32 v1, v2, v3
	global_store_dwordx2 v[18:19], v[0:1], off offset:32
	v_pk_mul_f32 v[0:1], v[8:9], v[16:17] op_sel_hi:[1,0]
	v_pk_mul_f32 v[2:3], v[10:11], v[16:17] op_sel_hi:[1,0]
	v_cvt_pk_bf16_f32 v0, v0, v1
	v_cvt_pk_bf16_f32 v1, v2, v3
	global_store_dwordx2 v[18:19], v[0:1], off offset:64
	v_pk_mul_f32 v[0:1], v[12:13], v[16:17] op_sel_hi:[1,0]
	v_pk_mul_f32 v[2:3], v[14:15], v[16:17] op_sel_hi:[1,0]
	v_cvt_pk_bf16_f32 v0, v0, v1
	v_cvt_pk_bf16_f32 v1, v2, v3
	global_store_dwordx2 v[18:19], v[0:1], off offset:96
	s_cbranch_scc1 .LBB0_246
	s_mov_b32 s76, s79
	v_readlane_b32 s72, v253, 43
	v_xor_b32_e32 v240, 32, v174
	v_xor_b32_e32 v241, 16, v174
	v_xor_b32_e32 v242, 8, v174
	v_xor_b32_e32 v243, 4, v174
	v_xor_b32_e32 v244, 2, v174
	v_xor_b32_e32 v245, 1, v174
	v_and_b32_e32 v246, 64, v174
